# K-loop staging DMAs in saddr form (90 per-DMA 64-bit VALU address adds removed), K-loop placement kept
# speedup vs baseline: 1.0021x; 1.0021x over previous
.LBB0_150:
	ds_read_b128 v[48:51], v214
	ds_read_b128 v[52:55], v214 offset:1024
	ds_read_b128 v[56:59], v214 offset:2048
	ds_read_b128 v[60:63], v214 offset:3072
	ds_read_b128 v[168:171], v215
	ds_read_b128 v[172:175], v215 offset:1024
	ds_read_b128 v[176:179], v215 offset:2048
	ds_read_b128 v[180:183], v215 offset:3072
	s_add_u32 s4, s2, 0xfffc0080
	s_addc_u32 s5, s3, -1
	s_cmp_eq_u32 s89, 12
	s_cselect_b32 s7, s8, s5
	s_cselect_b32 s6, s9, s4
	s_cselect_b32 s5, s79, s88
	s_cselect_b32 s4, s81, s87

	s_add_i32 m0, s68, 0xc000
	ds_read_b128 v[184:187], v216
	ds_read_b128 v[188:191], v216 offset:1024
	ds_read_b128 v[192:195], v216 offset:2048
	ds_read_b128 v[196:199], v216 offset:3072
	ds_read_b128 v[200:203], v216 offset:4096
	ds_read_b128 v[204:207], v216 offset:5120
	ds_read_b128 v[208:211], v216 offset:6144
	ds_read_b128 v[220:223], v216 offset:7168
	global_load_lds_dwordx4 v158, s[2:3]

	s_add_i32 m0, s68, 0xe000
	s_nop 0
	global_load_lds_dwordx4 v160, s[2:3]
	s_waitcnt vmcnt(8)
	s_waitcnt lgkmcnt(0)
	s_barrier

	v_mfma_f32_16x16x32_bf16 v[140:143], v[48:51], v[184:187], v[140:143]
	v_mfma_f32_16x16x32_bf16 v[136:139], v[56:59], v[184:187], v[136:139]
	v_mfma_f32_16x16x32_bf16 v[124:127], v[48:51], v[192:195], v[124:127]
	v_mfma_f32_16x16x32_bf16 v[120:123], v[56:59], v[192:195], v[120:123]
	v_mfma_f32_16x16x32_bf16 v[108:111], v[48:51], v[200:203], v[108:111]
	v_mfma_f32_16x16x32_bf16 v[104:107], v[56:59], v[200:203], v[104:107]
	v_mfma_f32_16x16x32_bf16 v[92:95], v[48:51], v[208:211], v[92:95]
	v_mfma_f32_16x16x32_bf16 v[88:91], v[56:59], v[208:211], v[88:91]
	v_mfma_f32_16x16x32_bf16 v[140:143], v[52:55], v[188:191], v[140:143]
	v_mfma_f32_16x16x32_bf16 v[136:139], v[60:63], v[188:191], v[136:139]
	v_mfma_f32_16x16x32_bf16 v[124:127], v[52:55], v[196:199], v[124:127]
	v_mfma_f32_16x16x32_bf16 v[120:123], v[60:63], v[196:199], v[120:123]
	v_mfma_f32_16x16x32_bf16 v[108:111], v[52:55], v[204:207], v[108:111]
	v_mfma_f32_16x16x32_bf16 v[104:107], v[60:63], v[204:207], v[104:107]
	v_mfma_f32_16x16x32_bf16 v[92:95], v[52:55], v[220:223], v[92:95]
	v_mfma_f32_16x16x32_bf16 v[88:91], v[60:63], v[220:223], v[88:91]

	v_mfma_f32_16x16x32_bf16 v[132:135], v[168:171], v[184:187], v[132:135]
	v_mfma_f32_16x16x32_bf16 v[128:131], v[176:179], v[184:187], v[128:131]
	v_mfma_f32_16x16x32_bf16 v[116:119], v[168:171], v[192:195], v[116:119]
	v_mfma_f32_16x16x32_bf16 v[112:115], v[176:179], v[192:195], v[112:115]
	v_mfma_f32_16x16x32_bf16 v[100:103], v[168:171], v[200:203], v[100:103]
	v_mfma_f32_16x16x32_bf16 v[96:99], v[176:179], v[200:203], v[96:99]
	v_mfma_f32_16x16x32_bf16 v[84:87], v[168:171], v[208:211], v[84:87]
	v_mfma_f32_16x16x32_bf16 v[80:83], v[176:179], v[208:211], v[80:83]
	v_mfma_f32_16x16x32_bf16 v[132:135], v[172:175], v[188:191], v[132:135]
	v_mfma_f32_16x16x32_bf16 v[128:131], v[180:183], v[188:191], v[128:131]
	v_mfma_f32_16x16x32_bf16 v[116:119], v[172:175], v[196:199], v[116:119]
	v_mfma_f32_16x16x32_bf16 v[112:115], v[180:183], v[196:199], v[112:115]
	v_mfma_f32_16x16x32_bf16 v[100:103], v[172:175], v[204:207], v[100:103]
	v_mfma_f32_16x16x32_bf16 v[96:99], v[180:183], v[204:207], v[96:99]
	v_mfma_f32_16x16x32_bf16 v[84:87], v[172:175], v[220:223], v[84:87]
	v_mfma_f32_16x16x32_bf16 v[80:83], v[180:183], v[220:223], v[80:83]

	s_barrier
	s_add_i32 s90, s72, s61
	v_lshl_add_u64 v[212:213], s[4:5], 0, v[146:147]
	s_mov_b32 m0, s90
	ds_read_b128 v[184:187], v216 offset:16384
	ds_read_b128 v[188:191], v216 offset:17408
	ds_read_b128 v[192:195], v216 offset:18432
	ds_read_b128 v[196:199], v216 offset:19456
	ds_read_b128 v[200:203], v216 offset:20480
	ds_read_b128 v[204:207], v216 offset:21504
	ds_read_b128 v[208:211], v216 offset:22528
	ds_read_b128 v[220:223], v216 offset:23552
	global_load_lds_dwordx4 v[212:213], off
	s_add_i32 m0, s90, 0x2000
	s_add_u32 s90, s4, 0x40000
	v_lshl_add_u64 v[224:225], s[4:5], 0, v[150:151]
	s_addc_u32 s91, s5, 0
	s_add_i32 s93, s73, s61
	global_load_lds_dwordx4 v[224:225], off

	s_mov_b32 m0, s93
	v_lshl_add_u64 v[228:229], s[6:7], 0, v[148:149]
	global_load_lds_dwordx4 v146, s[90:91]

	s_add_i32 m0, s93, 0x2000
	s_nop 0
	global_load_lds_dwordx4 v150, s[90:91]
	v_lshl_add_u64 v[226:227], s[6:7], 0, v[144:145]
	s_mov_b32 m0, s68
	s_nop 0
	global_load_lds_dwordx4 v[226:227], off
	s_mov_b32 m0, s69
	s_nop 0
	global_load_lds_dwordx4 v[228:229], off
	s_waitcnt vmcnt(8)
	s_waitcnt lgkmcnt(0)
	s_barrier

	v_mfma_f32_16x16x32_bf16 v[76:79], v[48:51], v[184:187], v[76:79]
	v_mfma_f32_16x16x32_bf16 v[72:75], v[56:59], v[184:187], v[72:75]
	v_mfma_f32_16x16x32_bf16 v[44:47], v[48:51], v[192:195], v[44:47]
	v_mfma_f32_16x16x32_bf16 v[40:43], v[56:59], v[192:195], v[40:43]
	v_mfma_f32_16x16x32_bf16 v[28:31], v[48:51], v[200:203], v[28:31]
	v_mfma_f32_16x16x32_bf16 v[24:27], v[56:59], v[200:203], v[24:27]
	v_mfma_f32_16x16x32_bf16 v[12:15], v[48:51], v[208:211], v[12:15]
	v_mfma_f32_16x16x32_bf16 v[8:11], v[56:59], v[208:211], v[8:11]
	v_mfma_f32_16x16x32_bf16 v[76:79], v[52:55], v[188:191], v[76:79]
	v_mfma_f32_16x16x32_bf16 v[72:75], v[60:63], v[188:191], v[72:75]
	v_mfma_f32_16x16x32_bf16 v[44:47], v[52:55], v[196:199], v[44:47]
	v_mfma_f32_16x16x32_bf16 v[40:43], v[60:63], v[196:199], v[40:43]
	v_mfma_f32_16x16x32_bf16 v[28:31], v[52:55], v[204:207], v[28:31]
	v_mfma_f32_16x16x32_bf16 v[24:27], v[60:63], v[204:207], v[24:27]
	v_mfma_f32_16x16x32_bf16 v[12:15], v[52:55], v[220:223], v[12:15]
	v_mfma_f32_16x16x32_bf16 v[8:11], v[60:63], v[220:223], v[8:11]

	v_mfma_f32_16x16x32_bf16 v[36:39], v[168:171], v[192:195], v[36:39]
	v_mfma_f32_16x16x32_bf16 v[32:35], v[176:179], v[192:195], v[32:35]
	v_mfma_f32_16x16x32_bf16 v[20:23], v[168:171], v[200:203], v[20:23]
	v_mfma_f32_16x16x32_bf16 v[16:19], v[176:179], v[200:203], v[16:19]
	v_mfma_f32_16x16x32_bf16 v[4:7], v[168:171], v[208:211], v[4:7]
	v_mfma_f32_16x16x32_bf16 v[0:3], v[176:179], v[208:211], v[0:3]
	v_mfma_f32_16x16x32_bf16 v[48:51], v[168:171], v[184:187], v[68:71]
	v_mfma_f32_16x16x32_bf16 v[52:55], v[176:179], v[184:187], v[64:67]
	v_mfma_f32_16x16x32_bf16 v[36:39], v[172:175], v[196:199], v[36:39]
	v_mfma_f32_16x16x32_bf16 v[32:35], v[180:183], v[196:199], v[32:35]
	v_mfma_f32_16x16x32_bf16 v[20:23], v[172:175], v[204:207], v[20:23]
	v_mfma_f32_16x16x32_bf16 v[16:19], v[180:183], v[204:207], v[16:19]
	v_mfma_f32_16x16x32_bf16 v[4:7], v[172:175], v[220:223], v[4:7]
	v_mfma_f32_16x16x32_bf16 v[0:3], v[180:183], v[220:223], v[0:3]
	v_mfma_f32_16x16x32_bf16 v[48:51], v[172:175], v[188:191], v[48:51]
	v_mfma_f32_16x16x32_bf16 v[52:55], v[180:183], v[188:191], v[52:55]

	s_barrier
	s_add_i32 s90, 0, 0x18000
	s_add_i32 s91, 0, 0x1c000
	v_add_u32_e32 v68, s90, v167
	v_add_u32_e32 v154, s91, v167
	ds_read_b128 v[56:59], v68
	ds_read_b128 v[60:63], v68 offset:1024
	ds_read_b128 v[64:67], v68 offset:2048
	ds_read_b128 v[68:71], v68 offset:3072
	ds_read_b128 v[168:171], v154
	ds_read_b128 v[172:175], v154 offset:1024
	ds_read_b128 v[176:179], v154 offset:2048
	ds_read_b128 v[180:183], v154 offset:3072
	s_add_u32 s6, s6, 0x40000
	s_addc_u32 s7, s7, 0
	s_mov_b32 m0, s70

	ds_read_b128 v[184:187], v216 offset:32768
	ds_read_b128 v[188:191], v216 offset:33792
	ds_read_b128 v[192:195], v216 offset:34816
	ds_read_b128 v[196:199], v216 offset:35840
	ds_read_b128 v[200:203], v216 offset:36864
	ds_read_b128 v[204:207], v216 offset:37888
	ds_read_b128 v[208:211], v216 offset:38912
	ds_read_b128 v[220:223], v216 offset:39936
	global_load_lds_dwordx4 v144, s[6:7]

	s_mov_b32 m0, s77
	s_nop 0
	global_load_lds_dwordx4 v148, s[6:7]
	s_waitcnt vmcnt(8)
	s_waitcnt lgkmcnt(0)
	s_barrier

	v_mfma_f32_16x16x32_bf16 v[140:143], v[56:59], v[184:187], v[140:143]
	v_mfma_f32_16x16x32_bf16 v[136:139], v[64:67], v[184:187], v[136:139]
	v_mfma_f32_16x16x32_bf16 v[124:127], v[56:59], v[192:195], v[124:127]
	v_mfma_f32_16x16x32_bf16 v[120:123], v[64:67], v[192:195], v[120:123]
	v_mfma_f32_16x16x32_bf16 v[108:111], v[56:59], v[200:203], v[108:111]
	v_mfma_f32_16x16x32_bf16 v[104:107], v[64:67], v[200:203], v[104:107]
	v_mfma_f32_16x16x32_bf16 v[92:95], v[56:59], v[208:211], v[92:95]
	v_mfma_f32_16x16x32_bf16 v[88:91], v[64:67], v[208:211], v[88:91]
	v_mfma_f32_16x16x32_bf16 v[140:143], v[60:63], v[188:191], v[140:143]
	v_mfma_f32_16x16x32_bf16 v[136:139], v[68:71], v[188:191], v[136:139]
	v_mfma_f32_16x16x32_bf16 v[124:127], v[60:63], v[196:199], v[124:127]
	v_mfma_f32_16x16x32_bf16 v[120:123], v[68:71], v[196:199], v[120:123]
	v_mfma_f32_16x16x32_bf16 v[108:111], v[60:63], v[204:207], v[108:111]
	v_mfma_f32_16x16x32_bf16 v[104:107], v[68:71], v[204:207], v[104:107]
	v_mfma_f32_16x16x32_bf16 v[92:95], v[60:63], v[220:223], v[92:95]
	v_mfma_f32_16x16x32_bf16 v[88:91], v[68:71], v[220:223], v[88:91]

	v_mfma_f32_16x16x32_bf16 v[132:135], v[168:171], v[184:187], v[132:135]
	v_mfma_f32_16x16x32_bf16 v[128:131], v[176:179], v[184:187], v[128:131]
	v_mfma_f32_16x16x32_bf16 v[116:119], v[168:171], v[192:195], v[116:119]
	v_mfma_f32_16x16x32_bf16 v[112:115], v[176:179], v[192:195], v[112:115]
	v_mfma_f32_16x16x32_bf16 v[100:103], v[168:171], v[200:203], v[100:103]
	v_mfma_f32_16x16x32_bf16 v[96:99], v[176:179], v[200:203], v[96:99]
	v_mfma_f32_16x16x32_bf16 v[84:87], v[168:171], v[208:211], v[84:87]
	v_mfma_f32_16x16x32_bf16 v[80:83], v[176:179], v[208:211], v[80:83]
	v_mfma_f32_16x16x32_bf16 v[132:135], v[172:175], v[188:191], v[132:135]
	v_mfma_f32_16x16x32_bf16 v[128:131], v[180:183], v[188:191], v[128:131]
	v_mfma_f32_16x16x32_bf16 v[116:119], v[172:175], v[196:199], v[116:119]
	v_mfma_f32_16x16x32_bf16 v[112:115], v[180:183], v[196:199], v[112:115]
	v_mfma_f32_16x16x32_bf16 v[100:103], v[172:175], v[204:207], v[100:103]
	v_mfma_f32_16x16x32_bf16 v[96:99], v[180:183], v[204:207], v[96:99]
	v_mfma_f32_16x16x32_bf16 v[84:87], v[172:175], v[220:223], v[84:87]
	v_mfma_f32_16x16x32_bf16 v[80:83], v[180:183], v[220:223], v[80:83]

	s_barrier
	s_add_i32 s6, s90, s61
	v_lshl_add_u64 v[212:213], v[212:213], 0, s[56:57]
	s_mov_b32 m0, s6
	ds_read_b128 v[184:187], v216 offset:49152
	ds_read_b128 v[188:191], v216 offset:50176
	ds_read_b128 v[192:195], v216 offset:51200
	ds_read_b128 v[196:199], v216 offset:52224
	ds_read_b128 v[200:203], v216 offset:53248
	ds_read_b128 v[204:207], v216 offset:54272
	ds_read_b128 v[208:211], v216 offset:55296
	ds_read_b128 v[220:223], v216 offset:56320
	global_load_lds_dwordx4 v[212:213], off
	s_add_i32 m0, s6, 0x2000
	s_add_u32 s4, s4, 0x40080
	v_lshl_add_u64 v[212:213], v[224:225], 0, s[56:57]
	s_addc_u32 s5, s5, 0
	s_add_i32 s6, s91, s61
	global_load_lds_dwordx4 v[212:213], off

	s_mov_b32 m0, s6
	s_nop 0
	global_load_lds_dwordx4 v146, s[4:5]

	s_add_i32 m0, s6, 0x2000
	s_nop 0
	global_load_lds_dwordx4 v150, s[4:5]
	v_lshl_add_u64 v[212:213], v[226:227], 0, s[56:57]
	s_mov_b32 m0, s96
	s_nop 0
	global_load_lds_dwordx4 v[212:213], off
	v_lshl_add_u64 v[212:213], v[228:229], 0, s[56:57]
	s_mov_b32 m0, s71
	s_nop 0
	global_load_lds_dwordx4 v[212:213], off
	s_waitcnt vmcnt(8)
	s_waitcnt lgkmcnt(0)
	s_barrier

	v_mfma_f32_16x16x32_bf16 v[76:79], v[56:59], v[184:187], v[76:79]
	v_mfma_f32_16x16x32_bf16 v[72:75], v[64:67], v[184:187], v[72:75]
	v_mfma_f32_16x16x32_bf16 v[44:47], v[56:59], v[192:195], v[44:47]
	v_mfma_f32_16x16x32_bf16 v[40:43], v[64:67], v[192:195], v[40:43]
	v_mfma_f32_16x16x32_bf16 v[28:31], v[56:59], v[200:203], v[28:31]
	v_mfma_f32_16x16x32_bf16 v[24:27], v[64:67], v[200:203], v[24:27]
	v_mfma_f32_16x16x32_bf16 v[12:15], v[56:59], v[208:211], v[12:15]
	v_mfma_f32_16x16x32_bf16 v[8:11], v[64:67], v[208:211], v[8:11]
	v_mfma_f32_16x16x32_bf16 v[76:79], v[60:63], v[188:191], v[76:79]
	v_mfma_f32_16x16x32_bf16 v[72:75], v[68:71], v[188:191], v[72:75]
	v_mfma_f32_16x16x32_bf16 v[44:47], v[60:63], v[196:199], v[44:47]
	v_mfma_f32_16x16x32_bf16 v[40:43], v[68:71], v[196:199], v[40:43]
	v_mfma_f32_16x16x32_bf16 v[28:31], v[60:63], v[204:207], v[28:31]
	v_mfma_f32_16x16x32_bf16 v[24:27], v[68:71], v[204:207], v[24:27]
	v_mfma_f32_16x16x32_bf16 v[12:15], v[60:63], v[220:223], v[12:15]
	v_mfma_f32_16x16x32_bf16 v[8:11], v[68:71], v[220:223], v[8:11]

	v_mfma_f32_16x16x32_bf16 v[48:51], v[168:171], v[184:187], v[48:51]
	v_mfma_f32_16x16x32_bf16 v[68:71], v[172:175], v[188:191], v[48:51]
	v_mfma_f32_16x16x32_bf16 v[48:51], v[176:179], v[184:187], v[52:55]
	v_mfma_f32_16x16x32_bf16 v[36:39], v[168:171], v[192:195], v[36:39]
	v_mfma_f32_16x16x32_bf16 v[32:35], v[176:179], v[192:195], v[32:35]
	v_mfma_f32_16x16x32_bf16 v[20:23], v[168:171], v[200:203], v[20:23]
	v_mfma_f32_16x16x32_bf16 v[16:19], v[176:179], v[200:203], v[16:19]
	v_mfma_f32_16x16x32_bf16 v[4:7], v[168:171], v[208:211], v[4:7]
	v_mfma_f32_16x16x32_bf16 v[0:3], v[176:179], v[208:211], v[0:3]
	v_mfma_f32_16x16x32_bf16 v[64:67], v[180:183], v[188:191], v[48:51]
	v_mfma_f32_16x16x32_bf16 v[36:39], v[172:175], v[196:199], v[36:39]
	v_mfma_f32_16x16x32_bf16 v[32:35], v[180:183], v[196:199], v[32:35]
	v_mfma_f32_16x16x32_bf16 v[20:23], v[172:175], v[204:207], v[20:23]
	v_mfma_f32_16x16x32_bf16 v[16:19], v[180:183], v[204:207], v[16:19]
	v_mfma_f32_16x16x32_bf16 v[4:7], v[172:175], v[220:223], v[4:7]
	v_mfma_f32_16x16x32_bf16 v[0:3], v[180:183], v[220:223], v[0:3]

	s_barrier
	s_add_i32 s89, s89, 2
	s_add_u32 s2, s2, 0x100
	s_addc_u32 s3, s3, 0
	s_add_u32 s87, s87, 0x100
	s_addc_u32 s88, s88, 0
	s_cmp_gt_u32 s89, 13
	s_cbranch_scc0 .LBB0_150
	s_and_b64 vcc, exec, s[58:59]
	s_cbranch_vccz .LBB0_153
	s_barrier

.LBB0_741:
	ds_read_b128 v[128:131], v187
	ds_read_b128 v[132:135], v187 offset:1024
	ds_read_b128 v[136:139], v187 offset:2048
	ds_read_b128 v[140:143], v187 offset:3072
	ds_read_b128 v[144:147], v188
	ds_read_b128 v[148:151], v188 offset:1024
	ds_read_b128 v[168:171], v188 offset:2048
	ds_read_b128 v[172:175], v188 offset:3072
	s_add_u32 s58, s52, 0xfffc0080
	s_addc_u32 s59, s53, -1
	s_cmp_eq_u32 s83, 12
	s_cselect_b32 s61, s6, s59
	s_cselect_b32 s60, s11, s58
	s_cselect_b32 s59, s13, s82
	s_cselect_b32 s58, s80, s81

	s_add_i32 m0, s62, 0xc000
	ds_read_b128 v[176:179], v189
	ds_read_b128 v[180:183], v189 offset:1024
	ds_read_b128 v[192:195], v189 offset:2048
	ds_read_b128 v[196:199], v189 offset:3072
	ds_read_b128 v[200:203], v189 offset:4096
	ds_read_b128 v[204:207], v189 offset:5120
	ds_read_b128 v[208:211], v189 offset:6144
	ds_read_b128 v[212:215], v189 offset:7168
	global_load_lds_dwordx4 v160, s[52:53]

	s_add_i32 m0, s62, 0xe000
	s_nop 0
	global_load_lds_dwordx4 v162, s[52:53]
	s_waitcnt vmcnt(8)
	s_waitcnt lgkmcnt(0)
	s_barrier

	v_mfma_f32_16x16x32_bf16 v[124:127], v[128:131], v[176:179], v[124:127]
	v_mfma_f32_16x16x32_bf16 v[120:123], v[136:139], v[176:179], v[120:123]
	v_mfma_f32_16x16x32_bf16 v[108:111], v[128:131], v[192:195], v[108:111]
	v_mfma_f32_16x16x32_bf16 v[104:107], v[136:139], v[192:195], v[104:107]
	v_mfma_f32_16x16x32_bf16 v[92:95], v[128:131], v[200:203], v[92:95]
	v_mfma_f32_16x16x32_bf16 v[88:91], v[136:139], v[200:203], v[88:91]
	v_mfma_f32_16x16x32_bf16 v[76:79], v[128:131], v[208:211], v[76:79]
	v_mfma_f32_16x16x32_bf16 v[72:75], v[136:139], v[208:211], v[72:75]
	v_mfma_f32_16x16x32_bf16 v[124:127], v[132:135], v[180:183], v[124:127]
	v_mfma_f32_16x16x32_bf16 v[120:123], v[140:143], v[180:183], v[120:123]
	v_mfma_f32_16x16x32_bf16 v[108:111], v[132:135], v[196:199], v[108:111]
	v_mfma_f32_16x16x32_bf16 v[104:107], v[140:143], v[196:199], v[104:107]
	v_mfma_f32_16x16x32_bf16 v[92:95], v[132:135], v[204:207], v[92:95]
	v_mfma_f32_16x16x32_bf16 v[88:91], v[140:143], v[204:207], v[88:91]
	v_mfma_f32_16x16x32_bf16 v[76:79], v[132:135], v[212:215], v[76:79]
	v_mfma_f32_16x16x32_bf16 v[72:75], v[140:143], v[212:215], v[72:75]

	v_mfma_f32_16x16x32_bf16 v[116:119], v[144:147], v[176:179], v[116:119]
	v_mfma_f32_16x16x32_bf16 v[112:115], v[168:171], v[176:179], v[112:115]
	v_mfma_f32_16x16x32_bf16 v[100:103], v[144:147], v[192:195], v[100:103]
	v_mfma_f32_16x16x32_bf16 v[96:99], v[168:171], v[192:195], v[96:99]
	v_mfma_f32_16x16x32_bf16 v[84:87], v[144:147], v[200:203], v[84:87]
	v_mfma_f32_16x16x32_bf16 v[80:83], v[168:171], v[200:203], v[80:83]
	v_mfma_f32_16x16x32_bf16 v[68:71], v[144:147], v[208:211], v[68:71]
	v_mfma_f32_16x16x32_bf16 v[64:67], v[168:171], v[208:211], v[64:67]
	v_mfma_f32_16x16x32_bf16 v[116:119], v[148:151], v[180:183], v[116:119]
	v_mfma_f32_16x16x32_bf16 v[112:115], v[172:175], v[180:183], v[112:115]
	v_mfma_f32_16x16x32_bf16 v[100:103], v[148:151], v[196:199], v[100:103]
	v_mfma_f32_16x16x32_bf16 v[96:99], v[172:175], v[196:199], v[96:99]
	v_mfma_f32_16x16x32_bf16 v[84:87], v[148:151], v[204:207], v[84:87]
	v_mfma_f32_16x16x32_bf16 v[80:83], v[172:175], v[204:207], v[80:83]
	v_mfma_f32_16x16x32_bf16 v[68:71], v[148:151], v[212:215], v[68:71]
	v_mfma_f32_16x16x32_bf16 v[64:67], v[172:175], v[212:215], v[64:67]

	s_barrier
	s_add_i32 s84, s71, s57
	v_lshl_add_u64 v[216:217], s[58:59], 0, v[154:155]
	s_mov_b32 m0, s84
	ds_read_b128 v[176:179], v189 offset:16384
	ds_read_b128 v[180:183], v189 offset:17408
	ds_read_b128 v[192:195], v189 offset:18432
	ds_read_b128 v[196:199], v189 offset:19456
	ds_read_b128 v[200:203], v189 offset:20480
	ds_read_b128 v[204:207], v189 offset:21504
	ds_read_b128 v[208:211], v189 offset:22528
	ds_read_b128 v[212:215], v189 offset:23552
	global_load_lds_dwordx4 v[216:217], off
	s_add_i32 m0, s84, 0x2000
	s_add_u32 s84, s58, 0x40000
	v_lshl_add_u64 v[218:219], s[58:59], 0, v[158:159]
	s_addc_u32 s85, s59, 0
	s_add_i32 s86, s72, s57
	global_load_lds_dwordx4 v[218:219], off

	s_mov_b32 m0, s86
	v_lshl_add_u64 v[222:223], s[60:61], 0, v[156:157]
	global_load_lds_dwordx4 v154, s[84:85]

	s_add_i32 m0, s86, 0x2000
	s_nop 0
	global_load_lds_dwordx4 v158, s[84:85]
	v_lshl_add_u64 v[220:221], s[60:61], 0, v[152:153]
	s_mov_b32 m0, s62
	s_nop 0
	global_load_lds_dwordx4 v[220:221], off
	s_mov_b32 m0, s63
	s_nop 0
	global_load_lds_dwordx4 v[222:223], off
	s_waitcnt vmcnt(8)
	s_waitcnt lgkmcnt(0)
	s_barrier

	v_mfma_f32_16x16x32_bf16 v[60:63], v[128:131], v[176:179], v[60:63]
	v_mfma_f32_16x16x32_bf16 v[56:59], v[136:139], v[176:179], v[56:59]
	v_mfma_f32_16x16x32_bf16 v[44:47], v[128:131], v[192:195], v[44:47]
	v_mfma_f32_16x16x32_bf16 v[40:43], v[136:139], v[192:195], v[40:43]
	v_mfma_f32_16x16x32_bf16 v[28:31], v[128:131], v[200:203], v[28:31]
	v_mfma_f32_16x16x32_bf16 v[24:27], v[136:139], v[200:203], v[24:27]
	v_mfma_f32_16x16x32_bf16 v[12:15], v[128:131], v[208:211], v[12:15]
	v_mfma_f32_16x16x32_bf16 v[8:11], v[136:139], v[208:211], v[8:11]
	v_mfma_f32_16x16x32_bf16 v[60:63], v[132:135], v[180:183], v[60:63]
	v_mfma_f32_16x16x32_bf16 v[56:59], v[140:143], v[180:183], v[56:59]
	v_mfma_f32_16x16x32_bf16 v[44:47], v[132:135], v[196:199], v[44:47]
	v_mfma_f32_16x16x32_bf16 v[40:43], v[140:143], v[196:199], v[40:43]
	v_mfma_f32_16x16x32_bf16 v[28:31], v[132:135], v[204:207], v[28:31]
	v_mfma_f32_16x16x32_bf16 v[24:27], v[140:143], v[204:207], v[24:27]
	v_mfma_f32_16x16x32_bf16 v[12:15], v[132:135], v[212:215], v[12:15]
	v_mfma_f32_16x16x32_bf16 v[8:11], v[140:143], v[212:215], v[8:11]

	v_mfma_f32_16x16x32_bf16 v[52:55], v[144:147], v[176:179], v[52:55]
	v_mfma_f32_16x16x32_bf16 v[48:51], v[168:171], v[176:179], v[48:51]
	v_mfma_f32_16x16x32_bf16 v[36:39], v[144:147], v[192:195], v[36:39]
	v_mfma_f32_16x16x32_bf16 v[32:35], v[168:171], v[192:195], v[32:35]
	v_mfma_f32_16x16x32_bf16 v[20:23], v[144:147], v[200:203], v[20:23]
	v_mfma_f32_16x16x32_bf16 v[16:19], v[168:171], v[200:203], v[16:19]
	v_mfma_f32_16x16x32_bf16 v[4:7], v[144:147], v[208:211], v[4:7]
	v_mfma_f32_16x16x32_bf16 v[0:3], v[168:171], v[208:211], v[0:3]
	v_mfma_f32_16x16x32_bf16 v[52:55], v[148:151], v[180:183], v[52:55]
	v_mfma_f32_16x16x32_bf16 v[48:51], v[172:175], v[180:183], v[48:51]
	v_mfma_f32_16x16x32_bf16 v[36:39], v[148:151], v[196:199], v[36:39]
	v_mfma_f32_16x16x32_bf16 v[32:35], v[172:175], v[196:199], v[32:35]
	v_mfma_f32_16x16x32_bf16 v[20:23], v[148:151], v[204:207], v[20:23]
	v_mfma_f32_16x16x32_bf16 v[16:19], v[172:175], v[204:207], v[16:19]
	v_mfma_f32_16x16x32_bf16 v[4:7], v[148:151], v[212:215], v[4:7]
	v_mfma_f32_16x16x32_bf16 v[0:3], v[172:175], v[212:215], v[0:3]

	s_barrier
	s_add_i32 s84, 0, 0x18000
	s_add_i32 s85, 0, 0x1c000
	v_add_u32_e32 v140, s84, v185
	v_add_u32_e32 v172, s85, v185
	ds_read_b128 v[128:131], v140
	ds_read_b128 v[132:135], v140 offset:1024
	ds_read_b128 v[136:139], v140 offset:2048
	ds_read_b128 v[140:143], v140 offset:3072
	ds_read_b128 v[144:147], v172
	ds_read_b128 v[148:151], v172 offset:1024
	ds_read_b128 v[168:171], v172 offset:2048
	ds_read_b128 v[172:175], v172 offset:3072
	s_add_u32 s60, s60, 0x40000
	s_addc_u32 s61, s61, 0
	s_mov_b32 m0, s64

	ds_read_b128 v[176:179], v189 offset:32768
	ds_read_b128 v[180:183], v189 offset:33792
	ds_read_b128 v[192:195], v189 offset:34816
	ds_read_b128 v[196:199], v189 offset:35840
	ds_read_b128 v[200:203], v189 offset:36864
	ds_read_b128 v[204:207], v189 offset:37888
	ds_read_b128 v[208:211], v189 offset:38912
	ds_read_b128 v[212:215], v189 offset:39936
	global_load_lds_dwordx4 v152, s[60:61]

	s_mov_b32 m0, s65
	s_nop 0
	global_load_lds_dwordx4 v156, s[60:61]
	s_waitcnt vmcnt(8)
	s_waitcnt lgkmcnt(0)
	s_barrier

	v_mfma_f32_16x16x32_bf16 v[124:127], v[128:131], v[176:179], v[124:127]
	v_mfma_f32_16x16x32_bf16 v[120:123], v[136:139], v[176:179], v[120:123]
	v_mfma_f32_16x16x32_bf16 v[108:111], v[128:131], v[192:195], v[108:111]
	v_mfma_f32_16x16x32_bf16 v[104:107], v[136:139], v[192:195], v[104:107]
	v_mfma_f32_16x16x32_bf16 v[92:95], v[128:131], v[200:203], v[92:95]
	v_mfma_f32_16x16x32_bf16 v[88:91], v[136:139], v[200:203], v[88:91]
	v_mfma_f32_16x16x32_bf16 v[76:79], v[128:131], v[208:211], v[76:79]
	v_mfma_f32_16x16x32_bf16 v[72:75], v[136:139], v[208:211], v[72:75]
	v_mfma_f32_16x16x32_bf16 v[124:127], v[132:135], v[180:183], v[124:127]
	v_mfma_f32_16x16x32_bf16 v[120:123], v[140:143], v[180:183], v[120:123]
	v_mfma_f32_16x16x32_bf16 v[108:111], v[132:135], v[196:199], v[108:111]
	v_mfma_f32_16x16x32_bf16 v[104:107], v[140:143], v[196:199], v[104:107]
	v_mfma_f32_16x16x32_bf16 v[92:95], v[132:135], v[204:207], v[92:95]
	v_mfma_f32_16x16x32_bf16 v[88:91], v[140:143], v[204:207], v[88:91]
	v_mfma_f32_16x16x32_bf16 v[76:79], v[132:135], v[212:215], v[76:79]
	v_mfma_f32_16x16x32_bf16 v[72:75], v[140:143], v[212:215], v[72:75]

	v_mfma_f32_16x16x32_bf16 v[116:119], v[144:147], v[176:179], v[116:119]
	v_mfma_f32_16x16x32_bf16 v[112:115], v[168:171], v[176:179], v[112:115]
	v_mfma_f32_16x16x32_bf16 v[100:103], v[144:147], v[192:195], v[100:103]
	v_mfma_f32_16x16x32_bf16 v[96:99], v[168:171], v[192:195], v[96:99]
	v_mfma_f32_16x16x32_bf16 v[84:87], v[144:147], v[200:203], v[84:87]
	v_mfma_f32_16x16x32_bf16 v[80:83], v[168:171], v[200:203], v[80:83]
	v_mfma_f32_16x16x32_bf16 v[68:71], v[144:147], v[208:211], v[68:71]
	v_mfma_f32_16x16x32_bf16 v[64:67], v[168:171], v[208:211], v[64:67]
	v_mfma_f32_16x16x32_bf16 v[116:119], v[148:151], v[180:183], v[116:119]
	v_mfma_f32_16x16x32_bf16 v[112:115], v[172:175], v[180:183], v[112:115]
	v_mfma_f32_16x16x32_bf16 v[100:103], v[148:151], v[196:199], v[100:103]
	v_mfma_f32_16x16x32_bf16 v[96:99], v[172:175], v[196:199], v[96:99]
	v_mfma_f32_16x16x32_bf16 v[84:87], v[148:151], v[204:207], v[84:87]
	v_mfma_f32_16x16x32_bf16 v[80:83], v[172:175], v[204:207], v[80:83]
	v_mfma_f32_16x16x32_bf16 v[68:71], v[148:151], v[212:215], v[68:71]
	v_mfma_f32_16x16x32_bf16 v[64:67], v[172:175], v[212:215], v[64:67]

	s_barrier
	s_add_i32 s60, s84, s57
	v_lshl_add_u64 v[216:217], v[216:217], 0, s[8:9]
	s_mov_b32 m0, s60
	ds_read_b128 v[176:179], v189 offset:49152
	ds_read_b128 v[180:183], v189 offset:50176
	ds_read_b128 v[192:195], v189 offset:51200
	ds_read_b128 v[196:199], v189 offset:52224
	ds_read_b128 v[200:203], v189 offset:53248
	ds_read_b128 v[204:207], v189 offset:54272
	ds_read_b128 v[208:211], v189 offset:55296
	ds_read_b128 v[212:215], v189 offset:56320
	global_load_lds_dwordx4 v[216:217], off
	s_add_i32 m0, s60, 0x2000
	s_add_u32 s58, s58, 0x40080
	v_lshl_add_u64 v[216:217], v[218:219], 0, s[8:9]
	s_addc_u32 s59, s59, 0
	s_add_i32 s60, s85, s57
	global_load_lds_dwordx4 v[216:217], off

	s_mov_b32 m0, s60
	s_nop 0
	global_load_lds_dwordx4 v154, s[58:59]

	s_add_i32 m0, s60, 0x2000
	s_nop 0
	global_load_lds_dwordx4 v158, s[58:59]
	v_lshl_add_u64 v[216:217], v[220:221], 0, s[8:9]
	s_mov_b32 m0, s67
	s_nop 0
	global_load_lds_dwordx4 v[216:217], off
	v_lshl_add_u64 v[216:217], v[222:223], 0, s[8:9]
	s_mov_b32 m0, s68
	s_nop 0
	global_load_lds_dwordx4 v[216:217], off
	s_waitcnt vmcnt(8)
	s_waitcnt lgkmcnt(0)
	s_barrier

	v_mfma_f32_16x16x32_bf16 v[60:63], v[128:131], v[176:179], v[60:63]
	v_mfma_f32_16x16x32_bf16 v[56:59], v[136:139], v[176:179], v[56:59]
	v_mfma_f32_16x16x32_bf16 v[44:47], v[128:131], v[192:195], v[44:47]
	v_mfma_f32_16x16x32_bf16 v[40:43], v[136:139], v[192:195], v[40:43]
	v_mfma_f32_16x16x32_bf16 v[28:31], v[128:131], v[200:203], v[28:31]
	v_mfma_f32_16x16x32_bf16 v[24:27], v[136:139], v[200:203], v[24:27]
	v_mfma_f32_16x16x32_bf16 v[12:15], v[128:131], v[208:211], v[12:15]
	v_mfma_f32_16x16x32_bf16 v[8:11], v[136:139], v[208:211], v[8:11]
	v_mfma_f32_16x16x32_bf16 v[60:63], v[132:135], v[180:183], v[60:63]
	v_mfma_f32_16x16x32_bf16 v[56:59], v[140:143], v[180:183], v[56:59]
	v_mfma_f32_16x16x32_bf16 v[44:47], v[132:135], v[196:199], v[44:47]
	v_mfma_f32_16x16x32_bf16 v[40:43], v[140:143], v[196:199], v[40:43]
	v_mfma_f32_16x16x32_bf16 v[28:31], v[132:135], v[204:207], v[28:31]
	v_mfma_f32_16x16x32_bf16 v[24:27], v[140:143], v[204:207], v[24:27]
	v_mfma_f32_16x16x32_bf16 v[12:15], v[132:135], v[212:215], v[12:15]
	v_mfma_f32_16x16x32_bf16 v[8:11], v[140:143], v[212:215], v[8:11]

	v_mfma_f32_16x16x32_bf16 v[52:55], v[144:147], v[176:179], v[52:55]
	v_mfma_f32_16x16x32_bf16 v[48:51], v[168:171], v[176:179], v[48:51]
	v_mfma_f32_16x16x32_bf16 v[36:39], v[144:147], v[192:195], v[36:39]
	v_mfma_f32_16x16x32_bf16 v[32:35], v[168:171], v[192:195], v[32:35]
	v_mfma_f32_16x16x32_bf16 v[20:23], v[144:147], v[200:203], v[20:23]
	v_mfma_f32_16x16x32_bf16 v[16:19], v[168:171], v[200:203], v[16:19]
	v_mfma_f32_16x16x32_bf16 v[4:7], v[144:147], v[208:211], v[4:7]
	v_mfma_f32_16x16x32_bf16 v[0:3], v[168:171], v[208:211], v[0:3]
	v_mfma_f32_16x16x32_bf16 v[52:55], v[148:151], v[180:183], v[52:55]
	v_mfma_f32_16x16x32_bf16 v[48:51], v[172:175], v[180:183], v[48:51]
	v_mfma_f32_16x16x32_bf16 v[36:39], v[148:151], v[196:199], v[36:39]
	v_mfma_f32_16x16x32_bf16 v[32:35], v[172:175], v[196:199], v[32:35]
	v_mfma_f32_16x16x32_bf16 v[20:23], v[148:151], v[204:207], v[20:23]
	v_mfma_f32_16x16x32_bf16 v[16:19], v[172:175], v[204:207], v[16:19]
	v_mfma_f32_16x16x32_bf16 v[4:7], v[148:151], v[212:215], v[4:7]
	v_mfma_f32_16x16x32_bf16 v[0:3], v[172:175], v[212:215], v[0:3]

	s_barrier
	s_add_i32 s83, s83, 2
	s_add_u32 s52, s52, 0x100
	s_addc_u32 s53, s53, 0
	s_add_u32 s81, s81, 0x100
	s_addc_u32 s82, s82, 0
	s_cmp_gt_u32 s83, 13
	s_cbranch_scc0 .LBB0_741
	v_lshl_add_u32 v168, s79, 8, v184
	v_lshl_or_b32 v128, s78, 8, v186
	v_ashrrev_i32_e32 v169, 31, v168
	v_ashrrev_i32_e32 v129, 31, v128
	v_lshlrev_b64 v[130:131], 11, v[168:169]
	v_lshl_add_u64 v[130:131], s[34:35], 0, v[130:131]
	v_lshlrev_b64 v[170:171], 1, v[128:129]
	v_lshl_add_u64 v[200:201], v[130:131], 0, v[170:171]
	global_load_dwordx4 v[192:195], v[200:201], off
	global_load_dwordx4 v[196:199], v[200:201], off offset:256
	v_or_b32_e32 v180, 16, v168
	v_or_b32_e32 v176, 32, v168
	v_or_b32_e32 v172, 48, v168
	v_ashrrev_i32_e32 v181, 31, v180
	v_ashrrev_i32_e32 v177, 31, v176
	v_ashrrev_i32_e32 v173, 31, v172
	v_lshlrev_b64 v[128:129], 11, v[180:181]
	v_lshlrev_b64 v[130:131], 11, v[176:177]
	v_lshlrev_b64 v[132:133], 11, v[172:173]
	v_lshl_add_u64 v[128:129], s[34:35], 0, v[128:129]
	v_lshl_add_u64 v[130:131], s[34:35], 0, v[130:131]
	v_lshl_add_u64 v[132:133], s[34:35], 0, v[132:133]
	v_lshl_add_u64 v[182:183], v[128:129], 0, v[170:171]
	v_lshl_add_u64 v[178:179], v[130:131], 0, v[170:171]
	v_lshl_add_u64 v[174:175], v[132:133], 0, v[170:171]
	global_load_dwordx4 v[148:151], v[182:183], off
	global_load_dwordx4 v[144:147], v[182:183], off offset:256
	global_load_dwordx4 v[140:143], v[178:179], off
	global_load_dwordx4 v[136:139], v[178:179], off offset:256
	global_load_dwordx4 v[132:135], v[174:175], off
	global_load_dwordx4 v[128:131], v[174:175], off offset:256
	v_and_b32_e32 v202, 64, v190
	v_xor_b32_e32 v191, 16, v190
	v_add_u32_e32 v202, 64, v202
	v_xor_b32_e32 v203, 32, v190
	v_cmp_lt_i32_e32 vcc, v191, v202
	s_lshl_b32 s52, s78, 2
	s_ashr_i32 s53, s52, 31
	v_cndmask_b32_e32 v191, v190, v191, vcc
	v_cmp_lt_i32_e32 vcc, v203, v202
	v_lshlrev_b32_e32 v191, 2, v191
	s_waitcnt vmcnt(0)
	v_lshlrev_b32_e32 v202, 16, v192
	v_cndmask_b32_e32 v210, v190, v203, vcc
	v_and_b32_e32 v203, 0xffff0000, v192
	v_lshlrev_b32_e32 v192, 16, v193
	v_and_b32_e32 v193, 0xffff0000, v193
	v_lshlrev_b32_e32 v204, 16, v194
	v_and_b32_e32 v205, 0xffff0000, v194
	v_lshlrev_b32_e32 v194, 16, v195
	v_and_b32_e32 v195, 0xffff0000, v195
	v_lshlrev_b32_e32 v206, 16, v196
	v_and_b32_e32 v207, 0xffff0000, v196
	v_lshlrev_b32_e32 v196, 16, v197
	v_and_b32_e32 v197, 0xffff0000, v197
	v_lshlrev_b32_e32 v208, 16, v198
	v_and_b32_e32 v209, 0xffff0000, v198
	v_lshlrev_b32_e32 v198, 16, v199
	v_and_b32_e32 v199, 0xffff0000, v199
	v_pk_add_f32 v[126:127], v[126:127], v[192:193]
	v_pk_add_f32 v[124:125], v[124:125], v[202:203]
	v_pk_add_f32 v[122:123], v[122:123], v[194:195]
	v_pk_add_f32 v[120:121], v[120:121], v[204:205]
	v_pk_add_f32 v[118:119], v[118:119], v[196:197]
	v_pk_add_f32 v[116:117], v[116:117], v[206:207]
	v_pk_add_f32 v[192:193], v[114:115], v[198:199]
	v_pk_add_f32 v[194:195], v[112:113], v[208:209]
	v_cvt_pk_bf16_f32 v112, v124, v125
	v_cvt_pk_bf16_f32 v113, v126, v127
	v_mul_f32_e32 v114, v125, v125
	v_mul_f32_e32 v115, v127, v127
	v_mul_f32_e32 v125, v121, v121
	v_mul_f32_e32 v127, v123, v123
	v_mul_f32_e32 v196, v117, v117
	v_mul_f32_e32 v197, v119, v119
	v_mul_f32_e32 v198, v195, v195
	v_mul_f32_e32 v199, v193, v193
	v_fmac_f32_e32 v114, v124, v124
	v_fmac_f32_e32 v115, v126, v126
	v_fmac_f32_e32 v125, v120, v120
	v_fmac_f32_e32 v127, v122, v122
	v_fmac_f32_e32 v196, v116, v116
	v_fmac_f32_e32 v197, v118, v118
	v_fmac_f32_e32 v198, v194, v194
	v_fmac_f32_e32 v199, v192, v192
	v_add_f32_e32 v114, v114, v115
	v_add_f32_e32 v115, v125, v127
	v_add_f32_e32 v124, v196, v197
	v_add_f32_e32 v125, v198, v199
	v_add_f32_e32 v114, v114, v115
	v_add_f32_e32 v115, v124, v125
	v_add_f32_e32 v124, v114, v115
	ds_bpermute_b32 v125, v191, v124
	v_cvt_pk_bf16_f32 v114, v120, v121
	v_cvt_pk_bf16_f32 v115, v122, v123
	global_store_dwordx4 v[200:201], v[112:115], off
	v_cvt_pk_bf16_f32 v116, v116, v117
	v_cvt_pk_bf16_f32 v117, v118, v119
	s_waitcnt lgkmcnt(0)
	v_add_f32_e32 v113, v124, v125
	v_lshlrev_b32_e32 v112, 2, v210
	ds_bpermute_b32 v114, v112, v113
	v_cvt_pk_bf16_f32 v118, v194, v195
	v_cvt_pk_bf16_f32 v119, v192, v193
	global_store_dwordx4 v[200:201], v[116:119], off offset:256
	s_and_saveexec_b64 s[58:59], s[0:1]
	s_cbranch_execz .LBB0_744
	s_waitcnt lgkmcnt(0)
	v_add_f32_e32 v113, v113, v114
	v_lshlrev_b64 v[114:115], 6, v[168:169]
	v_lshl_add_u64 v[114:115], s[74:75], 0, v[114:115]
	v_lshl_add_u64 v[114:115], s[52:53], 2, v[114:115]
	s_lshl_b32 s6, s66, 2
	v_lshl_add_u64 v[114:115], v[114:115], 0, s[6:7]
	global_store_dword v[114:115], v113, off

.LBB0_876:
	ds_read_b128 v[96:99], v182
	ds_read_b128 v[100:103], v182 offset:1024
	ds_read_b128 v[104:107], v182 offset:2048
	ds_read_b128 v[108:111], v182 offset:3072
	ds_read_b128 v[112:115], v183
	ds_read_b128 v[116:119], v183 offset:1024
	ds_read_b128 v[120:123], v183 offset:2048
	ds_read_b128 v[124:127], v183 offset:3072
	s_add_u32 s88, s86, 0xfff80080
	s_addc_u32 s89, s87, -1
	s_cmp_eq_u32 s68, 12
	s_cselect_b32 s91, s3, s5
	s_cselect_b32 s90, s61, s4
	s_cselect_b32 s89, s65, s89
	s_cselect_b32 s88, s73, s88

	s_add_i32 m0, s41, 0xc000
	ds_read_b128 v[128:131], v184
	ds_read_b128 v[150:153], v184 offset:1024
	ds_read_b128 v[154:157], v184 offset:2048
	ds_read_b128 v[158:161], v184 offset:3072
	ds_read_b128 v[162:165], v184 offset:4096
	ds_read_b128 v[176:179], v184 offset:5120
	ds_read_b128 v[188:191], v184 offset:6144
	ds_read_b128 v[192:195], v184 offset:7168
	global_load_lds_dwordx4 v142, s[86:87]

	s_add_i32 m0, s41, 0xe000
	s_nop 0
	global_load_lds_dwordx4 v144, s[86:87]
	s_waitcnt vmcnt(8)
	s_waitcnt lgkmcnt(0)
	s_barrier

	v_mfma_f32_16x16x32_bf16 v[92:95], v[96:99], v[128:131], v[92:95]
	v_mfma_f32_16x16x32_bf16 v[88:91], v[104:107], v[128:131], v[88:91]
	v_mfma_f32_16x16x32_bf16 v[84:87], v[96:99], v[154:157], v[84:87]
	v_mfma_f32_16x16x32_bf16 v[80:83], v[104:107], v[154:157], v[80:83]
	v_mfma_f32_16x16x32_bf16 v[68:71], v[96:99], v[162:165], v[68:71]
	v_mfma_f32_16x16x32_bf16 v[64:67], v[104:107], v[162:165], v[64:67]
	v_mfma_f32_16x16x32_bf16 v[52:55], v[96:99], v[188:191], v[52:55]
	v_mfma_f32_16x16x32_bf16 v[48:51], v[104:107], v[188:191], v[48:51]
	v_mfma_f32_16x16x32_bf16 v[92:95], v[100:103], v[150:153], v[92:95]
	v_mfma_f32_16x16x32_bf16 v[88:91], v[108:111], v[150:153], v[88:91]
	v_mfma_f32_16x16x32_bf16 v[84:87], v[100:103], v[158:161], v[84:87]
	v_mfma_f32_16x16x32_bf16 v[80:83], v[108:111], v[158:161], v[80:83]
	v_mfma_f32_16x16x32_bf16 v[68:71], v[100:103], v[176:179], v[68:71]
	v_mfma_f32_16x16x32_bf16 v[64:67], v[108:111], v[176:179], v[64:67]
	v_mfma_f32_16x16x32_bf16 v[52:55], v[100:103], v[192:195], v[52:55]
	v_mfma_f32_16x16x32_bf16 v[48:51], v[108:111], v[192:195], v[48:51]

	v_mfma_f32_16x16x32_bf16 v[76:79], v[112:115], v[128:131], v[76:79]
	v_mfma_f32_16x16x32_bf16 v[72:75], v[120:123], v[128:131], v[72:75]
	v_mfma_f32_16x16x32_bf16 v[60:63], v[112:115], v[154:157], v[60:63]
	v_mfma_f32_16x16x32_bf16 v[56:59], v[120:123], v[154:157], v[56:59]
	v_mfma_f32_16x16x32_bf16 v[44:47], v[112:115], v[162:165], v[44:47]
	v_mfma_f32_16x16x32_bf16 v[40:43], v[120:123], v[162:165], v[40:43]
	v_mfma_f32_16x16x32_bf16 v[36:39], v[112:115], v[188:191], v[36:39]
	v_mfma_f32_16x16x32_bf16 v[32:35], v[120:123], v[188:191], v[32:35]
	v_mfma_f32_16x16x32_bf16 v[76:79], v[116:119], v[150:153], v[76:79]
	v_mfma_f32_16x16x32_bf16 v[72:75], v[124:127], v[150:153], v[72:75]
	v_mfma_f32_16x16x32_bf16 v[60:63], v[116:119], v[158:161], v[60:63]
	v_mfma_f32_16x16x32_bf16 v[56:59], v[124:127], v[158:161], v[56:59]
	v_mfma_f32_16x16x32_bf16 v[44:47], v[116:119], v[176:179], v[44:47]
	v_mfma_f32_16x16x32_bf16 v[40:43], v[124:127], v[176:179], v[40:43]
	v_mfma_f32_16x16x32_bf16 v[36:39], v[116:119], v[192:195], v[36:39]
	v_mfma_f32_16x16x32_bf16 v[32:35], v[124:127], v[192:195], v[32:35]

	s_barrier
	s_add_i32 s92, s76, s15
	v_lshl_add_u64 v[168:169], s[88:89], 0, v[134:135]
	s_mov_b32 m0, s92
	ds_read_b128 v[96:99], v185 offset:16384
	ds_read_b128 v[100:103], v185 offset:17408
	ds_read_b128 v[104:107], v185 offset:18432
	ds_read_b128 v[108:111], v185 offset:19456
	global_load_lds_dwordx4 v[168:169], off
	s_add_i32 m0, s92, 0x2000
	s_add_u32 s92, s88, 0x40000
	v_lshl_add_u64 v[172:173], s[88:89], 0, v[138:139]
	s_addc_u32 s93, s89, 0
	s_add_i32 vcc_lo, s77, s15
	global_load_lds_dwordx4 v[172:173], off

	s_mov_b32 m0, vcc_lo
	v_lshl_add_u64 v[180:181], s[90:91], 0, v[132:133]
	global_load_lds_dwordx4 v134, s[92:93]

	s_add_i32 m0, vcc_lo, 0x2000
	v_lshl_add_u64 v[196:197], s[90:91], 0, v[136:137]
	global_load_lds_dwordx4 v138, s[92:93]
	s_mov_b32 m0, s41
	s_nop 0
	global_load_lds_dwordx4 v[180:181], off
	s_mov_b32 m0, s52
	s_nop 0
	global_load_lds_dwordx4 v[196:197], off
	s_waitcnt vmcnt(8)
	s_waitcnt lgkmcnt(0)
	s_barrier

	v_mfma_f32_16x16x32_bf16 v[28:31], v[96:99], v[128:131], v[28:31]
	v_mfma_f32_16x16x32_bf16 v[24:27], v[104:107], v[128:131], v[24:27]
	v_mfma_f32_16x16x32_bf16 v[20:23], v[96:99], v[154:157], v[20:23]
	v_mfma_f32_16x16x32_bf16 v[16:19], v[104:107], v[154:157], v[16:19]
	v_mfma_f32_16x16x32_bf16 v[12:15], v[96:99], v[162:165], v[12:15]
	v_mfma_f32_16x16x32_bf16 v[8:11], v[104:107], v[162:165], v[8:11]
	v_mfma_f32_16x16x32_bf16 v[4:7], v[96:99], v[188:191], v[4:7]
	v_mfma_f32_16x16x32_bf16 v[0:3], v[104:107], v[188:191], v[0:3]
	v_mfma_f32_16x16x32_bf16 v[28:31], v[100:103], v[150:153], v[28:31]
	v_mfma_f32_16x16x32_bf16 v[24:27], v[108:111], v[150:153], v[24:27]
	v_mfma_f32_16x16x32_bf16 v[20:23], v[100:103], v[158:161], v[20:23]
	v_mfma_f32_16x16x32_bf16 v[16:19], v[108:111], v[158:161], v[16:19]
	v_mfma_f32_16x16x32_bf16 v[12:15], v[100:103], v[176:179], v[12:15]
	v_mfma_f32_16x16x32_bf16 v[8:11], v[108:111], v[176:179], v[8:11]
	v_mfma_f32_16x16x32_bf16 v[4:7], v[100:103], v[192:195], v[4:7]
	v_mfma_f32_16x16x32_bf16 v[0:3], v[108:111], v[192:195], v[0:3]

	s_barrier
	s_add_i32 s92, 0, 0x18000
	s_add_i32 s93, 0, 0x1c000
	v_add_u32_e32 v108, s92, v171
	v_add_u32_e32 v124, s93, v171
	ds_read_b128 v[96:99], v108
	ds_read_b128 v[100:103], v108 offset:1024
	ds_read_b128 v[104:107], v108 offset:2048
	ds_read_b128 v[108:111], v108 offset:3072
	ds_read_b128 v[112:115], v124
	ds_read_b128 v[116:119], v124 offset:1024
	ds_read_b128 v[120:123], v124 offset:2048
	ds_read_b128 v[124:127], v124 offset:3072
	s_add_u32 s90, s88, 0x80000
	s_addc_u32 s91, s89, 0
	s_mov_b32 m0, s53

	ds_read_b128 v[128:131], v184 offset:32768
	ds_read_b128 v[150:153], v184 offset:33792
	ds_read_b128 v[154:157], v184 offset:34816
	ds_read_b128 v[158:161], v184 offset:35840
	ds_read_b128 v[162:165], v184 offset:36864
	ds_read_b128 v[176:179], v184 offset:37888
	ds_read_b128 v[188:191], v184 offset:38912
	ds_read_b128 v[192:195], v184 offset:39936
	global_load_lds_dwordx4 v134, s[90:91]

	s_mov_b32 m0, s54
	s_nop 0
	global_load_lds_dwordx4 v138, s[90:91]
	s_waitcnt vmcnt(8)
	s_waitcnt lgkmcnt(0)
	s_barrier

	v_mfma_f32_16x16x32_bf16 v[92:95], v[96:99], v[128:131], v[92:95]
	v_mfma_f32_16x16x32_bf16 v[88:91], v[104:107], v[128:131], v[88:91]
	v_mfma_f32_16x16x32_bf16 v[84:87], v[96:99], v[154:157], v[84:87]
	v_mfma_f32_16x16x32_bf16 v[80:83], v[104:107], v[154:157], v[80:83]
	v_mfma_f32_16x16x32_bf16 v[68:71], v[96:99], v[162:165], v[68:71]
	v_mfma_f32_16x16x32_bf16 v[64:67], v[104:107], v[162:165], v[64:67]
	v_mfma_f32_16x16x32_bf16 v[52:55], v[96:99], v[188:191], v[52:55]
	v_mfma_f32_16x16x32_bf16 v[48:51], v[104:107], v[188:191], v[48:51]
	v_mfma_f32_16x16x32_bf16 v[92:95], v[100:103], v[150:153], v[92:95]
	v_mfma_f32_16x16x32_bf16 v[88:91], v[108:111], v[150:153], v[88:91]
	v_mfma_f32_16x16x32_bf16 v[84:87], v[100:103], v[158:161], v[84:87]
	v_mfma_f32_16x16x32_bf16 v[80:83], v[108:111], v[158:161], v[80:83]
	v_mfma_f32_16x16x32_bf16 v[68:71], v[100:103], v[176:179], v[68:71]
	v_mfma_f32_16x16x32_bf16 v[64:67], v[108:111], v[176:179], v[64:67]
	v_mfma_f32_16x16x32_bf16 v[52:55], v[100:103], v[192:195], v[52:55]
	v_mfma_f32_16x16x32_bf16 v[48:51], v[108:111], v[192:195], v[48:51]

	v_mfma_f32_16x16x32_bf16 v[76:79], v[112:115], v[128:131], v[76:79]
	v_mfma_f32_16x16x32_bf16 v[72:75], v[120:123], v[128:131], v[72:75]
	v_mfma_f32_16x16x32_bf16 v[60:63], v[112:115], v[154:157], v[60:63]
	v_mfma_f32_16x16x32_bf16 v[56:59], v[120:123], v[154:157], v[56:59]
	v_mfma_f32_16x16x32_bf16 v[44:47], v[112:115], v[162:165], v[44:47]
	v_mfma_f32_16x16x32_bf16 v[40:43], v[120:123], v[162:165], v[40:43]
	v_mfma_f32_16x16x32_bf16 v[36:39], v[112:115], v[188:191], v[36:39]
	v_mfma_f32_16x16x32_bf16 v[32:35], v[120:123], v[188:191], v[32:35]
	v_mfma_f32_16x16x32_bf16 v[76:79], v[116:119], v[150:153], v[76:79]
	v_mfma_f32_16x16x32_bf16 v[72:75], v[124:127], v[150:153], v[72:75]
	v_mfma_f32_16x16x32_bf16 v[60:63], v[116:119], v[158:161], v[60:63]
	v_mfma_f32_16x16x32_bf16 v[56:59], v[124:127], v[158:161], v[56:59]
	v_mfma_f32_16x16x32_bf16 v[44:47], v[116:119], v[176:179], v[44:47]
	v_mfma_f32_16x16x32_bf16 v[40:43], v[124:127], v[176:179], v[40:43]
	v_mfma_f32_16x16x32_bf16 v[36:39], v[116:119], v[192:195], v[36:39]
	v_mfma_f32_16x16x32_bf16 v[32:35], v[124:127], v[192:195], v[32:35]

	s_barrier
	s_add_i32 s90, s92, s15
	v_lshl_add_u64 v[112:113], v[168:169], 0, s[10:11]
	s_mov_b32 m0, s90
	ds_read_b128 v[96:99], v185 offset:49152
	ds_read_b128 v[100:103], v185 offset:50176
	ds_read_b128 v[104:107], v185 offset:51200
	ds_read_b128 v[108:111], v185 offset:52224
	global_load_lds_dwordx4 v[112:113], off
	s_add_i32 m0, s90, 0x2000
	s_add_u32 s88, s88, 0x40080
	v_lshl_add_u64 v[112:113], v[172:173], 0, s[10:11]
	s_addc_u32 s89, s89, 0
	s_add_i32 s90, s93, s15
	global_load_lds_dwordx4 v[112:113], off

	s_mov_b32 m0, s90
	s_nop 0
	global_load_lds_dwordx4 v134, s[88:89]

	s_add_i32 m0, s90, 0x2000
	s_nop 0
	global_load_lds_dwordx4 v138, s[88:89]
	v_lshl_add_u64 v[112:113], v[180:181], 0, s[10:11]
	s_mov_b32 m0, s55
	s_nop 0
	global_load_lds_dwordx4 v[112:113], off
	v_lshl_add_u64 v[112:113], v[196:197], 0, s[10:11]
	s_mov_b32 m0, s56
	s_nop 0
	global_load_lds_dwordx4 v[112:113], off
	s_waitcnt vmcnt(8)
	s_waitcnt lgkmcnt(0)
	s_barrier

	v_mfma_f32_16x16x32_bf16 v[28:31], v[96:99], v[128:131], v[28:31]
	v_mfma_f32_16x16x32_bf16 v[24:27], v[104:107], v[128:131], v[24:27]
	v_mfma_f32_16x16x32_bf16 v[20:23], v[96:99], v[154:157], v[20:23]
	v_mfma_f32_16x16x32_bf16 v[16:19], v[104:107], v[154:157], v[16:19]
	v_mfma_f32_16x16x32_bf16 v[12:15], v[96:99], v[162:165], v[12:15]
	v_mfma_f32_16x16x32_bf16 v[8:11], v[104:107], v[162:165], v[8:11]
	v_mfma_f32_16x16x32_bf16 v[4:7], v[96:99], v[188:191], v[4:7]
	v_mfma_f32_16x16x32_bf16 v[0:3], v[104:107], v[188:191], v[0:3]
	v_mfma_f32_16x16x32_bf16 v[28:31], v[100:103], v[150:153], v[28:31]
	v_mfma_f32_16x16x32_bf16 v[24:27], v[108:111], v[150:153], v[24:27]
	v_mfma_f32_16x16x32_bf16 v[20:23], v[100:103], v[158:161], v[20:23]
	v_mfma_f32_16x16x32_bf16 v[16:19], v[108:111], v[158:161], v[16:19]
	v_mfma_f32_16x16x32_bf16 v[12:15], v[100:103], v[176:179], v[12:15]
	v_mfma_f32_16x16x32_bf16 v[8:11], v[108:111], v[176:179], v[8:11]
	v_mfma_f32_16x16x32_bf16 v[4:7], v[100:103], v[192:195], v[4:7]
	v_mfma_f32_16x16x32_bf16 v[0:3], v[108:111], v[192:195], v[0:3]

	s_barrier
	s_add_i32 s68, s68, 2
	s_add_u32 s4, s4, 0x100
	s_addc_u32 s5, s5, 0
	s_add_u32 s86, s86, 0x100
	s_addc_u32 s87, s87, 0
	s_cmp_gt_u32 s68, 13
	s_cbranch_scc0 .LBB0_876
	s_mov_b64 s[86:87], 0
	s_branch .LBB0_879

.LBB0_881:
	ds_read_b128 v[128:131], v182
	ds_read_b128 v[150:153], v182 offset:1024
	ds_read_b128 v[154:157], v182 offset:2048
	ds_read_b128 v[158:161], v182 offset:3072
	ds_read_b128 v[162:165], v183
	ds_read_b128 v[176:179], v183 offset:1024
	ds_read_b128 v[188:191], v183 offset:2048
	ds_read_b128 v[192:195], v183 offset:3072
	s_add_u32 s92, s84, 0xfffc0080
	s_addc_u32 s93, s85, -1
	s_cmp_eq_u32 s5, 12
	s_cselect_b64 s[90:91], -1, 0
	s_and_b64 s[88:89], s[90:91], exec
	s_cselect_b32 s89, s65, s71
	s_cselect_b32 s88, s73, s69
	s_cselect_b32 s93, s3, s93
	s_cselect_b32 s92, s61, s92

	s_add_i32 m0, s41, 0xc000
	ds_read_b128 v[196:199], v184
	ds_read_b128 v[200:203], v184 offset:1024
	ds_read_b128 v[204:207], v184 offset:2048
	ds_read_b128 v[208:211], v184 offset:3072
	ds_read_b128 v[212:215], v184 offset:4096
	ds_read_b128 v[216:219], v184 offset:5120
	ds_read_b128 v[220:223], v184 offset:6144
	ds_read_b128 v[224:227], v184 offset:7168
	global_load_lds_dwordx4 v146, s[84:85]

	s_add_i32 m0, s41, 0xe000
	s_nop 0
	global_load_lds_dwordx4 v136, s[84:85]
	s_waitcnt vmcnt(8)
	s_waitcnt lgkmcnt(0)
	s_barrier

	v_mfma_f32_16x16x32_bf16 v[92:95], v[128:131], v[196:199], v[92:95]
	v_mfma_f32_16x16x32_bf16 v[88:91], v[154:157], v[196:199], v[88:91]
	v_mfma_f32_16x16x32_bf16 v[84:87], v[128:131], v[204:207], v[84:87]
	v_mfma_f32_16x16x32_bf16 v[80:83], v[154:157], v[204:207], v[80:83]
	v_mfma_f32_16x16x32_bf16 v[68:71], v[128:131], v[212:215], v[68:71]
	v_mfma_f32_16x16x32_bf16 v[64:67], v[154:157], v[212:215], v[64:67]
	v_mfma_f32_16x16x32_bf16 v[52:55], v[128:131], v[220:223], v[52:55]
	v_mfma_f32_16x16x32_bf16 v[48:51], v[154:157], v[220:223], v[48:51]
	v_mfma_f32_16x16x32_bf16 v[92:95], v[150:153], v[200:203], v[92:95]
	v_mfma_f32_16x16x32_bf16 v[88:91], v[158:161], v[200:203], v[88:91]
	v_mfma_f32_16x16x32_bf16 v[84:87], v[150:153], v[208:211], v[84:87]
	v_mfma_f32_16x16x32_bf16 v[80:83], v[158:161], v[208:211], v[80:83]
	v_mfma_f32_16x16x32_bf16 v[68:71], v[150:153], v[216:219], v[68:71]
	v_mfma_f32_16x16x32_bf16 v[64:67], v[158:161], v[216:219], v[64:67]
	v_mfma_f32_16x16x32_bf16 v[52:55], v[150:153], v[224:227], v[52:55]
	v_mfma_f32_16x16x32_bf16 v[48:51], v[158:161], v[224:227], v[48:51]

	v_mfma_f32_16x16x32_bf16 v[76:79], v[162:165], v[196:199], v[76:79]
	v_mfma_f32_16x16x32_bf16 v[72:75], v[188:191], v[196:199], v[72:75]
	v_mfma_f32_16x16x32_bf16 v[60:63], v[162:165], v[204:207], v[60:63]
	v_mfma_f32_16x16x32_bf16 v[56:59], v[188:191], v[204:207], v[56:59]
	v_mfma_f32_16x16x32_bf16 v[44:47], v[162:165], v[212:215], v[44:47]
	v_mfma_f32_16x16x32_bf16 v[40:43], v[188:191], v[212:215], v[40:43]
	v_mfma_f32_16x16x32_bf16 v[36:39], v[162:165], v[220:223], v[36:39]
	v_mfma_f32_16x16x32_bf16 v[32:35], v[188:191], v[220:223], v[32:35]
	v_mfma_f32_16x16x32_bf16 v[76:79], v[176:179], v[200:203], v[76:79]
	v_mfma_f32_16x16x32_bf16 v[72:75], v[192:195], v[200:203], v[72:75]
	v_mfma_f32_16x16x32_bf16 v[60:63], v[176:179], v[208:211], v[60:63]
	v_mfma_f32_16x16x32_bf16 v[56:59], v[192:195], v[208:211], v[56:59]
	v_mfma_f32_16x16x32_bf16 v[44:47], v[176:179], v[216:219], v[44:47]
	v_mfma_f32_16x16x32_bf16 v[40:43], v[192:195], v[216:219], v[40:43]
	v_mfma_f32_16x16x32_bf16 v[36:39], v[176:179], v[224:227], v[36:39]
	v_mfma_f32_16x16x32_bf16 v[32:35], v[192:195], v[224:227], v[32:35]

	s_barrier
	s_add_i32 vcc_lo, s76, s15
	v_lshl_add_u64 v[168:169], s[88:89], 0, v[134:135]
	s_mov_b32 m0, vcc_lo
	ds_read_b128 v[196:199], v184 offset:16384
	ds_read_b128 v[200:203], v184 offset:17408
	ds_read_b128 v[204:207], v184 offset:18432
	ds_read_b128 v[208:211], v184 offset:19456
	ds_read_b128 v[212:215], v184 offset:20480
	ds_read_b128 v[216:219], v184 offset:21504
	ds_read_b128 v[220:223], v184 offset:22528
	ds_read_b128 v[224:227], v184 offset:23552
	global_load_lds_dwordx4 v[168:169], off
	s_add_i32 m0, vcc_lo, 0x2000
	s_add_u32 vcc_lo, s88, 0x40000
	v_lshl_add_u64 v[172:173], s[88:89], 0, v[138:139]
	s_addc_u32 vcc_hi, s89, 0
	s_add_i32 s6, s77, s15
	global_load_lds_dwordx4 v[172:173], off
	v_lshl_add_u64 v[180:181], vcc, 0, v[134:135]
	s_mov_b32 m0, s6
	v_lshl_add_u64 v[228:229], s[92:93], 0, v[136:137]
	global_load_lds_dwordx4 v[180:181], off
	v_lshl_add_u64 v[180:181], vcc, 0, v[138:139]
	s_add_i32 m0, s6, 0x2000
	s_nop 0
	global_load_lds_dwordx4 v[180:181], off
	v_lshl_add_u64 v[180:181], s[92:93], 0, v[132:133]
	s_mov_b32 m0, s41
	s_nop 0
	global_load_lds_dwordx4 v[180:181], off
	s_mov_b32 m0, s52
	s_nop 0
	global_load_lds_dwordx4 v[228:229], off
	s_waitcnt vmcnt(8)
	s_waitcnt lgkmcnt(0)
	s_barrier

	v_mfma_f32_16x16x32_bf16 v[28:31], v[128:131], v[196:199], v[28:31]
	v_mfma_f32_16x16x32_bf16 v[24:27], v[154:157], v[196:199], v[24:27]
	v_mfma_f32_16x16x32_bf16 v[20:23], v[128:131], v[204:207], v[20:23]
	v_mfma_f32_16x16x32_bf16 v[16:19], v[154:157], v[204:207], v[16:19]
	v_mfma_f32_16x16x32_bf16 v[12:15], v[128:131], v[212:215], v[12:15]
	v_mfma_f32_16x16x32_bf16 v[8:11], v[154:157], v[212:215], v[8:11]
	v_mfma_f32_16x16x32_bf16 v[4:7], v[128:131], v[220:223], v[4:7]
	v_mfma_f32_16x16x32_bf16 v[0:3], v[154:157], v[220:223], v[0:3]
	v_mfma_f32_16x16x32_bf16 v[28:31], v[150:153], v[200:203], v[28:31]
	v_mfma_f32_16x16x32_bf16 v[24:27], v[158:161], v[200:203], v[24:27]
	v_mfma_f32_16x16x32_bf16 v[20:23], v[150:153], v[208:211], v[20:23]
	v_mfma_f32_16x16x32_bf16 v[16:19], v[158:161], v[208:211], v[16:19]
	v_mfma_f32_16x16x32_bf16 v[12:15], v[150:153], v[216:219], v[12:15]
	v_mfma_f32_16x16x32_bf16 v[8:11], v[158:161], v[216:219], v[8:11]
	v_mfma_f32_16x16x32_bf16 v[4:7], v[150:153], v[224:227], v[4:7]
	v_mfma_f32_16x16x32_bf16 v[0:3], v[158:161], v[224:227], v[0:3]

	v_mfma_f32_16x16x32_bf16 v[124:127], v[162:165], v[196:199], v[124:127]
	v_mfma_f32_16x16x32_bf16 v[120:123], v[188:191], v[196:199], v[120:123]
	v_mfma_f32_16x16x32_bf16 v[116:119], v[162:165], v[204:207], v[116:119]
	v_mfma_f32_16x16x32_bf16 v[112:115], v[188:191], v[204:207], v[112:115]
	v_mfma_f32_16x16x32_bf16 v[108:111], v[162:165], v[212:215], v[108:111]
	v_mfma_f32_16x16x32_bf16 v[104:107], v[188:191], v[212:215], v[104:107]
	v_mfma_f32_16x16x32_bf16 v[100:103], v[162:165], v[220:223], v[100:103]
	v_mfma_f32_16x16x32_bf16 v[96:99], v[188:191], v[220:223], v[96:99]
	v_mfma_f32_16x16x32_bf16 v[124:127], v[176:179], v[200:203], v[124:127]
	v_mfma_f32_16x16x32_bf16 v[120:123], v[192:195], v[200:203], v[120:123]
	v_mfma_f32_16x16x32_bf16 v[116:119], v[176:179], v[208:211], v[116:119]
	v_mfma_f32_16x16x32_bf16 v[112:115], v[192:195], v[208:211], v[112:115]
	v_mfma_f32_16x16x32_bf16 v[108:111], v[176:179], v[216:219], v[108:111]
	v_mfma_f32_16x16x32_bf16 v[104:107], v[192:195], v[216:219], v[104:107]
	v_mfma_f32_16x16x32_bf16 v[100:103], v[176:179], v[224:227], v[100:103]
	v_mfma_f32_16x16x32_bf16 v[96:99], v[192:195], v[224:227], v[96:99]

	s_barrier
	s_add_i32 s6, 0, 0x18000
	s_add_i32 s7, 0, 0x1c000
	v_add_u32_e32 v158, s6, v171
	v_add_u32_e32 v166, s7, v171
	ds_read_b128 v[128:131], v158
	ds_read_b128 v[150:153], v158 offset:1024
	ds_read_b128 v[154:157], v158 offset:2048
	ds_read_b128 v[158:161], v158 offset:3072
	ds_read_b128 v[162:165], v166
	ds_read_b128 v[176:179], v166 offset:1024
	ds_read_b128 v[188:191], v166 offset:2048
	ds_read_b128 v[192:195], v166 offset:3072
	s_and_b64 s[90:91], s[62:63], s[90:91]
	s_and_b64 vcc, s[90:91], s[86:87]
	s_add_u32 s92, s92, 0x40000
	s_addc_u32 s93, s93, 0
	s_and_b64 s[90:91], vcc, exec
	s_mov_b32 m0, s53
	v_cndmask_b32_e32 v166, v132, v134, vcc
	s_cselect_b32 s91, s4, s93
	s_cselect_b32 s90, s68, s92
	ds_read_b128 v[196:199], v184 offset:32768
	ds_read_b128 v[200:203], v184 offset:33792
	ds_read_b128 v[204:207], v184 offset:34816
	ds_read_b128 v[208:211], v184 offset:35840
	ds_read_b128 v[212:215], v184 offset:36864
	ds_read_b128 v[216:219], v184 offset:37888
	ds_read_b128 v[220:223], v184 offset:38912
	ds_read_b128 v[224:227], v184 offset:39936
	v_cndmask_b32_e32 v170, v136, v138, vcc
	global_load_lds_dwordx4 v166, s[90:91]
	s_mov_b32 m0, s54
	s_nop 0
	global_load_lds_dwordx4 v170, s[90:91]
	s_waitcnt vmcnt(8)
	s_waitcnt lgkmcnt(0)
	s_barrier

	v_mfma_f32_16x16x32_bf16 v[92:95], v[128:131], v[196:199], v[92:95]
	v_mfma_f32_16x16x32_bf16 v[88:91], v[154:157], v[196:199], v[88:91]
	v_mfma_f32_16x16x32_bf16 v[84:87], v[128:131], v[204:207], v[84:87]
	v_mfma_f32_16x16x32_bf16 v[80:83], v[154:157], v[204:207], v[80:83]
	v_mfma_f32_16x16x32_bf16 v[68:71], v[128:131], v[212:215], v[68:71]
	v_mfma_f32_16x16x32_bf16 v[64:67], v[154:157], v[212:215], v[64:67]
	v_mfma_f32_16x16x32_bf16 v[52:55], v[128:131], v[220:223], v[52:55]
	v_mfma_f32_16x16x32_bf16 v[48:51], v[154:157], v[220:223], v[48:51]
	v_mfma_f32_16x16x32_bf16 v[92:95], v[150:153], v[200:203], v[92:95]
	v_mfma_f32_16x16x32_bf16 v[88:91], v[158:161], v[200:203], v[88:91]
	v_mfma_f32_16x16x32_bf16 v[84:87], v[150:153], v[208:211], v[84:87]
	v_mfma_f32_16x16x32_bf16 v[80:83], v[158:161], v[208:211], v[80:83]
	v_mfma_f32_16x16x32_bf16 v[68:71], v[150:153], v[216:219], v[68:71]
	v_mfma_f32_16x16x32_bf16 v[64:67], v[158:161], v[216:219], v[64:67]
	v_mfma_f32_16x16x32_bf16 v[52:55], v[150:153], v[224:227], v[52:55]
	v_mfma_f32_16x16x32_bf16 v[48:51], v[158:161], v[224:227], v[48:51]

	v_mfma_f32_16x16x32_bf16 v[76:79], v[162:165], v[196:199], v[76:79]
	v_mfma_f32_16x16x32_bf16 v[72:75], v[188:191], v[196:199], v[72:75]
	v_mfma_f32_16x16x32_bf16 v[60:63], v[162:165], v[204:207], v[60:63]
	v_mfma_f32_16x16x32_bf16 v[56:59], v[188:191], v[204:207], v[56:59]
	v_mfma_f32_16x16x32_bf16 v[44:47], v[162:165], v[212:215], v[44:47]
	v_mfma_f32_16x16x32_bf16 v[40:43], v[188:191], v[212:215], v[40:43]
	v_mfma_f32_16x16x32_bf16 v[36:39], v[162:165], v[220:223], v[36:39]
	v_mfma_f32_16x16x32_bf16 v[32:35], v[188:191], v[220:223], v[32:35]
	v_mfma_f32_16x16x32_bf16 v[76:79], v[176:179], v[200:203], v[76:79]
	v_mfma_f32_16x16x32_bf16 v[72:75], v[192:195], v[200:203], v[72:75]
	v_mfma_f32_16x16x32_bf16 v[60:63], v[176:179], v[208:211], v[60:63]
	v_mfma_f32_16x16x32_bf16 v[56:59], v[192:195], v[208:211], v[56:59]
	v_mfma_f32_16x16x32_bf16 v[44:47], v[176:179], v[216:219], v[44:47]
	v_mfma_f32_16x16x32_bf16 v[40:43], v[192:195], v[216:219], v[40:43]
	v_mfma_f32_16x16x32_bf16 v[36:39], v[176:179], v[224:227], v[36:39]
	v_mfma_f32_16x16x32_bf16 v[32:35], v[192:195], v[224:227], v[32:35]

	s_barrier
	s_add_i32 s6, s6, s15
	v_lshl_add_u64 v[168:169], v[168:169], 0, s[10:11]
	s_mov_b32 m0, s6
	ds_read_b128 v[196:199], v184 offset:49152
	ds_read_b128 v[200:203], v184 offset:50176
	ds_read_b128 v[204:207], v184 offset:51200
	ds_read_b128 v[208:211], v184 offset:52224
	ds_read_b128 v[212:215], v184 offset:53248
	ds_read_b128 v[216:219], v184 offset:54272
	ds_read_b128 v[220:223], v184 offset:55296
	ds_read_b128 v[224:227], v184 offset:56320
	global_load_lds_dwordx4 v[168:169], off
	s_add_i32 m0, s6, 0x2000
	s_add_u32 s88, s88, 0x40080
	v_lshl_add_u64 v[168:169], v[172:173], 0, s[10:11]
	s_addc_u32 s89, s89, 0
	s_add_i32 s6, s7, s15
	global_load_lds_dwordx4 v[168:169], off

	s_mov_b32 m0, s6
	s_nop 0
	global_load_lds_dwordx4 v134, s[88:89]

	s_add_i32 m0, s6, 0x2000
	s_nop 0
	global_load_lds_dwordx4 v138, s[88:89]
	v_lshl_add_u64 v[168:169], v[180:181], 0, s[10:11]
	s_mov_b32 m0, s55
	s_nop 0
	global_load_lds_dwordx4 v[168:169], off
	v_lshl_add_u64 v[168:169], v[228:229], 0, s[10:11]
	s_mov_b32 m0, s56
	s_nop 0
	global_load_lds_dwordx4 v[168:169], off
	s_waitcnt vmcnt(8)
	s_waitcnt lgkmcnt(0)
	s_barrier

	v_mfma_f32_16x16x32_bf16 v[28:31], v[128:131], v[196:199], v[28:31]
	v_mfma_f32_16x16x32_bf16 v[24:27], v[154:157], v[196:199], v[24:27]
	v_mfma_f32_16x16x32_bf16 v[20:23], v[128:131], v[204:207], v[20:23]
	v_mfma_f32_16x16x32_bf16 v[16:19], v[154:157], v[204:207], v[16:19]
	v_mfma_f32_16x16x32_bf16 v[12:15], v[128:131], v[212:215], v[12:15]
	v_mfma_f32_16x16x32_bf16 v[8:11], v[154:157], v[212:215], v[8:11]
	v_mfma_f32_16x16x32_bf16 v[4:7], v[128:131], v[220:223], v[4:7]
	v_mfma_f32_16x16x32_bf16 v[0:3], v[154:157], v[220:223], v[0:3]
	v_mfma_f32_16x16x32_bf16 v[28:31], v[150:153], v[200:203], v[28:31]
	v_mfma_f32_16x16x32_bf16 v[24:27], v[158:161], v[200:203], v[24:27]
	v_mfma_f32_16x16x32_bf16 v[20:23], v[150:153], v[208:211], v[20:23]
	v_mfma_f32_16x16x32_bf16 v[16:19], v[158:161], v[208:211], v[16:19]
	v_mfma_f32_16x16x32_bf16 v[12:15], v[150:153], v[216:219], v[12:15]
	v_mfma_f32_16x16x32_bf16 v[8:11], v[158:161], v[216:219], v[8:11]
	v_mfma_f32_16x16x32_bf16 v[4:7], v[150:153], v[224:227], v[4:7]
	v_mfma_f32_16x16x32_bf16 v[0:3], v[158:161], v[224:227], v[0:3]

	v_mfma_f32_16x16x32_bf16 v[124:127], v[162:165], v[196:199], v[124:127]
	v_mfma_f32_16x16x32_bf16 v[120:123], v[188:191], v[196:199], v[120:123]
	v_mfma_f32_16x16x32_bf16 v[116:119], v[162:165], v[204:207], v[116:119]
	v_mfma_f32_16x16x32_bf16 v[112:115], v[188:191], v[204:207], v[112:115]
	v_mfma_f32_16x16x32_bf16 v[108:111], v[162:165], v[212:215], v[108:111]
	v_mfma_f32_16x16x32_bf16 v[104:107], v[188:191], v[212:215], v[104:107]
	v_mfma_f32_16x16x32_bf16 v[100:103], v[162:165], v[220:223], v[100:103]
	v_mfma_f32_16x16x32_bf16 v[96:99], v[188:191], v[220:223], v[96:99]
	v_mfma_f32_16x16x32_bf16 v[124:127], v[176:179], v[200:203], v[124:127]
	v_mfma_f32_16x16x32_bf16 v[120:123], v[192:195], v[200:203], v[120:123]
	v_mfma_f32_16x16x32_bf16 v[116:119], v[176:179], v[208:211], v[116:119]
	v_mfma_f32_16x16x32_bf16 v[112:115], v[192:195], v[208:211], v[112:115]
	v_mfma_f32_16x16x32_bf16 v[108:111], v[176:179], v[216:219], v[108:111]
	v_mfma_f32_16x16x32_bf16 v[104:107], v[192:195], v[216:219], v[104:107]
	v_mfma_f32_16x16x32_bf16 v[100:103], v[176:179], v[224:227], v[100:103]
	v_mfma_f32_16x16x32_bf16 v[96:99], v[192:195], v[224:227], v[96:99]

	s_barrier
	s_add_i32 s5, s5, 2
	s_add_u32 s84, s84, 0x100
	s_addc_u32 s85, s85, 0
	s_add_u32 s69, s69, 0x100
	s_addc_u32 s71, s71, 0
	s_cmp_gt_u32 s5, 13
	s_cbranch_scc0 .LBB0_881

.LBB0_970:
	s_ashr_i32 s65, s64, 31
	s_lshl_b64 s[78:79], s[64:65], 11
	s_add_u32 s78, s34, s78
	s_addc_u32 s79, s35, s79
	s_and_b64 s[80:81], s[2:3], exec
	s_cselect_b32 s65, s79, s5
	s_cselect_b32 s73, s78, s4
	s_ashr_i32 s67, s66, 31
	s_lshl_b64 s[80:81], s[66:67], 11
	s_add_u32 s80, s40, s80
	s_addc_u32 s81, s41, s81
	s_and_b64 s[82:83], s[2:3], exec
	s_cselect_b32 s67, s81, s7
	s_cselect_b32 s76, s80, s6
	s_add_u32 s4, s4, 0x40080
	s_addc_u32 s5, s5, 0
	s_add_u32 s86, s6, 0x100
	v_mov_b32_e32 v0, 0
	s_addc_u32 s87, s7, 0
	s_mov_b32 s88, -2
	v_mov_b32_e32 v1, 0
	v_mov_b64_e32 v[2:3], 0
	v_mov_b64_e32 v[4:5], 0
	v_mov_b64_e32 v[6:7], 0
	v_mov_b64_e32 v[8:9], 0
	v_mov_b64_e32 v[10:11], 0
	v_mov_b64_e32 v[12:13], 0
	v_mov_b64_e32 v[14:15], 0
	v_mov_b64_e32 v[16:17], 0
	v_mov_b64_e32 v[18:19], 0
	v_mov_b64_e32 v[20:21], 0
	v_mov_b64_e32 v[22:23], 0
	v_mov_b64_e32 v[24:25], 0
	v_mov_b64_e32 v[26:27], 0
	v_mov_b64_e32 v[28:29], 0
	v_mov_b64_e32 v[30:31], 0
	v_mov_b64_e32 v[32:33], 0
	v_mov_b64_e32 v[34:35], 0
	v_mov_b64_e32 v[36:37], 0
	v_mov_b64_e32 v[38:39], 0
	v_mov_b64_e32 v[40:41], 0
	v_mov_b64_e32 v[42:43], 0
	v_mov_b64_e32 v[44:45], 0
	v_mov_b64_e32 v[46:47], 0
	v_mov_b64_e32 v[48:49], 0
	v_mov_b64_e32 v[50:51], 0
	v_mov_b64_e32 v[52:53], 0
	v_mov_b64_e32 v[54:55], 0
	v_mov_b64_e32 v[56:57], 0
	v_mov_b64_e32 v[58:59], 0
	v_mov_b64_e32 v[60:61], 0
	v_mov_b64_e32 v[62:63], 0
	v_mov_b64_e32 v[64:65], 0
	v_mov_b64_e32 v[66:67], 0
	v_mov_b64_e32 v[68:69], 0
	v_mov_b64_e32 v[70:71], 0
	v_mov_b64_e32 v[72:73], 0
	v_mov_b64_e32 v[74:75], 0
	v_mov_b64_e32 v[76:77], 0
	v_mov_b64_e32 v[78:79], 0
	v_mov_b64_e32 v[80:81], 0
	v_mov_b64_e32 v[82:83], 0
	v_mov_b64_e32 v[84:85], 0
	v_mov_b64_e32 v[86:87], 0
	v_mov_b64_e32 v[88:89], 0
	v_mov_b64_e32 v[90:91], 0
	v_mov_b64_e32 v[92:93], 0
	v_mov_b64_e32 v[94:95], 0
	v_mov_b64_e32 v[96:97], 0
	v_mov_b64_e32 v[98:99], 0
	v_mov_b64_e32 v[100:101], 0
	v_mov_b64_e32 v[102:103], 0
	v_mov_b64_e32 v[104:105], 0
	v_mov_b64_e32 v[106:107], 0
	v_mov_b64_e32 v[108:109], 0
	v_mov_b64_e32 v[110:111], 0
	v_mov_b64_e32 v[112:113], 0
	v_mov_b64_e32 v[114:115], 0
	v_mov_b64_e32 v[116:117], 0
	v_mov_b64_e32 v[118:119], 0
	v_mov_b64_e32 v[124:125], 0
	v_mov_b64_e32 v[126:127], 0
	v_mov_b64_e32 v[132:133], 0
	v_mov_b64_e32 v[134:135], 0
	s_nop 0
	s_nop 0
	s_nop 0
	s_nop 0
	s_nop 0
	s_nop 0
	s_nop 0
	s_nop 0
.LBB0_971:
	ds_read_b128 v[120:123], v237
	ds_read_b128 v[128:131], v237 offset:1024
	ds_read_b128 v[136:139], v237 offset:2048
	ds_read_b128 v[140:143], v237 offset:3072
	ds_read_b128 v[144:147], v238
	ds_read_b128 v[148:151], v238 offset:1024
	ds_read_b128 v[152:155], v238 offset:2048
	ds_read_b128 v[156:159], v238 offset:3072
	s_add_u32 s6, s4, 0xfffc0080
	s_addc_u32 s7, s5, -1
	s_cmp_eq_u32 s88, 12
	s_cselect_b32 s83, s65, s7
	s_cselect_b32 s82, s73, s6
	s_cselect_b32 s7, s67, s87
	s_cselect_b32 s6, s76, s86

	s_add_i32 m0, s53, 0xc000
	ds_read_b128 v[160:163], v239
	ds_read_b128 v[164:167], v239 offset:1024
	ds_read_b128 v[168:171], v239 offset:2048
	ds_read_b128 v[172:175], v239 offset:3072
	ds_read_b128 v[176:179], v239 offset:4096
	ds_read_b128 v[198:201], v239 offset:5120
	ds_read_b128 v[202:205], v239 offset:6144
	ds_read_b128 v[206:209], v239 offset:7168
	global_load_lds_dwordx4 v190, s[4:5]

	s_add_i32 m0, s53, 0xe000
	s_nop 0
	global_load_lds_dwordx4 v192, s[4:5]
	s_waitcnt vmcnt(8)
	s_waitcnt lgkmcnt(0)
	s_barrier

	v_mfma_f32_16x16x32_bf16 v[132:135], v[120:123], v[160:163], v[132:135]
	v_mfma_f32_16x16x32_bf16 v[124:127], v[136:139], v[160:163], v[124:127]
	v_mfma_f32_16x16x32_bf16 v[116:119], v[120:123], v[168:171], v[116:119]
	v_mfma_f32_16x16x32_bf16 v[112:115], v[136:139], v[168:171], v[112:115]
	v_mfma_f32_16x16x32_bf16 v[108:111], v[120:123], v[176:179], v[108:111]
	v_mfma_f32_16x16x32_bf16 v[104:107], v[136:139], v[176:179], v[104:107]
	v_mfma_f32_16x16x32_bf16 v[100:103], v[120:123], v[202:205], v[100:103]
	v_mfma_f32_16x16x32_bf16 v[96:99], v[136:139], v[202:205], v[96:99]
	v_mfma_f32_16x16x32_bf16 v[132:135], v[128:131], v[164:167], v[132:135]
	v_mfma_f32_16x16x32_bf16 v[124:127], v[140:143], v[164:167], v[124:127]
	v_mfma_f32_16x16x32_bf16 v[116:119], v[128:131], v[172:175], v[116:119]
	v_mfma_f32_16x16x32_bf16 v[112:115], v[140:143], v[172:175], v[112:115]
	v_mfma_f32_16x16x32_bf16 v[108:111], v[128:131], v[198:201], v[108:111]
	v_mfma_f32_16x16x32_bf16 v[104:107], v[140:143], v[198:201], v[104:107]
	v_mfma_f32_16x16x32_bf16 v[100:103], v[128:131], v[206:209], v[100:103]
	v_mfma_f32_16x16x32_bf16 v[96:99], v[140:143], v[206:209], v[96:99]

	v_mfma_f32_16x16x32_bf16 v[92:95], v[144:147], v[160:163], v[92:95]
	v_mfma_f32_16x16x32_bf16 v[88:91], v[152:155], v[160:163], v[88:91]
	v_mfma_f32_16x16x32_bf16 v[84:87], v[144:147], v[168:171], v[84:87]
	v_mfma_f32_16x16x32_bf16 v[80:83], v[152:155], v[168:171], v[80:83]
	v_mfma_f32_16x16x32_bf16 v[76:79], v[144:147], v[176:179], v[76:79]
	v_mfma_f32_16x16x32_bf16 v[72:75], v[152:155], v[176:179], v[72:75]
	v_mfma_f32_16x16x32_bf16 v[68:71], v[144:147], v[202:205], v[68:71]
	v_mfma_f32_16x16x32_bf16 v[64:67], v[152:155], v[202:205], v[64:67]
	v_mfma_f32_16x16x32_bf16 v[92:95], v[148:151], v[164:167], v[92:95]
	v_mfma_f32_16x16x32_bf16 v[88:91], v[156:159], v[164:167], v[88:91]
	v_mfma_f32_16x16x32_bf16 v[84:87], v[148:151], v[172:175], v[84:87]
	v_mfma_f32_16x16x32_bf16 v[80:83], v[156:159], v[172:175], v[80:83]
	v_mfma_f32_16x16x32_bf16 v[76:79], v[148:151], v[198:201], v[76:79]
	v_mfma_f32_16x16x32_bf16 v[72:75], v[156:159], v[198:201], v[72:75]
	v_mfma_f32_16x16x32_bf16 v[68:71], v[148:151], v[206:209], v[68:71]
	v_mfma_f32_16x16x32_bf16 v[64:67], v[156:159], v[206:209], v[64:67]

	s_barrier
	s_add_i32 s89, s68, s52
	v_lshl_add_u64 v[210:211], s[6:7], 0, v[182:183]
	s_mov_b32 m0, s89
	ds_read_b128 v[160:163], v239 offset:16384
	ds_read_b128 v[164:167], v239 offset:17408
	ds_read_b128 v[168:171], v239 offset:18432
	ds_read_b128 v[172:175], v239 offset:19456
	ds_read_b128 v[176:179], v239 offset:20480
	ds_read_b128 v[198:201], v239 offset:21504
	ds_read_b128 v[202:205], v239 offset:22528
	ds_read_b128 v[206:209], v239 offset:23552
	global_load_lds_dwordx4 v[210:211], off
	s_add_i32 m0, s89, 0x2000
	s_add_u32 s90, s6, 0x40000
	v_lshl_add_u64 v[212:213], s[6:7], 0, v[186:187]
	s_addc_u32 s91, s7, 0
	s_add_i32 s89, s69, s52
	global_load_lds_dwordx4 v[212:213], off

	s_mov_b32 m0, s89
	v_lshl_add_u64 v[216:217], s[82:83], 0, v[184:185]
	global_load_lds_dwordx4 v182, s[90:91]

	s_add_i32 m0, s89, 0x2000
	s_nop 0
	global_load_lds_dwordx4 v186, s[90:91]
	v_lshl_add_u64 v[214:215], s[82:83], 0, v[180:181]
	s_mov_b32 m0, s53
	s_nop 0
	global_load_lds_dwordx4 v[214:215], off
	s_mov_b32 m0, s54
	s_nop 0
	global_load_lds_dwordx4 v[216:217], off
	s_waitcnt vmcnt(8)
	s_waitcnt lgkmcnt(0)
	s_barrier

	v_mfma_f32_16x16x32_bf16 v[60:63], v[120:123], v[160:163], v[60:63]
	v_mfma_f32_16x16x32_bf16 v[56:59], v[136:139], v[160:163], v[56:59]
	v_mfma_f32_16x16x32_bf16 v[52:55], v[120:123], v[168:171], v[52:55]
	v_mfma_f32_16x16x32_bf16 v[48:51], v[136:139], v[168:171], v[48:51]
	v_mfma_f32_16x16x32_bf16 v[44:47], v[120:123], v[176:179], v[44:47]
	v_mfma_f32_16x16x32_bf16 v[40:43], v[136:139], v[176:179], v[40:43]
	v_mfma_f32_16x16x32_bf16 v[36:39], v[120:123], v[202:205], v[36:39]
	v_mfma_f32_16x16x32_bf16 v[32:35], v[136:139], v[202:205], v[32:35]
	v_mfma_f32_16x16x32_bf16 v[60:63], v[128:131], v[164:167], v[60:63]
	v_mfma_f32_16x16x32_bf16 v[56:59], v[140:143], v[164:167], v[56:59]
	v_mfma_f32_16x16x32_bf16 v[52:55], v[128:131], v[172:175], v[52:55]
	v_mfma_f32_16x16x32_bf16 v[48:51], v[140:143], v[172:175], v[48:51]
	v_mfma_f32_16x16x32_bf16 v[44:47], v[128:131], v[198:201], v[44:47]
	v_mfma_f32_16x16x32_bf16 v[40:43], v[140:143], v[198:201], v[40:43]
	v_mfma_f32_16x16x32_bf16 v[36:39], v[128:131], v[206:209], v[36:39]
	v_mfma_f32_16x16x32_bf16 v[32:35], v[140:143], v[206:209], v[32:35]

	v_mfma_f32_16x16x32_bf16 v[28:31], v[144:147], v[160:163], v[28:31]
	v_mfma_f32_16x16x32_bf16 v[24:27], v[152:155], v[160:163], v[24:27]
	v_mfma_f32_16x16x32_bf16 v[20:23], v[144:147], v[168:171], v[20:23]
	v_mfma_f32_16x16x32_bf16 v[16:19], v[152:155], v[168:171], v[16:19]
	v_mfma_f32_16x16x32_bf16 v[12:15], v[144:147], v[176:179], v[12:15]
	v_mfma_f32_16x16x32_bf16 v[8:11], v[152:155], v[176:179], v[8:11]
	v_mfma_f32_16x16x32_bf16 v[4:7], v[144:147], v[202:205], v[4:7]
	v_mfma_f32_16x16x32_bf16 v[0:3], v[152:155], v[202:205], v[0:3]
	v_mfma_f32_16x16x32_bf16 v[28:31], v[148:151], v[164:167], v[28:31]
	v_mfma_f32_16x16x32_bf16 v[24:27], v[156:159], v[164:167], v[24:27]
	v_mfma_f32_16x16x32_bf16 v[20:23], v[148:151], v[172:175], v[20:23]
	v_mfma_f32_16x16x32_bf16 v[16:19], v[156:159], v[172:175], v[16:19]
	v_mfma_f32_16x16x32_bf16 v[12:15], v[148:151], v[198:201], v[12:15]
	v_mfma_f32_16x16x32_bf16 v[8:11], v[156:159], v[198:201], v[8:11]
	v_mfma_f32_16x16x32_bf16 v[4:7], v[148:151], v[206:209], v[4:7]
	v_mfma_f32_16x16x32_bf16 v[0:3], v[156:159], v[206:209], v[0:3]

	s_barrier
	s_add_i32 s89, 0, 0x18000
	s_add_i32 s90, 0, 0x1c000
	v_add_u32_e32 v140, s89, v235
	v_add_u32_e32 v156, s90, v235
	ds_read_b128 v[120:123], v140
	ds_read_b128 v[128:131], v140 offset:1024
	ds_read_b128 v[136:139], v140 offset:2048
	ds_read_b128 v[140:143], v140 offset:3072
	ds_read_b128 v[144:147], v156
	ds_read_b128 v[148:151], v156 offset:1024
	ds_read_b128 v[152:155], v156 offset:2048
	ds_read_b128 v[156:159], v156 offset:3072
	s_add_u32 s82, s82, 0x40000
	s_addc_u32 s83, s83, 0
	s_mov_b32 m0, s55

	ds_read_b128 v[160:163], v239 offset:32768
	ds_read_b128 v[164:167], v239 offset:33792
	ds_read_b128 v[168:171], v239 offset:34816
	ds_read_b128 v[172:175], v239 offset:35840
	ds_read_b128 v[176:179], v239 offset:36864
	ds_read_b128 v[198:201], v239 offset:37888
	ds_read_b128 v[202:205], v239 offset:38912
	ds_read_b128 v[206:209], v239 offset:39936
	global_load_lds_dwordx4 v180, s[82:83]

	s_mov_b32 m0, s56
	s_nop 0
	global_load_lds_dwordx4 v184, s[82:83]
	s_waitcnt vmcnt(8)
	s_waitcnt lgkmcnt(0)
	s_barrier

	v_mfma_f32_16x16x32_bf16 v[132:135], v[120:123], v[160:163], v[132:135]
	v_mfma_f32_16x16x32_bf16 v[124:127], v[136:139], v[160:163], v[124:127]
	v_mfma_f32_16x16x32_bf16 v[116:119], v[120:123], v[168:171], v[116:119]
	v_mfma_f32_16x16x32_bf16 v[112:115], v[136:139], v[168:171], v[112:115]
	v_mfma_f32_16x16x32_bf16 v[108:111], v[120:123], v[176:179], v[108:111]
	v_mfma_f32_16x16x32_bf16 v[104:107], v[136:139], v[176:179], v[104:107]
	v_mfma_f32_16x16x32_bf16 v[100:103], v[120:123], v[202:205], v[100:103]
	v_mfma_f32_16x16x32_bf16 v[96:99], v[136:139], v[202:205], v[96:99]
	v_mfma_f32_16x16x32_bf16 v[132:135], v[128:131], v[164:167], v[132:135]
	v_mfma_f32_16x16x32_bf16 v[124:127], v[140:143], v[164:167], v[124:127]
	v_mfma_f32_16x16x32_bf16 v[116:119], v[128:131], v[172:175], v[116:119]
	v_mfma_f32_16x16x32_bf16 v[112:115], v[140:143], v[172:175], v[112:115]
	v_mfma_f32_16x16x32_bf16 v[108:111], v[128:131], v[198:201], v[108:111]
	v_mfma_f32_16x16x32_bf16 v[104:107], v[140:143], v[198:201], v[104:107]
	v_mfma_f32_16x16x32_bf16 v[100:103], v[128:131], v[206:209], v[100:103]
	v_mfma_f32_16x16x32_bf16 v[96:99], v[140:143], v[206:209], v[96:99]

	v_mfma_f32_16x16x32_bf16 v[92:95], v[144:147], v[160:163], v[92:95]
	v_mfma_f32_16x16x32_bf16 v[88:91], v[152:155], v[160:163], v[88:91]
	v_mfma_f32_16x16x32_bf16 v[84:87], v[144:147], v[168:171], v[84:87]
	v_mfma_f32_16x16x32_bf16 v[80:83], v[152:155], v[168:171], v[80:83]
	v_mfma_f32_16x16x32_bf16 v[76:79], v[144:147], v[176:179], v[76:79]
	v_mfma_f32_16x16x32_bf16 v[72:75], v[152:155], v[176:179], v[72:75]
	v_mfma_f32_16x16x32_bf16 v[68:71], v[144:147], v[202:205], v[68:71]
	v_mfma_f32_16x16x32_bf16 v[64:67], v[152:155], v[202:205], v[64:67]
	v_mfma_f32_16x16x32_bf16 v[92:95], v[148:151], v[164:167], v[92:95]
	v_mfma_f32_16x16x32_bf16 v[88:91], v[156:159], v[164:167], v[88:91]
	v_mfma_f32_16x16x32_bf16 v[84:87], v[148:151], v[172:175], v[84:87]
	v_mfma_f32_16x16x32_bf16 v[80:83], v[156:159], v[172:175], v[80:83]
	v_mfma_f32_16x16x32_bf16 v[76:79], v[148:151], v[198:201], v[76:79]
	v_mfma_f32_16x16x32_bf16 v[72:75], v[156:159], v[198:201], v[72:75]
	v_mfma_f32_16x16x32_bf16 v[68:71], v[148:151], v[206:209], v[68:71]
	v_mfma_f32_16x16x32_bf16 v[64:67], v[156:159], v[206:209], v[64:67]

	s_barrier
	s_add_i32 s82, s89, s52
	v_lshl_add_u64 v[210:211], v[210:211], 0, s[18:19]
	s_mov_b32 m0, s82
	ds_read_b128 v[160:163], v239 offset:49152
	ds_read_b128 v[164:167], v239 offset:50176
	ds_read_b128 v[168:171], v239 offset:51200
	ds_read_b128 v[172:175], v239 offset:52224
	ds_read_b128 v[176:179], v239 offset:53248
	ds_read_b128 v[198:201], v239 offset:54272
	ds_read_b128 v[202:205], v239 offset:55296
	ds_read_b128 v[206:209], v239 offset:56320
	global_load_lds_dwordx4 v[210:211], off
	s_add_i32 m0, s82, 0x2000
	s_add_u32 s6, s6, 0x40080
	v_lshl_add_u64 v[210:211], v[212:213], 0, s[18:19]
	s_addc_u32 s7, s7, 0
	s_add_i32 s82, s90, s52
	global_load_lds_dwordx4 v[210:211], off

	s_mov_b32 m0, s82
	s_nop 0
	global_load_lds_dwordx4 v182, s[6:7]

	s_add_i32 m0, s82, 0x2000
	s_nop 0
	global_load_lds_dwordx4 v186, s[6:7]
	v_lshl_add_u64 v[210:211], v[214:215], 0, s[18:19]
	s_mov_b32 m0, s58
	s_nop 0
	global_load_lds_dwordx4 v[210:211], off
	v_lshl_add_u64 v[210:211], v[216:217], 0, s[18:19]
	s_mov_b32 m0, s59
	s_nop 0
	global_load_lds_dwordx4 v[210:211], off
	s_waitcnt vmcnt(8)
	s_waitcnt lgkmcnt(0)
	s_barrier

	v_mfma_f32_16x16x32_bf16 v[60:63], v[120:123], v[160:163], v[60:63]
	v_mfma_f32_16x16x32_bf16 v[56:59], v[136:139], v[160:163], v[56:59]
	v_mfma_f32_16x16x32_bf16 v[52:55], v[120:123], v[168:171], v[52:55]
	v_mfma_f32_16x16x32_bf16 v[48:51], v[136:139], v[168:171], v[48:51]
	v_mfma_f32_16x16x32_bf16 v[44:47], v[120:123], v[176:179], v[44:47]
	v_mfma_f32_16x16x32_bf16 v[40:43], v[136:139], v[176:179], v[40:43]
	v_mfma_f32_16x16x32_bf16 v[36:39], v[120:123], v[202:205], v[36:39]
	v_mfma_f32_16x16x32_bf16 v[32:35], v[136:139], v[202:205], v[32:35]
	v_mfma_f32_16x16x32_bf16 v[60:63], v[128:131], v[164:167], v[60:63]
	v_mfma_f32_16x16x32_bf16 v[56:59], v[140:143], v[164:167], v[56:59]
	v_mfma_f32_16x16x32_bf16 v[52:55], v[128:131], v[172:175], v[52:55]
	v_mfma_f32_16x16x32_bf16 v[48:51], v[140:143], v[172:175], v[48:51]
	v_mfma_f32_16x16x32_bf16 v[44:47], v[128:131], v[198:201], v[44:47]
	v_mfma_f32_16x16x32_bf16 v[40:43], v[140:143], v[198:201], v[40:43]
	v_mfma_f32_16x16x32_bf16 v[36:39], v[128:131], v[206:209], v[36:39]
	v_mfma_f32_16x16x32_bf16 v[32:35], v[140:143], v[206:209], v[32:35]

	v_mfma_f32_16x16x32_bf16 v[28:31], v[144:147], v[160:163], v[28:31]
	v_mfma_f32_16x16x32_bf16 v[24:27], v[152:155], v[160:163], v[24:27]
	v_mfma_f32_16x16x32_bf16 v[20:23], v[144:147], v[168:171], v[20:23]
	v_mfma_f32_16x16x32_bf16 v[16:19], v[152:155], v[168:171], v[16:19]
	v_mfma_f32_16x16x32_bf16 v[12:15], v[144:147], v[176:179], v[12:15]
	v_mfma_f32_16x16x32_bf16 v[8:11], v[152:155], v[176:179], v[8:11]
	v_mfma_f32_16x16x32_bf16 v[4:7], v[144:147], v[202:205], v[4:7]
	v_mfma_f32_16x16x32_bf16 v[0:3], v[152:155], v[202:205], v[0:3]
	v_mfma_f32_16x16x32_bf16 v[28:31], v[148:151], v[164:167], v[28:31]
	v_mfma_f32_16x16x32_bf16 v[24:27], v[156:159], v[164:167], v[24:27]
	v_mfma_f32_16x16x32_bf16 v[20:23], v[148:151], v[172:175], v[20:23]
	v_mfma_f32_16x16x32_bf16 v[16:19], v[156:159], v[172:175], v[16:19]
	v_mfma_f32_16x16x32_bf16 v[12:15], v[148:151], v[198:201], v[12:15]
	v_mfma_f32_16x16x32_bf16 v[8:11], v[156:159], v[198:201], v[8:11]
	v_mfma_f32_16x16x32_bf16 v[4:7], v[148:151], v[206:209], v[4:7]
	v_mfma_f32_16x16x32_bf16 v[0:3], v[156:159], v[206:209], v[0:3]

	s_barrier
	s_add_i32 s88, s88, 2
	s_add_u32 s4, s4, 0x100
	s_addc_u32 s5, s5, 0
	s_add_u32 s86, s86, 0x100
	s_addc_u32 s87, s87, 0
	s_cmp_gt_u32 s88, 13
	s_cbranch_scc0 .LBB0_971
	s_and_b64 vcc, exec, s[36:37]
	s_cbranch_vccz .LBB0_974
	s_barrier

.LBB0_1080:
	ds_read_b128 v[128:131], v187
	ds_read_b128 v[132:135], v187 offset:1024
	ds_read_b128 v[136:139], v187 offset:2048
	ds_read_b128 v[140:143], v187 offset:3072
	ds_read_b128 v[144:147], v188
	ds_read_b128 v[148:151], v188 offset:1024
	ds_read_b128 v[168:171], v188 offset:2048
	ds_read_b128 v[172:175], v188 offset:3072
	s_add_u32 s38, s36, 0x100
	s_addc_u32 s39, s37, 0
	s_cmp_eq_u32 s77, 40
	s_cselect_b32 s61, s5, s39
	s_cselect_b32 s60, s4, s38
	s_cselect_b32 s45, s7, s76
	s_cselect_b32 s44, s6, s73
	v_lshl_add_u64 v[216:217], s[36:37], 0, v[160:161]
	s_add_i32 m0, s54, 0xc000
	ds_read_b128 v[176:179], v189
	ds_read_b128 v[180:183], v189 offset:1024
	ds_read_b128 v[192:195], v189 offset:2048
	ds_read_b128 v[196:199], v189 offset:3072
	ds_read_b128 v[200:203], v189 offset:4096
	ds_read_b128 v[204:207], v189 offset:5120
	ds_read_b128 v[208:211], v189 offset:6144
	ds_read_b128 v[212:215], v189 offset:7168
	global_load_lds_dwordx4 v[216:217], off
	v_lshl_add_u64 v[216:217], s[36:37], 0, v[162:163]
	s_add_i32 m0, s54, 0xe000
	s_nop 0
	global_load_lds_dwordx4 v[216:217], off
	s_waitcnt vmcnt(8)
	s_waitcnt lgkmcnt(0)
	s_barrier

	v_mfma_f32_16x16x32_bf16 v[124:127], v[128:131], v[176:179], v[124:127]
	v_mfma_f32_16x16x32_bf16 v[120:123], v[136:139], v[176:179], v[120:123]
	v_mfma_f32_16x16x32_bf16 v[108:111], v[128:131], v[192:195], v[108:111]
	v_mfma_f32_16x16x32_bf16 v[104:107], v[136:139], v[192:195], v[104:107]
	v_mfma_f32_16x16x32_bf16 v[92:95], v[128:131], v[200:203], v[92:95]
	v_mfma_f32_16x16x32_bf16 v[88:91], v[136:139], v[200:203], v[88:91]
	v_mfma_f32_16x16x32_bf16 v[76:79], v[128:131], v[208:211], v[76:79]
	v_mfma_f32_16x16x32_bf16 v[72:75], v[136:139], v[208:211], v[72:75]
	v_mfma_f32_16x16x32_bf16 v[124:127], v[132:135], v[180:183], v[124:127]
	v_mfma_f32_16x16x32_bf16 v[120:123], v[140:143], v[180:183], v[120:123]
	v_mfma_f32_16x16x32_bf16 v[108:111], v[132:135], v[196:199], v[108:111]
	v_mfma_f32_16x16x32_bf16 v[104:107], v[140:143], v[196:199], v[104:107]
	v_mfma_f32_16x16x32_bf16 v[92:95], v[132:135], v[204:207], v[92:95]
	v_mfma_f32_16x16x32_bf16 v[88:91], v[140:143], v[204:207], v[88:91]
	v_mfma_f32_16x16x32_bf16 v[76:79], v[132:135], v[212:215], v[76:79]
	v_mfma_f32_16x16x32_bf16 v[72:75], v[140:143], v[212:215], v[72:75]

	v_mfma_f32_16x16x32_bf16 v[116:119], v[144:147], v[176:179], v[116:119]
	v_mfma_f32_16x16x32_bf16 v[112:115], v[168:171], v[176:179], v[112:115]
	v_mfma_f32_16x16x32_bf16 v[100:103], v[144:147], v[192:195], v[100:103]
	v_mfma_f32_16x16x32_bf16 v[96:99], v[168:171], v[192:195], v[96:99]
	v_mfma_f32_16x16x32_bf16 v[84:87], v[144:147], v[200:203], v[84:87]
	v_mfma_f32_16x16x32_bf16 v[80:83], v[168:171], v[200:203], v[80:83]
	v_mfma_f32_16x16x32_bf16 v[68:71], v[144:147], v[208:211], v[68:71]
	v_mfma_f32_16x16x32_bf16 v[64:67], v[168:171], v[208:211], v[64:67]
	v_mfma_f32_16x16x32_bf16 v[116:119], v[148:151], v[180:183], v[116:119]
	v_mfma_f32_16x16x32_bf16 v[112:115], v[172:175], v[180:183], v[112:115]
	v_mfma_f32_16x16x32_bf16 v[100:103], v[148:151], v[196:199], v[100:103]
	v_mfma_f32_16x16x32_bf16 v[96:99], v[172:175], v[196:199], v[96:99]
	v_mfma_f32_16x16x32_bf16 v[84:87], v[148:151], v[204:207], v[84:87]
	v_mfma_f32_16x16x32_bf16 v[80:83], v[172:175], v[204:207], v[80:83]
	v_mfma_f32_16x16x32_bf16 v[68:71], v[148:151], v[212:215], v[68:71]
	v_mfma_f32_16x16x32_bf16 v[64:67], v[172:175], v[212:215], v[64:67]

	s_barrier
	s_add_i32 s36, s65, s53
	v_lshl_add_u64 v[216:217], s[44:45], 0, v[154:155]
	s_mov_b32 m0, s36
	ds_read_b128 v[176:179], v189 offset:16384
	ds_read_b128 v[180:183], v189 offset:17408
	ds_read_b128 v[192:195], v189 offset:18432
	ds_read_b128 v[196:199], v189 offset:19456
	ds_read_b128 v[200:203], v189 offset:20480
	ds_read_b128 v[204:207], v189 offset:21504
	ds_read_b128 v[208:211], v189 offset:22528
	ds_read_b128 v[212:215], v189 offset:23552
	global_load_lds_dwordx4 v[216:217], off
	s_add_i32 m0, s36, 0x2000
	s_add_u32 s36, s44, 0xb0000
	v_lshl_add_u64 v[218:219], s[44:45], 0, v[158:159]
	s_addc_u32 s37, s45, 0
	s_add_i32 s78, s66, s53
	global_load_lds_dwordx4 v[218:219], off

	s_mov_b32 m0, s78
	v_lshl_add_u64 v[222:223], s[60:61], 0, v[156:157]
	global_load_lds_dwordx4 v154, s[36:37]

	s_add_i32 m0, s78, 0x2000
	s_nop 0
	global_load_lds_dwordx4 v158, s[36:37]
	v_lshl_add_u64 v[220:221], s[60:61], 0, v[152:153]
	s_mov_b32 m0, s54
	s_nop 0
	global_load_lds_dwordx4 v[220:221], off
	s_mov_b32 m0, s55
	s_nop 0
	global_load_lds_dwordx4 v[222:223], off
	s_waitcnt vmcnt(8)
	s_waitcnt lgkmcnt(0)
	s_barrier

	v_mfma_f32_16x16x32_bf16 v[60:63], v[128:131], v[176:179], v[60:63]
	v_mfma_f32_16x16x32_bf16 v[56:59], v[136:139], v[176:179], v[56:59]
	v_mfma_f32_16x16x32_bf16 v[44:47], v[128:131], v[192:195], v[44:47]
	v_mfma_f32_16x16x32_bf16 v[40:43], v[136:139], v[192:195], v[40:43]
	v_mfma_f32_16x16x32_bf16 v[28:31], v[128:131], v[200:203], v[28:31]
	v_mfma_f32_16x16x32_bf16 v[24:27], v[136:139], v[200:203], v[24:27]
	v_mfma_f32_16x16x32_bf16 v[12:15], v[128:131], v[208:211], v[12:15]
	v_mfma_f32_16x16x32_bf16 v[8:11], v[136:139], v[208:211], v[8:11]
	v_mfma_f32_16x16x32_bf16 v[60:63], v[132:135], v[180:183], v[60:63]
	v_mfma_f32_16x16x32_bf16 v[56:59], v[140:143], v[180:183], v[56:59]
	v_mfma_f32_16x16x32_bf16 v[44:47], v[132:135], v[196:199], v[44:47]
	v_mfma_f32_16x16x32_bf16 v[40:43], v[140:143], v[196:199], v[40:43]
	v_mfma_f32_16x16x32_bf16 v[28:31], v[132:135], v[204:207], v[28:31]
	v_mfma_f32_16x16x32_bf16 v[24:27], v[140:143], v[204:207], v[24:27]
	v_mfma_f32_16x16x32_bf16 v[12:15], v[132:135], v[212:215], v[12:15]
	v_mfma_f32_16x16x32_bf16 v[8:11], v[140:143], v[212:215], v[8:11]

	v_mfma_f32_16x16x32_bf16 v[52:55], v[144:147], v[176:179], v[52:55]
	v_mfma_f32_16x16x32_bf16 v[48:51], v[168:171], v[176:179], v[48:51]
	v_mfma_f32_16x16x32_bf16 v[36:39], v[144:147], v[192:195], v[36:39]
	v_mfma_f32_16x16x32_bf16 v[32:35], v[168:171], v[192:195], v[32:35]
	v_mfma_f32_16x16x32_bf16 v[20:23], v[144:147], v[200:203], v[20:23]
	v_mfma_f32_16x16x32_bf16 v[16:19], v[168:171], v[200:203], v[16:19]
	v_mfma_f32_16x16x32_bf16 v[4:7], v[144:147], v[208:211], v[4:7]
	v_mfma_f32_16x16x32_bf16 v[0:3], v[168:171], v[208:211], v[0:3]
	v_mfma_f32_16x16x32_bf16 v[52:55], v[148:151], v[180:183], v[52:55]
	v_mfma_f32_16x16x32_bf16 v[48:51], v[172:175], v[180:183], v[48:51]
	v_mfma_f32_16x16x32_bf16 v[36:39], v[148:151], v[196:199], v[36:39]
	v_mfma_f32_16x16x32_bf16 v[32:35], v[172:175], v[196:199], v[32:35]
	v_mfma_f32_16x16x32_bf16 v[20:23], v[148:151], v[204:207], v[20:23]
	v_mfma_f32_16x16x32_bf16 v[16:19], v[172:175], v[204:207], v[16:19]
	v_mfma_f32_16x16x32_bf16 v[4:7], v[148:151], v[212:215], v[4:7]
	v_mfma_f32_16x16x32_bf16 v[0:3], v[172:175], v[212:215], v[0:3]

	s_barrier
	s_add_i32 s78, 0, 0x18000
	s_add_i32 s79, 0, 0x1c000
	v_add_u32_e32 v140, s78, v185
	v_add_u32_e32 v172, s79, v185
	ds_read_b128 v[128:131], v140
	ds_read_b128 v[132:135], v140 offset:1024
	ds_read_b128 v[136:139], v140 offset:2048
	ds_read_b128 v[140:143], v140 offset:3072
	ds_read_b128 v[144:147], v172
	ds_read_b128 v[148:151], v172 offset:1024
	ds_read_b128 v[168:171], v172 offset:2048
	ds_read_b128 v[172:175], v172 offset:3072
	s_add_u32 s36, s60, 0xb0000
	s_addc_u32 s37, s61, 0
	s_mov_b32 m0, s56

	ds_read_b128 v[176:179], v189 offset:32768
	ds_read_b128 v[180:183], v189 offset:33792
	ds_read_b128 v[192:195], v189 offset:34816
	ds_read_b128 v[196:199], v189 offset:35840
	ds_read_b128 v[200:203], v189 offset:36864
	ds_read_b128 v[204:207], v189 offset:37888
	ds_read_b128 v[208:211], v189 offset:38912
	ds_read_b128 v[212:215], v189 offset:39936
	global_load_lds_dwordx4 v152, s[36:37]

	s_mov_b32 m0, s57
	s_nop 0
	global_load_lds_dwordx4 v156, s[36:37]
	s_waitcnt vmcnt(8)
	s_waitcnt lgkmcnt(0)
	s_barrier

	v_mfma_f32_16x16x32_bf16 v[124:127], v[128:131], v[176:179], v[124:127]
	v_mfma_f32_16x16x32_bf16 v[120:123], v[136:139], v[176:179], v[120:123]
	v_mfma_f32_16x16x32_bf16 v[108:111], v[128:131], v[192:195], v[108:111]
	v_mfma_f32_16x16x32_bf16 v[104:107], v[136:139], v[192:195], v[104:107]
	v_mfma_f32_16x16x32_bf16 v[92:95], v[128:131], v[200:203], v[92:95]
	v_mfma_f32_16x16x32_bf16 v[88:91], v[136:139], v[200:203], v[88:91]
	v_mfma_f32_16x16x32_bf16 v[76:79], v[128:131], v[208:211], v[76:79]
	v_mfma_f32_16x16x32_bf16 v[72:75], v[136:139], v[208:211], v[72:75]
	v_mfma_f32_16x16x32_bf16 v[124:127], v[132:135], v[180:183], v[124:127]
	v_mfma_f32_16x16x32_bf16 v[120:123], v[140:143], v[180:183], v[120:123]
	v_mfma_f32_16x16x32_bf16 v[108:111], v[132:135], v[196:199], v[108:111]
	v_mfma_f32_16x16x32_bf16 v[104:107], v[140:143], v[196:199], v[104:107]
	v_mfma_f32_16x16x32_bf16 v[92:95], v[132:135], v[204:207], v[92:95]
	v_mfma_f32_16x16x32_bf16 v[88:91], v[140:143], v[204:207], v[88:91]
	v_mfma_f32_16x16x32_bf16 v[76:79], v[132:135], v[212:215], v[76:79]
	v_mfma_f32_16x16x32_bf16 v[72:75], v[140:143], v[212:215], v[72:75]

	v_mfma_f32_16x16x32_bf16 v[116:119], v[144:147], v[176:179], v[116:119]
	v_mfma_f32_16x16x32_bf16 v[112:115], v[168:171], v[176:179], v[112:115]
	v_mfma_f32_16x16x32_bf16 v[100:103], v[144:147], v[192:195], v[100:103]
	v_mfma_f32_16x16x32_bf16 v[96:99], v[168:171], v[192:195], v[96:99]
	v_mfma_f32_16x16x32_bf16 v[84:87], v[144:147], v[200:203], v[84:87]
	v_mfma_f32_16x16x32_bf16 v[80:83], v[168:171], v[200:203], v[80:83]
	v_mfma_f32_16x16x32_bf16 v[68:71], v[144:147], v[208:211], v[68:71]
	v_mfma_f32_16x16x32_bf16 v[64:67], v[168:171], v[208:211], v[64:67]
	v_mfma_f32_16x16x32_bf16 v[116:119], v[148:151], v[180:183], v[116:119]
	v_mfma_f32_16x16x32_bf16 v[112:115], v[172:175], v[180:183], v[112:115]
	v_mfma_f32_16x16x32_bf16 v[100:103], v[148:151], v[196:199], v[100:103]
	v_mfma_f32_16x16x32_bf16 v[96:99], v[172:175], v[196:199], v[96:99]
	v_mfma_f32_16x16x32_bf16 v[84:87], v[148:151], v[204:207], v[84:87]
	v_mfma_f32_16x16x32_bf16 v[80:83], v[172:175], v[204:207], v[80:83]
	v_mfma_f32_16x16x32_bf16 v[68:71], v[148:151], v[212:215], v[68:71]
	v_mfma_f32_16x16x32_bf16 v[64:67], v[172:175], v[212:215], v[64:67]

	s_barrier
	s_add_i32 s36, s78, s53
	v_lshl_add_u64 v[216:217], v[216:217], 0, s[14:15]
	s_mov_b32 m0, s36
	ds_read_b128 v[176:179], v189 offset:49152
	ds_read_b128 v[180:183], v189 offset:50176
	ds_read_b128 v[192:195], v189 offset:51200
	ds_read_b128 v[196:199], v189 offset:52224
	ds_read_b128 v[200:203], v189 offset:53248
	ds_read_b128 v[204:207], v189 offset:54272
	ds_read_b128 v[208:211], v189 offset:55296
	ds_read_b128 v[212:215], v189 offset:56320
	global_load_lds_dwordx4 v[216:217], off
	s_add_i32 m0, s36, 0x2000
	s_add_u32 s36, s44, 0xb0080
	v_lshl_add_u64 v[216:217], v[218:219], 0, s[14:15]
	s_addc_u32 s37, s45, 0
	s_add_i32 s44, s79, s53
	global_load_lds_dwordx4 v[216:217], off

	s_mov_b32 m0, s44
	s_nop 0
	global_load_lds_dwordx4 v154, s[36:37]

	s_add_i32 m0, s44, 0x2000
	s_nop 0
	global_load_lds_dwordx4 v158, s[36:37]
	v_lshl_add_u64 v[216:217], v[220:221], 0, s[14:15]
	s_mov_b32 m0, s59
	s_nop 0
	global_load_lds_dwordx4 v[216:217], off
	v_lshl_add_u64 v[216:217], v[222:223], 0, s[14:15]
	s_mov_b32 m0, s62
	s_nop 0
	global_load_lds_dwordx4 v[216:217], off
	s_waitcnt vmcnt(8)
	s_waitcnt lgkmcnt(0)
	s_barrier

	v_mfma_f32_16x16x32_bf16 v[60:63], v[128:131], v[176:179], v[60:63]
	v_mfma_f32_16x16x32_bf16 v[56:59], v[136:139], v[176:179], v[56:59]
	v_mfma_f32_16x16x32_bf16 v[44:47], v[128:131], v[192:195], v[44:47]
	v_mfma_f32_16x16x32_bf16 v[40:43], v[136:139], v[192:195], v[40:43]
	v_mfma_f32_16x16x32_bf16 v[28:31], v[128:131], v[200:203], v[28:31]
	v_mfma_f32_16x16x32_bf16 v[24:27], v[136:139], v[200:203], v[24:27]
	v_mfma_f32_16x16x32_bf16 v[12:15], v[128:131], v[208:211], v[12:15]
	v_mfma_f32_16x16x32_bf16 v[8:11], v[136:139], v[208:211], v[8:11]
	v_mfma_f32_16x16x32_bf16 v[60:63], v[132:135], v[180:183], v[60:63]
	v_mfma_f32_16x16x32_bf16 v[56:59], v[140:143], v[180:183], v[56:59]
	v_mfma_f32_16x16x32_bf16 v[44:47], v[132:135], v[196:199], v[44:47]
	v_mfma_f32_16x16x32_bf16 v[40:43], v[140:143], v[196:199], v[40:43]
	v_mfma_f32_16x16x32_bf16 v[28:31], v[132:135], v[204:207], v[28:31]
	v_mfma_f32_16x16x32_bf16 v[24:27], v[140:143], v[204:207], v[24:27]
	v_mfma_f32_16x16x32_bf16 v[12:15], v[132:135], v[212:215], v[12:15]
	v_mfma_f32_16x16x32_bf16 v[8:11], v[140:143], v[212:215], v[8:11]

	v_mfma_f32_16x16x32_bf16 v[52:55], v[144:147], v[176:179], v[52:55]
	v_mfma_f32_16x16x32_bf16 v[48:51], v[168:171], v[176:179], v[48:51]
	v_mfma_f32_16x16x32_bf16 v[36:39], v[144:147], v[192:195], v[36:39]
	v_mfma_f32_16x16x32_bf16 v[32:35], v[168:171], v[192:195], v[32:35]
	v_mfma_f32_16x16x32_bf16 v[20:23], v[144:147], v[200:203], v[20:23]
	v_mfma_f32_16x16x32_bf16 v[16:19], v[168:171], v[200:203], v[16:19]
	v_mfma_f32_16x16x32_bf16 v[4:7], v[144:147], v[208:211], v[4:7]
	v_mfma_f32_16x16x32_bf16 v[0:3], v[168:171], v[208:211], v[0:3]
	v_mfma_f32_16x16x32_bf16 v[52:55], v[148:151], v[180:183], v[52:55]
	v_mfma_f32_16x16x32_bf16 v[48:51], v[172:175], v[180:183], v[48:51]
	v_mfma_f32_16x16x32_bf16 v[36:39], v[148:151], v[196:199], v[36:39]
	v_mfma_f32_16x16x32_bf16 v[32:35], v[172:175], v[196:199], v[32:35]
	v_mfma_f32_16x16x32_bf16 v[20:23], v[148:151], v[204:207], v[20:23]
	v_mfma_f32_16x16x32_bf16 v[16:19], v[172:175], v[204:207], v[16:19]
	v_mfma_f32_16x16x32_bf16 v[4:7], v[148:151], v[212:215], v[4:7]
	v_mfma_f32_16x16x32_bf16 v[0:3], v[172:175], v[212:215], v[0:3]

	s_barrier
	s_add_i32 s77, s77, 2
	s_add_u32 s73, s73, 0x100
	s_addc_u32 s76, s76, 0
	s_cmp_gt_u32 s77, 41
	s_mov_b64 s[36:37], s[38:39]
	s_cbranch_scc0 .LBB0_1080
	v_lshl_add_u32 v168, s72, 8, v184
	v_lshl_or_b32 v128, s18, 8, v186
	v_ashrrev_i32_e32 v169, 31, v168
	v_ashrrev_i32_e32 v129, 31, v128
	v_lshlrev_b64 v[130:131], 11, v[168:169]
	v_lshl_add_u64 v[130:131], s[34:35], 0, v[130:131]
	v_lshlrev_b64 v[170:171], 1, v[128:129]
	v_lshl_add_u64 v[200:201], v[130:131], 0, v[170:171]
	global_load_dwordx4 v[192:195], v[200:201], off
	global_load_dwordx4 v[196:199], v[200:201], off offset:256
	v_or_b32_e32 v180, 16, v168
	v_or_b32_e32 v176, 32, v168
	v_or_b32_e32 v172, 48, v168
	v_ashrrev_i32_e32 v181, 31, v180
	v_ashrrev_i32_e32 v177, 31, v176
	v_ashrrev_i32_e32 v173, 31, v172
	v_lshlrev_b64 v[128:129], 11, v[180:181]
	v_lshlrev_b64 v[130:131], 11, v[176:177]
	v_lshlrev_b64 v[132:133], 11, v[172:173]
	v_lshl_add_u64 v[128:129], s[34:35], 0, v[128:129]
	v_lshl_add_u64 v[130:131], s[34:35], 0, v[130:131]
	v_lshl_add_u64 v[132:133], s[34:35], 0, v[132:133]
	v_lshl_add_u64 v[182:183], v[128:129], 0, v[170:171]
	v_lshl_add_u64 v[178:179], v[130:131], 0, v[170:171]
	v_lshl_add_u64 v[174:175], v[132:133], 0, v[170:171]
	global_load_dwordx4 v[148:151], v[182:183], off
	global_load_dwordx4 v[144:147], v[182:183], off offset:256
	global_load_dwordx4 v[140:143], v[178:179], off
	global_load_dwordx4 v[136:139], v[178:179], off offset:256
	global_load_dwordx4 v[132:135], v[174:175], off
	global_load_dwordx4 v[128:131], v[174:175], off offset:256
	v_and_b32_e32 v202, 64, v190
	v_xor_b32_e32 v191, 16, v190
	v_add_u32_e32 v202, 64, v202
	v_xor_b32_e32 v203, 32, v190
	v_cmp_lt_i32_e32 vcc, v191, v202
	s_lshl_b32 s36, s18, 2
	s_ashr_i32 s37, s36, 31
	v_cndmask_b32_e32 v191, v190, v191, vcc
	v_cmp_lt_i32_e32 vcc, v203, v202
	v_lshlrev_b32_e32 v191, 2, v191
	s_waitcnt vmcnt(0)
	v_lshlrev_b32_e32 v202, 16, v192
	v_cndmask_b32_e32 v210, v190, v203, vcc
	v_and_b32_e32 v203, 0xffff0000, v192
	v_lshlrev_b32_e32 v192, 16, v193
	v_and_b32_e32 v193, 0xffff0000, v193
	v_lshlrev_b32_e32 v204, 16, v194
	v_and_b32_e32 v205, 0xffff0000, v194
	v_lshlrev_b32_e32 v194, 16, v195
	v_and_b32_e32 v195, 0xffff0000, v195
	v_lshlrev_b32_e32 v206, 16, v196
	v_and_b32_e32 v207, 0xffff0000, v196
	v_lshlrev_b32_e32 v196, 16, v197
	v_and_b32_e32 v197, 0xffff0000, v197
	v_lshlrev_b32_e32 v208, 16, v198
	v_and_b32_e32 v209, 0xffff0000, v198
	v_lshlrev_b32_e32 v198, 16, v199
	v_and_b32_e32 v199, 0xffff0000, v199
	v_pk_add_f32 v[126:127], v[126:127], v[192:193]
	v_pk_add_f32 v[124:125], v[124:125], v[202:203]
	v_pk_add_f32 v[122:123], v[122:123], v[194:195]
	v_pk_add_f32 v[120:121], v[120:121], v[204:205]
	v_pk_add_f32 v[118:119], v[118:119], v[196:197]
	v_pk_add_f32 v[116:117], v[116:117], v[206:207]
	v_pk_add_f32 v[192:193], v[114:115], v[198:199]
	v_pk_add_f32 v[194:195], v[112:113], v[208:209]
	v_cvt_pk_bf16_f32 v112, v124, v125
	v_cvt_pk_bf16_f32 v113, v126, v127
	v_mul_f32_e32 v114, v125, v125
	v_mul_f32_e32 v115, v127, v127
	v_mul_f32_e32 v125, v121, v121
	v_mul_f32_e32 v127, v123, v123
	v_mul_f32_e32 v196, v117, v117
	v_mul_f32_e32 v197, v119, v119
	v_mul_f32_e32 v198, v195, v195
	v_mul_f32_e32 v199, v193, v193
	v_fmac_f32_e32 v114, v124, v124
	v_fmac_f32_e32 v115, v126, v126
	v_fmac_f32_e32 v125, v120, v120
	v_fmac_f32_e32 v127, v122, v122
	v_fmac_f32_e32 v196, v116, v116
	v_fmac_f32_e32 v197, v118, v118
	v_fmac_f32_e32 v198, v194, v194
	v_fmac_f32_e32 v199, v192, v192
	v_add_f32_e32 v114, v114, v115
	v_add_f32_e32 v115, v125, v127
	v_add_f32_e32 v124, v196, v197
	v_add_f32_e32 v125, v198, v199
	v_add_f32_e32 v114, v114, v115
	v_add_f32_e32 v115, v124, v125
	v_add_f32_e32 v124, v114, v115
	ds_bpermute_b32 v125, v191, v124
	v_cvt_pk_bf16_f32 v114, v120, v121
	v_cvt_pk_bf16_f32 v115, v122, v123
	global_store_dwordx4 v[200:201], v[112:115], off
	v_cvt_pk_bf16_f32 v116, v116, v117
	v_cvt_pk_bf16_f32 v117, v118, v119
	s_waitcnt lgkmcnt(0)
	v_add_f32_e32 v113, v124, v125
	v_lshlrev_b32_e32 v112, 2, v210
	ds_bpermute_b32 v114, v112, v113
	v_cvt_pk_bf16_f32 v118, v194, v195
	v_cvt_pk_bf16_f32 v119, v192, v193
	global_store_dwordx4 v[200:201], v[116:119], off offset:256
	s_and_saveexec_b64 s[38:39], s[0:1]
	s_cbranch_execz .LBB0_1083
	s_waitcnt lgkmcnt(0)
	v_add_f32_e32 v113, v113, v114
	v_lshlrev_b64 v[114:115], 6, v[168:169]
	v_lshl_add_u64 v[114:115], s[74:75], 0, v[114:115]
	v_lshl_add_u64 v[114:115], s[36:37], 2, v[114:115]
	s_lshl_b32 s18, s58, 2
	v_lshl_add_u64 v[114:115], v[114:115], 0, s[18:19]
	global_store_dword v[114:115], v113, off

.LBB0_1181:
	ds_read_b128 v[128:131], v175
	ds_read_b128 v[152:155], v175 offset:1024
	ds_read_b128 v[156:159], v175 offset:2048
	ds_read_b128 v[160:163], v175 offset:3072
	ds_read_b128 v[164:167], v176
	ds_read_b128 v[168:171], v176 offset:1024
	ds_read_b128 v[180:183], v176 offset:2048
	ds_read_b128 v[184:187], v176 offset:3072
	s_add_u32 s57, s2, 0xfffc0080
	s_addc_u32 s58, s3, -1
	s_cmp_eq_u32 s56, 12
	s_cselect_b32 s65, s37, s58
	s_cselect_b32 s64, s52, s57
	s_cselect_b32 s63, s39, s55
	s_cselect_b32 s62, s53, s54

	s_add_i32 m0, s79, 0xc000
	ds_read_b128 v[188:191], v177
	ds_read_b128 v[192:195], v177 offset:1024
	ds_read_b128 v[196:199], v177 offset:2048
	ds_read_b128 v[200:203], v177 offset:3072
	ds_read_b128 v[204:207], v177 offset:4096
	ds_read_b128 v[208:211], v177 offset:5120
	ds_read_b128 v[212:215], v177 offset:6144
	ds_read_b128 v[216:219], v177 offset:7168
	global_load_lds_dwordx4 v144, s[2:3]

	s_add_i32 m0, s79, 0xe000
	s_nop 0
	global_load_lds_dwordx4 v146, s[2:3]
	s_waitcnt vmcnt(8)
	s_waitcnt lgkmcnt(0)
	s_barrier

	v_mfma_f32_16x16x32_bf16 v[124:127], v[128:131], v[188:191], v[124:127]
	v_mfma_f32_16x16x32_bf16 v[120:123], v[156:159], v[188:191], v[120:123]
	v_mfma_f32_16x16x32_bf16 v[116:119], v[128:131], v[196:199], v[116:119]
	v_mfma_f32_16x16x32_bf16 v[112:115], v[156:159], v[196:199], v[112:115]
	v_mfma_f32_16x16x32_bf16 v[100:103], v[128:131], v[204:207], v[100:103]
	v_mfma_f32_16x16x32_bf16 v[96:99], v[156:159], v[204:207], v[96:99]
	v_mfma_f32_16x16x32_bf16 v[80:83], v[128:131], v[212:215], v[80:83]
	v_mfma_f32_16x16x32_bf16 v[76:79], v[156:159], v[212:215], v[76:79]
	v_mfma_f32_16x16x32_bf16 v[124:127], v[152:155], v[192:195], v[124:127]
	v_mfma_f32_16x16x32_bf16 v[120:123], v[160:163], v[192:195], v[120:123]
	v_mfma_f32_16x16x32_bf16 v[116:119], v[152:155], v[200:203], v[116:119]
	v_mfma_f32_16x16x32_bf16 v[112:115], v[160:163], v[200:203], v[112:115]
	v_mfma_f32_16x16x32_bf16 v[100:103], v[152:155], v[208:211], v[100:103]
	v_mfma_f32_16x16x32_bf16 v[96:99], v[160:163], v[208:211], v[96:99]
	v_mfma_f32_16x16x32_bf16 v[80:83], v[152:155], v[216:219], v[80:83]
	v_mfma_f32_16x16x32_bf16 v[76:79], v[160:163], v[216:219], v[76:79]

	v_mfma_f32_16x16x32_bf16 v[108:111], v[164:167], v[188:191], v[108:111]
	v_mfma_f32_16x16x32_bf16 v[104:107], v[180:183], v[188:191], v[104:107]
	v_mfma_f32_16x16x32_bf16 v[92:95], v[164:167], v[196:199], v[92:95]
	v_mfma_f32_16x16x32_bf16 v[88:91], v[180:183], v[196:199], v[88:91]
	v_mfma_f32_16x16x32_bf16 v[84:87], v[164:167], v[204:207], v[84:87]
	v_mfma_f32_16x16x32_bf16 v[72:75], v[180:183], v[204:207], v[72:75]
	v_mfma_f32_16x16x32_bf16 v[68:71], v[164:167], v[212:215], v[68:71]
	v_mfma_f32_16x16x32_bf16 v[32:35], v[180:183], v[212:215], v[32:35]
	v_mfma_f32_16x16x32_bf16 v[108:111], v[168:171], v[192:195], v[108:111]
	v_mfma_f32_16x16x32_bf16 v[104:107], v[184:187], v[192:195], v[104:107]
	v_mfma_f32_16x16x32_bf16 v[92:95], v[168:171], v[200:203], v[92:95]
	v_mfma_f32_16x16x32_bf16 v[88:91], v[184:187], v[200:203], v[88:91]
	v_mfma_f32_16x16x32_bf16 v[84:87], v[168:171], v[208:211], v[84:87]
	v_mfma_f32_16x16x32_bf16 v[72:75], v[184:187], v[208:211], v[72:75]
	v_mfma_f32_16x16x32_bf16 v[68:71], v[168:171], v[216:219], v[68:71]
	v_mfma_f32_16x16x32_bf16 v[32:35], v[184:187], v[216:219], v[32:35]

	s_barrier
	s_add_i32 s57, s89, s66
	v_lshl_add_u64 v[220:221], s[62:63], 0, v[134:135]
	s_mov_b32 m0, s57
	ds_read_b128 v[188:191], v177 offset:16384
	ds_read_b128 v[192:195], v177 offset:17408
	ds_read_b128 v[196:199], v177 offset:18432
	ds_read_b128 v[200:203], v177 offset:19456
	ds_read_b128 v[204:207], v177 offset:20480
	ds_read_b128 v[208:211], v177 offset:21504
	ds_read_b128 v[212:215], v177 offset:22528
	ds_read_b128 v[216:219], v177 offset:23552
	global_load_lds_dwordx4 v[220:221], off
	s_add_i32 m0, s57, 0x2000
	s_add_u32 s58, s62, 0x40000
	v_lshl_add_u64 v[222:223], s[62:63], 0, v[138:139]
	s_addc_u32 s59, s63, 0
	s_add_i32 s57, s90, s66
	global_load_lds_dwordx4 v[222:223], off

	s_mov_b32 m0, s57
	v_lshl_add_u64 v[226:227], s[64:65], 0, v[136:137]
	global_load_lds_dwordx4 v134, s[58:59]

	s_add_i32 m0, s57, 0x2000
	s_nop 0
	global_load_lds_dwordx4 v138, s[58:59]
	v_lshl_add_u64 v[224:225], s[64:65], 0, v[132:133]
	s_mov_b32 m0, s79
	s_nop 0
	global_load_lds_dwordx4 v[224:225], off
	s_mov_b32 m0, s80
	s_nop 0
	global_load_lds_dwordx4 v[226:227], off
	s_waitcnt vmcnt(8)
	s_waitcnt lgkmcnt(0)
	s_barrier

	v_mfma_f32_16x16x32_bf16 v[64:67], v[128:131], v[188:191], v[64:67]
	v_mfma_f32_16x16x32_bf16 v[60:63], v[156:159], v[188:191], v[60:63]
	v_mfma_f32_16x16x32_bf16 v[56:59], v[128:131], v[196:199], v[56:59]
	v_mfma_f32_16x16x32_bf16 v[52:55], v[156:159], v[196:199], v[52:55]
	v_mfma_f32_16x16x32_bf16 v[48:51], v[128:131], v[204:207], v[48:51]
	v_mfma_f32_16x16x32_bf16 v[44:47], v[156:159], v[204:207], v[44:47]
	v_mfma_f32_16x16x32_bf16 v[40:43], v[128:131], v[212:215], v[40:43]
	v_mfma_f32_16x16x32_bf16 v[36:39], v[156:159], v[212:215], v[36:39]
	v_mfma_f32_16x16x32_bf16 v[64:67], v[152:155], v[192:195], v[64:67]
	v_mfma_f32_16x16x32_bf16 v[60:63], v[160:163], v[192:195], v[60:63]
	v_mfma_f32_16x16x32_bf16 v[56:59], v[152:155], v[200:203], v[56:59]
	v_mfma_f32_16x16x32_bf16 v[52:55], v[160:163], v[200:203], v[52:55]
	v_mfma_f32_16x16x32_bf16 v[48:51], v[152:155], v[208:211], v[48:51]
	v_mfma_f32_16x16x32_bf16 v[44:47], v[160:163], v[208:211], v[44:47]
	v_mfma_f32_16x16x32_bf16 v[40:43], v[152:155], v[216:219], v[40:43]
	v_mfma_f32_16x16x32_bf16 v[36:39], v[160:163], v[216:219], v[36:39]

	v_mfma_f32_16x16x32_bf16 v[28:31], v[164:167], v[188:191], v[28:31]
	v_mfma_f32_16x16x32_bf16 v[24:27], v[180:183], v[188:191], v[24:27]
	v_mfma_f32_16x16x32_bf16 v[20:23], v[164:167], v[196:199], v[20:23]
	v_mfma_f32_16x16x32_bf16 v[16:19], v[180:183], v[196:199], v[16:19]
	v_mfma_f32_16x16x32_bf16 v[12:15], v[164:167], v[204:207], v[12:15]
	v_mfma_f32_16x16x32_bf16 v[8:11], v[180:183], v[204:207], v[8:11]
	v_mfma_f32_16x16x32_bf16 v[4:7], v[164:167], v[212:215], v[4:7]
	v_mfma_f32_16x16x32_bf16 v[0:3], v[180:183], v[212:215], v[0:3]
	v_mfma_f32_16x16x32_bf16 v[28:31], v[168:171], v[192:195], v[28:31]
	v_mfma_f32_16x16x32_bf16 v[24:27], v[184:187], v[192:195], v[24:27]
	v_mfma_f32_16x16x32_bf16 v[20:23], v[168:171], v[200:203], v[20:23]
	v_mfma_f32_16x16x32_bf16 v[16:19], v[184:187], v[200:203], v[16:19]
	v_mfma_f32_16x16x32_bf16 v[12:15], v[168:171], v[208:211], v[12:15]
	v_mfma_f32_16x16x32_bf16 v[8:11], v[184:187], v[208:211], v[8:11]
	v_mfma_f32_16x16x32_bf16 v[4:7], v[168:171], v[216:219], v[4:7]
	v_mfma_f32_16x16x32_bf16 v[0:3], v[184:187], v[216:219], v[0:3]

	s_barrier
	s_add_i32 s57, 0, 0x18000
	v_add_u32_e32 v140, s57, v173
	s_add_i32 s68, 0, 0x1c000
	ds_read_b128 v[128:131], v140
	ds_read_b128 v[152:155], v140 offset:1024
	ds_read_b128 v[156:159], v140 offset:2048
	ds_read_b128 v[160:163], v140 offset:3072
	v_add_u32_e32 v140, s68, v173
	ds_read_b128 v[164:167], v140
	ds_read_b128 v[168:171], v140 offset:1024
	ds_read_b128 v[180:183], v140 offset:2048
	ds_read_b128 v[184:187], v140 offset:3072
	s_add_u32 s58, s64, 0x40000
	s_addc_u32 s59, s65, 0
	s_mov_b32 m0, s81

	ds_read_b128 v[188:191], v177 offset:32768
	ds_read_b128 v[192:195], v177 offset:33792
	ds_read_b128 v[196:199], v177 offset:34816
	ds_read_b128 v[200:203], v177 offset:35840
	ds_read_b128 v[204:207], v177 offset:36864
	ds_read_b128 v[208:211], v177 offset:37888
	ds_read_b128 v[212:215], v177 offset:38912
	ds_read_b128 v[216:219], v177 offset:39936
	global_load_lds_dwordx4 v132, s[58:59]

	s_mov_b32 m0, s82
	s_nop 0
	global_load_lds_dwordx4 v136, s[58:59]
	s_waitcnt vmcnt(8)
	s_waitcnt lgkmcnt(0)
	s_barrier

	v_mfma_f32_16x16x32_bf16 v[124:127], v[128:131], v[188:191], v[124:127]
	v_mfma_f32_16x16x32_bf16 v[120:123], v[156:159], v[188:191], v[120:123]
	v_mfma_f32_16x16x32_bf16 v[116:119], v[128:131], v[196:199], v[116:119]
	v_mfma_f32_16x16x32_bf16 v[112:115], v[156:159], v[196:199], v[112:115]
	v_mfma_f32_16x16x32_bf16 v[100:103], v[128:131], v[204:207], v[100:103]
	v_mfma_f32_16x16x32_bf16 v[96:99], v[156:159], v[204:207], v[96:99]
	v_mfma_f32_16x16x32_bf16 v[80:83], v[128:131], v[212:215], v[80:83]
	v_mfma_f32_16x16x32_bf16 v[76:79], v[156:159], v[212:215], v[76:79]
	v_mfma_f32_16x16x32_bf16 v[124:127], v[152:155], v[192:195], v[124:127]
	v_mfma_f32_16x16x32_bf16 v[120:123], v[160:163], v[192:195], v[120:123]
	v_mfma_f32_16x16x32_bf16 v[116:119], v[152:155], v[200:203], v[116:119]
	v_mfma_f32_16x16x32_bf16 v[112:115], v[160:163], v[200:203], v[112:115]
	v_mfma_f32_16x16x32_bf16 v[100:103], v[152:155], v[208:211], v[100:103]
	v_mfma_f32_16x16x32_bf16 v[96:99], v[160:163], v[208:211], v[96:99]
	v_mfma_f32_16x16x32_bf16 v[80:83], v[152:155], v[216:219], v[80:83]
	v_mfma_f32_16x16x32_bf16 v[76:79], v[160:163], v[216:219], v[76:79]

	v_mfma_f32_16x16x32_bf16 v[108:111], v[164:167], v[188:191], v[108:111]
	v_mfma_f32_16x16x32_bf16 v[104:107], v[180:183], v[188:191], v[104:107]
	v_mfma_f32_16x16x32_bf16 v[92:95], v[164:167], v[196:199], v[92:95]
	v_mfma_f32_16x16x32_bf16 v[88:91], v[180:183], v[196:199], v[88:91]
	v_mfma_f32_16x16x32_bf16 v[84:87], v[164:167], v[204:207], v[84:87]
	v_mfma_f32_16x16x32_bf16 v[72:75], v[180:183], v[204:207], v[72:75]
	v_mfma_f32_16x16x32_bf16 v[68:71], v[164:167], v[212:215], v[68:71]
	v_mfma_f32_16x16x32_bf16 v[32:35], v[180:183], v[212:215], v[32:35]
	v_mfma_f32_16x16x32_bf16 v[108:111], v[168:171], v[192:195], v[108:111]
	v_mfma_f32_16x16x32_bf16 v[104:107], v[184:187], v[192:195], v[104:107]
	v_mfma_f32_16x16x32_bf16 v[92:95], v[168:171], v[200:203], v[92:95]
	v_mfma_f32_16x16x32_bf16 v[88:91], v[184:187], v[200:203], v[88:91]
	v_mfma_f32_16x16x32_bf16 v[84:87], v[168:171], v[208:211], v[84:87]
	v_mfma_f32_16x16x32_bf16 v[72:75], v[184:187], v[208:211], v[72:75]
	v_mfma_f32_16x16x32_bf16 v[68:71], v[168:171], v[216:219], v[68:71]
	v_mfma_f32_16x16x32_bf16 v[32:35], v[184:187], v[216:219], v[32:35]

	s_barrier
	s_add_i32 s57, s57, s66
	v_lshl_add_u64 v[220:221], v[220:221], 0, s[12:13]
	s_mov_b32 m0, s57
	ds_read_b128 v[188:191], v177 offset:49152
	ds_read_b128 v[192:195], v177 offset:50176
	ds_read_b128 v[196:199], v177 offset:51200
	ds_read_b128 v[200:203], v177 offset:52224
	ds_read_b128 v[204:207], v177 offset:53248
	ds_read_b128 v[208:211], v177 offset:54272
	ds_read_b128 v[212:215], v177 offset:55296
	ds_read_b128 v[216:219], v177 offset:56320
	global_load_lds_dwordx4 v[220:221], off
	s_add_i32 m0, s57, 0x2000
	s_add_u32 s58, s62, 0x40080
	v_lshl_add_u64 v[220:221], v[222:223], 0, s[12:13]
	s_addc_u32 s59, s63, 0
	s_add_i32 s57, s68, s66
	global_load_lds_dwordx4 v[220:221], off

	s_mov_b32 m0, s57
	s_nop 0
	global_load_lds_dwordx4 v134, s[58:59]

	s_add_i32 m0, s57, 0x2000
	s_nop 0
	global_load_lds_dwordx4 v138, s[58:59]
	v_lshl_add_u64 v[220:221], v[224:225], 0, s[12:13]
	s_mov_b32 m0, s86
	s_nop 0
	global_load_lds_dwordx4 v[220:221], off
	v_lshl_add_u64 v[220:221], v[226:227], 0, s[12:13]
	s_mov_b32 m0, s87
	s_nop 0
	global_load_lds_dwordx4 v[220:221], off
	s_waitcnt vmcnt(8)
	s_waitcnt lgkmcnt(0)
	s_barrier

	v_mfma_f32_16x16x32_bf16 v[64:67], v[128:131], v[188:191], v[64:67]
	v_mfma_f32_16x16x32_bf16 v[60:63], v[156:159], v[188:191], v[60:63]
	v_mfma_f32_16x16x32_bf16 v[56:59], v[128:131], v[196:199], v[56:59]
	v_mfma_f32_16x16x32_bf16 v[52:55], v[156:159], v[196:199], v[52:55]
	v_mfma_f32_16x16x32_bf16 v[48:51], v[128:131], v[204:207], v[48:51]
	v_mfma_f32_16x16x32_bf16 v[44:47], v[156:159], v[204:207], v[44:47]
	v_mfma_f32_16x16x32_bf16 v[40:43], v[128:131], v[212:215], v[40:43]
	v_mfma_f32_16x16x32_bf16 v[36:39], v[156:159], v[212:215], v[36:39]
	v_mfma_f32_16x16x32_bf16 v[64:67], v[152:155], v[192:195], v[64:67]
	v_mfma_f32_16x16x32_bf16 v[60:63], v[160:163], v[192:195], v[60:63]
	v_mfma_f32_16x16x32_bf16 v[56:59], v[152:155], v[200:203], v[56:59]
	v_mfma_f32_16x16x32_bf16 v[52:55], v[160:163], v[200:203], v[52:55]
	v_mfma_f32_16x16x32_bf16 v[48:51], v[152:155], v[208:211], v[48:51]
	v_mfma_f32_16x16x32_bf16 v[44:47], v[160:163], v[208:211], v[44:47]
	v_mfma_f32_16x16x32_bf16 v[40:43], v[152:155], v[216:219], v[40:43]
	v_mfma_f32_16x16x32_bf16 v[36:39], v[160:163], v[216:219], v[36:39]

	v_mfma_f32_16x16x32_bf16 v[28:31], v[164:167], v[188:191], v[28:31]
	v_mfma_f32_16x16x32_bf16 v[24:27], v[180:183], v[188:191], v[24:27]
	v_mfma_f32_16x16x32_bf16 v[20:23], v[164:167], v[196:199], v[20:23]
	v_mfma_f32_16x16x32_bf16 v[16:19], v[180:183], v[196:199], v[16:19]
	v_mfma_f32_16x16x32_bf16 v[12:15], v[164:167], v[204:207], v[12:15]
	v_mfma_f32_16x16x32_bf16 v[8:11], v[180:183], v[204:207], v[8:11]
	v_mfma_f32_16x16x32_bf16 v[4:7], v[164:167], v[212:215], v[4:7]
	v_mfma_f32_16x16x32_bf16 v[0:3], v[180:183], v[212:215], v[0:3]
	v_mfma_f32_16x16x32_bf16 v[28:31], v[168:171], v[192:195], v[28:31]
	v_mfma_f32_16x16x32_bf16 v[24:27], v[184:187], v[192:195], v[24:27]
	v_mfma_f32_16x16x32_bf16 v[20:23], v[168:171], v[200:203], v[20:23]
	v_mfma_f32_16x16x32_bf16 v[16:19], v[184:187], v[200:203], v[16:19]
	v_mfma_f32_16x16x32_bf16 v[12:15], v[168:171], v[208:211], v[12:15]
	v_mfma_f32_16x16x32_bf16 v[8:11], v[184:187], v[208:211], v[8:11]
	v_mfma_f32_16x16x32_bf16 v[4:7], v[168:171], v[216:219], v[4:7]
	v_mfma_f32_16x16x32_bf16 v[0:3], v[184:187], v[216:219], v[0:3]

	s_barrier
	s_add_i32 s56, s56, 2
	s_add_u32 s2, s2, 0x100
	s_addc_u32 s3, s3, 0
	s_add_u32 s54, s54, 0x100
	s_addc_u32 s55, s55, 0
	s_cmp_gt_u32 s56, 13
	s_cbranch_scc0 .LBB0_1181
	s_and_b64 vcc, exec, s[14:15]
	s_cbranch_vccz .LBB0_1184
	s_barrier

.LBB0_1530:
	ds_read_b128 v[128:131], v187
	ds_read_b128 v[132:135], v187 offset:1024
	ds_read_b128 v[136:139], v187 offset:2048
	ds_read_b128 v[140:143], v187 offset:3072
	ds_read_b128 v[144:147], v188
	ds_read_b128 v[148:151], v188 offset:1024
	ds_read_b128 v[168:171], v188 offset:2048
	ds_read_b128 v[172:175], v188 offset:3072
	s_add_u32 s36, s24, 0xfffc0080
	s_addc_u32 s37, s25, -1
	s_cmp_eq_u32 s65, 12
	s_cselect_b32 s39, s11, s37
	s_cselect_b32 s38, s61, s36
	s_cselect_b32 s37, s13, s64
	s_cselect_b32 s36, s62, s63

	s_add_i32 m0, s46, 0xc000
	ds_read_b128 v[176:179], v189
	ds_read_b128 v[180:183], v189 offset:1024
	ds_read_b128 v[192:195], v189 offset:2048
	ds_read_b128 v[196:199], v189 offset:3072
	ds_read_b128 v[200:203], v189 offset:4096
	ds_read_b128 v[204:207], v189 offset:5120
	ds_read_b128 v[208:211], v189 offset:6144
	ds_read_b128 v[212:215], v189 offset:7168
	global_load_lds_dwordx4 v160, s[24:25]

	s_add_i32 m0, s46, 0xe000
	s_nop 0
	global_load_lds_dwordx4 v162, s[24:25]
	s_waitcnt vmcnt(8)
	s_waitcnt lgkmcnt(0)
	s_barrier

	v_mfma_f32_16x16x32_bf16 v[124:127], v[128:131], v[176:179], v[124:127]
	v_mfma_f32_16x16x32_bf16 v[120:123], v[136:139], v[176:179], v[120:123]
	v_mfma_f32_16x16x32_bf16 v[108:111], v[128:131], v[192:195], v[108:111]
	v_mfma_f32_16x16x32_bf16 v[104:107], v[136:139], v[192:195], v[104:107]
	v_mfma_f32_16x16x32_bf16 v[92:95], v[128:131], v[200:203], v[92:95]
	v_mfma_f32_16x16x32_bf16 v[88:91], v[136:139], v[200:203], v[88:91]
	v_mfma_f32_16x16x32_bf16 v[76:79], v[128:131], v[208:211], v[76:79]
	v_mfma_f32_16x16x32_bf16 v[72:75], v[136:139], v[208:211], v[72:75]
	v_mfma_f32_16x16x32_bf16 v[124:127], v[132:135], v[180:183], v[124:127]
	v_mfma_f32_16x16x32_bf16 v[120:123], v[140:143], v[180:183], v[120:123]
	v_mfma_f32_16x16x32_bf16 v[108:111], v[132:135], v[196:199], v[108:111]
	v_mfma_f32_16x16x32_bf16 v[104:107], v[140:143], v[196:199], v[104:107]
	v_mfma_f32_16x16x32_bf16 v[92:95], v[132:135], v[204:207], v[92:95]
	v_mfma_f32_16x16x32_bf16 v[88:91], v[140:143], v[204:207], v[88:91]
	v_mfma_f32_16x16x32_bf16 v[76:79], v[132:135], v[212:215], v[76:79]
	v_mfma_f32_16x16x32_bf16 v[72:75], v[140:143], v[212:215], v[72:75]

	v_mfma_f32_16x16x32_bf16 v[116:119], v[144:147], v[176:179], v[116:119]
	v_mfma_f32_16x16x32_bf16 v[112:115], v[168:171], v[176:179], v[112:115]
	v_mfma_f32_16x16x32_bf16 v[100:103], v[144:147], v[192:195], v[100:103]
	v_mfma_f32_16x16x32_bf16 v[96:99], v[168:171], v[192:195], v[96:99]
	v_mfma_f32_16x16x32_bf16 v[84:87], v[144:147], v[200:203], v[84:87]
	v_mfma_f32_16x16x32_bf16 v[80:83], v[168:171], v[200:203], v[80:83]
	v_mfma_f32_16x16x32_bf16 v[68:71], v[144:147], v[208:211], v[68:71]
	v_mfma_f32_16x16x32_bf16 v[64:67], v[168:171], v[208:211], v[64:67]
	v_mfma_f32_16x16x32_bf16 v[116:119], v[148:151], v[180:183], v[116:119]
	v_mfma_f32_16x16x32_bf16 v[112:115], v[172:175], v[180:183], v[112:115]
	v_mfma_f32_16x16x32_bf16 v[100:103], v[148:151], v[196:199], v[100:103]
	v_mfma_f32_16x16x32_bf16 v[96:99], v[172:175], v[196:199], v[96:99]
	v_mfma_f32_16x16x32_bf16 v[84:87], v[148:151], v[204:207], v[84:87]
	v_mfma_f32_16x16x32_bf16 v[80:83], v[172:175], v[204:207], v[80:83]
	v_mfma_f32_16x16x32_bf16 v[68:71], v[148:151], v[212:215], v[68:71]
	v_mfma_f32_16x16x32_bf16 v[64:67], v[172:175], v[212:215], v[64:67]

	s_barrier
	s_add_i32 s66, s55, s45
	v_lshl_add_u64 v[216:217], s[36:37], 0, v[154:155]
	s_mov_b32 m0, s66
	ds_read_b128 v[176:179], v189 offset:16384
	ds_read_b128 v[180:183], v189 offset:17408
	ds_read_b128 v[192:195], v189 offset:18432
	ds_read_b128 v[196:199], v189 offset:19456
	ds_read_b128 v[200:203], v189 offset:20480
	ds_read_b128 v[204:207], v189 offset:21504
	ds_read_b128 v[208:211], v189 offset:22528
	ds_read_b128 v[212:215], v189 offset:23552
	global_load_lds_dwordx4 v[216:217], off
	s_add_i32 m0, s66, 0x2000
	s_add_u32 s66, s36, 0x40000
	v_lshl_add_u64 v[218:219], s[36:37], 0, v[158:159]
	s_addc_u32 s67, s37, 0
	s_add_i32 s68, s56, s45
	global_load_lds_dwordx4 v[218:219], off

	s_mov_b32 m0, s68
	v_lshl_add_u64 v[222:223], s[38:39], 0, v[156:157]
	global_load_lds_dwordx4 v154, s[66:67]

	s_add_i32 m0, s68, 0x2000
	s_nop 0
	global_load_lds_dwordx4 v158, s[66:67]
	v_lshl_add_u64 v[220:221], s[38:39], 0, v[152:153]
	s_mov_b32 m0, s46
	s_nop 0
	global_load_lds_dwordx4 v[220:221], off
	s_mov_b32 m0, s47
	s_nop 0
	global_load_lds_dwordx4 v[222:223], off
	s_waitcnt vmcnt(8)
	s_waitcnt lgkmcnt(0)
	s_barrier

	v_mfma_f32_16x16x32_bf16 v[60:63], v[128:131], v[176:179], v[60:63]
	v_mfma_f32_16x16x32_bf16 v[56:59], v[136:139], v[176:179], v[56:59]
	v_mfma_f32_16x16x32_bf16 v[44:47], v[128:131], v[192:195], v[44:47]
	v_mfma_f32_16x16x32_bf16 v[40:43], v[136:139], v[192:195], v[40:43]
	v_mfma_f32_16x16x32_bf16 v[28:31], v[128:131], v[200:203], v[28:31]
	v_mfma_f32_16x16x32_bf16 v[24:27], v[136:139], v[200:203], v[24:27]
	v_mfma_f32_16x16x32_bf16 v[12:15], v[128:131], v[208:211], v[12:15]
	v_mfma_f32_16x16x32_bf16 v[8:11], v[136:139], v[208:211], v[8:11]
	v_mfma_f32_16x16x32_bf16 v[60:63], v[132:135], v[180:183], v[60:63]
	v_mfma_f32_16x16x32_bf16 v[56:59], v[140:143], v[180:183], v[56:59]
	v_mfma_f32_16x16x32_bf16 v[44:47], v[132:135], v[196:199], v[44:47]
	v_mfma_f32_16x16x32_bf16 v[40:43], v[140:143], v[196:199], v[40:43]
	v_mfma_f32_16x16x32_bf16 v[28:31], v[132:135], v[204:207], v[28:31]
	v_mfma_f32_16x16x32_bf16 v[24:27], v[140:143], v[204:207], v[24:27]
	v_mfma_f32_16x16x32_bf16 v[12:15], v[132:135], v[212:215], v[12:15]
	v_mfma_f32_16x16x32_bf16 v[8:11], v[140:143], v[212:215], v[8:11]

	v_mfma_f32_16x16x32_bf16 v[52:55], v[144:147], v[176:179], v[52:55]
	v_mfma_f32_16x16x32_bf16 v[48:51], v[168:171], v[176:179], v[48:51]
	v_mfma_f32_16x16x32_bf16 v[36:39], v[144:147], v[192:195], v[36:39]
	v_mfma_f32_16x16x32_bf16 v[32:35], v[168:171], v[192:195], v[32:35]
	v_mfma_f32_16x16x32_bf16 v[20:23], v[144:147], v[200:203], v[20:23]
	v_mfma_f32_16x16x32_bf16 v[16:19], v[168:171], v[200:203], v[16:19]
	v_mfma_f32_16x16x32_bf16 v[4:7], v[144:147], v[208:211], v[4:7]
	v_mfma_f32_16x16x32_bf16 v[0:3], v[168:171], v[208:211], v[0:3]
	v_mfma_f32_16x16x32_bf16 v[52:55], v[148:151], v[180:183], v[52:55]
	v_mfma_f32_16x16x32_bf16 v[48:51], v[172:175], v[180:183], v[48:51]
	v_mfma_f32_16x16x32_bf16 v[36:39], v[148:151], v[196:199], v[36:39]
	v_mfma_f32_16x16x32_bf16 v[32:35], v[172:175], v[196:199], v[32:35]
	v_mfma_f32_16x16x32_bf16 v[20:23], v[148:151], v[204:207], v[20:23]
	v_mfma_f32_16x16x32_bf16 v[16:19], v[172:175], v[204:207], v[16:19]
	v_mfma_f32_16x16x32_bf16 v[4:7], v[148:151], v[212:215], v[4:7]
	v_mfma_f32_16x16x32_bf16 v[0:3], v[172:175], v[212:215], v[0:3]

	s_barrier
	s_add_i32 s66, 0, 0x18000
	s_add_i32 s67, 0, 0x1c000
	v_add_u32_e32 v140, s66, v185
	v_add_u32_e32 v172, s67, v185
	ds_read_b128 v[128:131], v140
	ds_read_b128 v[132:135], v140 offset:1024
	ds_read_b128 v[136:139], v140 offset:2048
	ds_read_b128 v[140:143], v140 offset:3072
	ds_read_b128 v[144:147], v172
	ds_read_b128 v[148:151], v172 offset:1024
	ds_read_b128 v[168:171], v172 offset:2048
	ds_read_b128 v[172:175], v172 offset:3072
	s_add_u32 s38, s38, 0x40000
	s_addc_u32 s39, s39, 0
	s_mov_b32 m0, s48

	ds_read_b128 v[176:179], v189 offset:32768
	ds_read_b128 v[180:183], v189 offset:33792
	ds_read_b128 v[192:195], v189 offset:34816
	ds_read_b128 v[196:199], v189 offset:35840
	ds_read_b128 v[200:203], v189 offset:36864
	ds_read_b128 v[204:207], v189 offset:37888
	ds_read_b128 v[208:211], v189 offset:38912
	ds_read_b128 v[212:215], v189 offset:39936
	global_load_lds_dwordx4 v152, s[38:39]

	s_mov_b32 m0, s49
	s_nop 0
	global_load_lds_dwordx4 v156, s[38:39]
	s_waitcnt vmcnt(8)
	s_waitcnt lgkmcnt(0)
	s_barrier

	v_mfma_f32_16x16x32_bf16 v[124:127], v[128:131], v[176:179], v[124:127]
	v_mfma_f32_16x16x32_bf16 v[120:123], v[136:139], v[176:179], v[120:123]
	v_mfma_f32_16x16x32_bf16 v[108:111], v[128:131], v[192:195], v[108:111]
	v_mfma_f32_16x16x32_bf16 v[104:107], v[136:139], v[192:195], v[104:107]
	v_mfma_f32_16x16x32_bf16 v[92:95], v[128:131], v[200:203], v[92:95]
	v_mfma_f32_16x16x32_bf16 v[88:91], v[136:139], v[200:203], v[88:91]
	v_mfma_f32_16x16x32_bf16 v[76:79], v[128:131], v[208:211], v[76:79]
	v_mfma_f32_16x16x32_bf16 v[72:75], v[136:139], v[208:211], v[72:75]
	v_mfma_f32_16x16x32_bf16 v[124:127], v[132:135], v[180:183], v[124:127]
	v_mfma_f32_16x16x32_bf16 v[120:123], v[140:143], v[180:183], v[120:123]
	v_mfma_f32_16x16x32_bf16 v[108:111], v[132:135], v[196:199], v[108:111]
	v_mfma_f32_16x16x32_bf16 v[104:107], v[140:143], v[196:199], v[104:107]
	v_mfma_f32_16x16x32_bf16 v[92:95], v[132:135], v[204:207], v[92:95]
	v_mfma_f32_16x16x32_bf16 v[88:91], v[140:143], v[204:207], v[88:91]
	v_mfma_f32_16x16x32_bf16 v[76:79], v[132:135], v[212:215], v[76:79]
	v_mfma_f32_16x16x32_bf16 v[72:75], v[140:143], v[212:215], v[72:75]

	v_mfma_f32_16x16x32_bf16 v[116:119], v[144:147], v[176:179], v[116:119]
	v_mfma_f32_16x16x32_bf16 v[112:115], v[168:171], v[176:179], v[112:115]
	v_mfma_f32_16x16x32_bf16 v[100:103], v[144:147], v[192:195], v[100:103]
	v_mfma_f32_16x16x32_bf16 v[96:99], v[168:171], v[192:195], v[96:99]
	v_mfma_f32_16x16x32_bf16 v[84:87], v[144:147], v[200:203], v[84:87]
	v_mfma_f32_16x16x32_bf16 v[80:83], v[168:171], v[200:203], v[80:83]
	v_mfma_f32_16x16x32_bf16 v[68:71], v[144:147], v[208:211], v[68:71]
	v_mfma_f32_16x16x32_bf16 v[64:67], v[168:171], v[208:211], v[64:67]
	v_mfma_f32_16x16x32_bf16 v[116:119], v[148:151], v[180:183], v[116:119]
	v_mfma_f32_16x16x32_bf16 v[112:115], v[172:175], v[180:183], v[112:115]
	v_mfma_f32_16x16x32_bf16 v[100:103], v[148:151], v[196:199], v[100:103]
	v_mfma_f32_16x16x32_bf16 v[96:99], v[172:175], v[196:199], v[96:99]
	v_mfma_f32_16x16x32_bf16 v[84:87], v[148:151], v[204:207], v[84:87]
	v_mfma_f32_16x16x32_bf16 v[80:83], v[172:175], v[204:207], v[80:83]
	v_mfma_f32_16x16x32_bf16 v[68:71], v[148:151], v[212:215], v[68:71]
	v_mfma_f32_16x16x32_bf16 v[64:67], v[172:175], v[212:215], v[64:67]

	s_barrier
	s_add_i32 s38, s66, s45
	v_lshl_add_u64 v[216:217], v[216:217], 0, s[6:7]
	s_mov_b32 m0, s38
	ds_read_b128 v[176:179], v189 offset:49152
	ds_read_b128 v[180:183], v189 offset:50176
	ds_read_b128 v[192:195], v189 offset:51200
	ds_read_b128 v[196:199], v189 offset:52224
	ds_read_b128 v[200:203], v189 offset:53248
	ds_read_b128 v[204:207], v189 offset:54272
	ds_read_b128 v[208:211], v189 offset:55296
	ds_read_b128 v[212:215], v189 offset:56320
	global_load_lds_dwordx4 v[216:217], off
	s_add_i32 m0, s38, 0x2000
	s_add_u32 s36, s36, 0x40080
	v_lshl_add_u64 v[216:217], v[218:219], 0, s[6:7]
	s_addc_u32 s37, s37, 0
	s_add_i32 s38, s67, s45
	global_load_lds_dwordx4 v[216:217], off

	s_mov_b32 m0, s38
	s_nop 0
	global_load_lds_dwordx4 v154, s[36:37]

	s_add_i32 m0, s38, 0x2000
	s_nop 0
	global_load_lds_dwordx4 v158, s[36:37]
	v_lshl_add_u64 v[216:217], v[220:221], 0, s[6:7]
	s_mov_b32 m0, s51
	s_nop 0
	global_load_lds_dwordx4 v[216:217], off
	v_lshl_add_u64 v[216:217], v[222:223], 0, s[6:7]
	s_mov_b32 m0, s52
	s_nop 0
	global_load_lds_dwordx4 v[216:217], off
	s_waitcnt vmcnt(8)
	s_waitcnt lgkmcnt(0)
	s_barrier

	v_mfma_f32_16x16x32_bf16 v[60:63], v[128:131], v[176:179], v[60:63]
	v_mfma_f32_16x16x32_bf16 v[56:59], v[136:139], v[176:179], v[56:59]
	v_mfma_f32_16x16x32_bf16 v[44:47], v[128:131], v[192:195], v[44:47]
	v_mfma_f32_16x16x32_bf16 v[40:43], v[136:139], v[192:195], v[40:43]
	v_mfma_f32_16x16x32_bf16 v[28:31], v[128:131], v[200:203], v[28:31]
	v_mfma_f32_16x16x32_bf16 v[24:27], v[136:139], v[200:203], v[24:27]
	v_mfma_f32_16x16x32_bf16 v[12:15], v[128:131], v[208:211], v[12:15]
	v_mfma_f32_16x16x32_bf16 v[8:11], v[136:139], v[208:211], v[8:11]
	v_mfma_f32_16x16x32_bf16 v[60:63], v[132:135], v[180:183], v[60:63]
	v_mfma_f32_16x16x32_bf16 v[56:59], v[140:143], v[180:183], v[56:59]
	v_mfma_f32_16x16x32_bf16 v[44:47], v[132:135], v[196:199], v[44:47]
	v_mfma_f32_16x16x32_bf16 v[40:43], v[140:143], v[196:199], v[40:43]
	v_mfma_f32_16x16x32_bf16 v[28:31], v[132:135], v[204:207], v[28:31]
	v_mfma_f32_16x16x32_bf16 v[24:27], v[140:143], v[204:207], v[24:27]
	v_mfma_f32_16x16x32_bf16 v[12:15], v[132:135], v[212:215], v[12:15]
	v_mfma_f32_16x16x32_bf16 v[8:11], v[140:143], v[212:215], v[8:11]

	v_mfma_f32_16x16x32_bf16 v[52:55], v[144:147], v[176:179], v[52:55]
	v_mfma_f32_16x16x32_bf16 v[48:51], v[168:171], v[176:179], v[48:51]
	v_mfma_f32_16x16x32_bf16 v[36:39], v[144:147], v[192:195], v[36:39]
	v_mfma_f32_16x16x32_bf16 v[32:35], v[168:171], v[192:195], v[32:35]
	v_mfma_f32_16x16x32_bf16 v[20:23], v[144:147], v[200:203], v[20:23]
	v_mfma_f32_16x16x32_bf16 v[16:19], v[168:171], v[200:203], v[16:19]
	v_mfma_f32_16x16x32_bf16 v[4:7], v[144:147], v[208:211], v[4:7]
	v_mfma_f32_16x16x32_bf16 v[0:3], v[168:171], v[208:211], v[0:3]
	v_mfma_f32_16x16x32_bf16 v[52:55], v[148:151], v[180:183], v[52:55]
	v_mfma_f32_16x16x32_bf16 v[48:51], v[172:175], v[180:183], v[48:51]
	v_mfma_f32_16x16x32_bf16 v[36:39], v[148:151], v[196:199], v[36:39]
	v_mfma_f32_16x16x32_bf16 v[32:35], v[172:175], v[196:199], v[32:35]
	v_mfma_f32_16x16x32_bf16 v[20:23], v[148:151], v[204:207], v[20:23]
	v_mfma_f32_16x16x32_bf16 v[16:19], v[172:175], v[204:207], v[16:19]
	v_mfma_f32_16x16x32_bf16 v[4:7], v[148:151], v[212:215], v[4:7]
	v_mfma_f32_16x16x32_bf16 v[0:3], v[172:175], v[212:215], v[0:3]

	s_barrier
	s_add_i32 s65, s65, 2
	s_add_u32 s24, s24, 0x100
	s_addc_u32 s25, s25, 0
	s_add_u32 s63, s63, 0x100
	s_addc_u32 s64, s64, 0
	s_cmp_gt_u32 s65, 13
	s_cbranch_scc0 .LBB0_1530
	v_lshl_add_u32 v168, s60, 8, v184
	v_lshl_or_b32 v128, s8, 8, v186
	v_ashrrev_i32_e32 v169, 31, v168
	v_ashrrev_i32_e32 v129, 31, v128
	v_lshlrev_b64 v[130:131], 11, v[168:169]
	v_lshl_add_u64 v[130:131], s[34:35], 0, v[130:131]
	v_lshlrev_b64 v[170:171], 1, v[128:129]
	v_lshl_add_u64 v[200:201], v[130:131], 0, v[170:171]
	global_load_dwordx4 v[192:195], v[200:201], off
	global_load_dwordx4 v[196:199], v[200:201], off offset:256
	v_or_b32_e32 v180, 16, v168
	v_or_b32_e32 v176, 32, v168
	v_or_b32_e32 v172, 48, v168
	v_ashrrev_i32_e32 v181, 31, v180
	v_ashrrev_i32_e32 v177, 31, v176
	v_ashrrev_i32_e32 v173, 31, v172
	v_lshlrev_b64 v[128:129], 11, v[180:181]
	v_lshlrev_b64 v[130:131], 11, v[176:177]
	v_lshlrev_b64 v[132:133], 11, v[172:173]
	v_lshl_add_u64 v[128:129], s[34:35], 0, v[128:129]
	v_lshl_add_u64 v[130:131], s[34:35], 0, v[130:131]
	v_lshl_add_u64 v[132:133], s[34:35], 0, v[132:133]
	v_lshl_add_u64 v[182:183], v[128:129], 0, v[170:171]
	v_lshl_add_u64 v[178:179], v[130:131], 0, v[170:171]
	v_lshl_add_u64 v[174:175], v[132:133], 0, v[170:171]
	global_load_dwordx4 v[148:151], v[182:183], off
	global_load_dwordx4 v[144:147], v[182:183], off offset:256
	global_load_dwordx4 v[140:143], v[178:179], off
	global_load_dwordx4 v[136:139], v[178:179], off offset:256
	global_load_dwordx4 v[132:135], v[174:175], off
	global_load_dwordx4 v[128:131], v[174:175], off offset:256
	v_and_b32_e32 v202, 64, v190
	v_xor_b32_e32 v191, 16, v190
	v_add_u32_e32 v202, 64, v202
	v_xor_b32_e32 v203, 32, v190
	v_cmp_lt_i32_e32 vcc, v191, v202
	s_lshl_b32 s24, s8, 2
	s_ashr_i32 s25, s24, 31
	v_cndmask_b32_e32 v191, v190, v191, vcc
	v_cmp_lt_i32_e32 vcc, v203, v202
	v_lshlrev_b32_e32 v191, 2, v191
	s_waitcnt vmcnt(0)
	v_lshlrev_b32_e32 v202, 16, v192
	v_cndmask_b32_e32 v210, v190, v203, vcc
	v_and_b32_e32 v203, 0xffff0000, v192
	v_lshlrev_b32_e32 v192, 16, v193
	v_and_b32_e32 v193, 0xffff0000, v193
	v_lshlrev_b32_e32 v204, 16, v194
	v_and_b32_e32 v205, 0xffff0000, v194
	v_lshlrev_b32_e32 v194, 16, v195
	v_and_b32_e32 v195, 0xffff0000, v195
	v_lshlrev_b32_e32 v206, 16, v196
	v_and_b32_e32 v207, 0xffff0000, v196
	v_lshlrev_b32_e32 v196, 16, v197
	v_and_b32_e32 v197, 0xffff0000, v197
	v_lshlrev_b32_e32 v208, 16, v198
	v_and_b32_e32 v209, 0xffff0000, v198
	v_lshlrev_b32_e32 v198, 16, v199
	v_and_b32_e32 v199, 0xffff0000, v199
	v_pk_add_f32 v[126:127], v[126:127], v[192:193]
	v_pk_add_f32 v[124:125], v[124:125], v[202:203]
	v_pk_add_f32 v[122:123], v[122:123], v[194:195]
	v_pk_add_f32 v[120:121], v[120:121], v[204:205]
	v_pk_add_f32 v[118:119], v[118:119], v[196:197]
	v_pk_add_f32 v[116:117], v[116:117], v[206:207]
	v_pk_add_f32 v[192:193], v[114:115], v[198:199]
	v_pk_add_f32 v[194:195], v[112:113], v[208:209]
	v_cvt_pk_bf16_f32 v112, v124, v125
	v_cvt_pk_bf16_f32 v113, v126, v127
	v_mul_f32_e32 v114, v125, v125
	v_mul_f32_e32 v115, v127, v127
	v_mul_f32_e32 v125, v121, v121
	v_mul_f32_e32 v127, v123, v123
	v_mul_f32_e32 v196, v117, v117
	v_mul_f32_e32 v197, v119, v119
	v_mul_f32_e32 v198, v195, v195
	v_mul_f32_e32 v199, v193, v193
	v_fmac_f32_e32 v114, v124, v124
	v_fmac_f32_e32 v115, v126, v126
	v_fmac_f32_e32 v125, v120, v120
	v_fmac_f32_e32 v127, v122, v122
	v_fmac_f32_e32 v196, v116, v116
	v_fmac_f32_e32 v197, v118, v118
	v_fmac_f32_e32 v198, v194, v194
	v_fmac_f32_e32 v199, v192, v192
	v_add_f32_e32 v114, v114, v115
	v_add_f32_e32 v115, v125, v127
	v_add_f32_e32 v124, v196, v197
	v_add_f32_e32 v125, v198, v199
	v_add_f32_e32 v114, v114, v115
	v_add_f32_e32 v115, v124, v125
	v_add_f32_e32 v124, v114, v115
	ds_bpermute_b32 v125, v191, v124
	v_cvt_pk_bf16_f32 v114, v120, v121
	v_cvt_pk_bf16_f32 v115, v122, v123
	global_store_dwordx4 v[200:201], v[112:115], off
	v_cvt_pk_bf16_f32 v116, v116, v117
	v_cvt_pk_bf16_f32 v117, v118, v119
	s_waitcnt lgkmcnt(0)
	v_add_f32_e32 v113, v124, v125
	v_lshlrev_b32_e32 v112, 2, v210
	ds_bpermute_b32 v114, v112, v113
	v_cvt_pk_bf16_f32 v118, v194, v195
	v_cvt_pk_bf16_f32 v119, v192, v193
	global_store_dwordx4 v[200:201], v[116:119], off offset:256
	s_and_saveexec_b64 s[36:37], s[0:1]
	s_cbranch_execz .LBB0_1533
	s_waitcnt lgkmcnt(0)
	v_add_f32_e32 v113, v113, v114
	v_lshlrev_b64 v[114:115], 6, v[168:169]
	v_lshl_add_u64 v[114:115], s[74:75], 0, v[114:115]
	v_lshl_add_u64 v[114:115], s[24:25], 2, v[114:115]
	s_lshl_b32 s8, s50, 2
	v_lshl_add_u64 v[114:115], v[114:115], 0, s[8:9]
	global_store_dword v[114:115], v113, off

.LBB0_1658:
	ds_read_b128 v[96:99], v169
	ds_read_b128 v[100:103], v169 offset:1024
	ds_read_b128 v[104:107], v169 offset:2048
	ds_read_b128 v[108:111], v169 offset:3072
	ds_read_b128 v[112:115], v170
	ds_read_b128 v[116:119], v170 offset:1024
	ds_read_b128 v[120:123], v170 offset:2048
	ds_read_b128 v[124:127], v170 offset:3072
	s_add_u32 s54, s50, 0xfff80080
	s_addc_u32 s55, s51, -1
	s_cmp_eq_u32 s58, 12
	s_cselect_b32 s89, s3, s57
	s_cselect_b32 s88, s5, s56
	s_cselect_b32 s55, s39, s55
	s_cselect_b32 s54, s43, s54

	s_add_i32 m0, s53, 0xc000
	ds_read_b128 v[146:149], v171
	ds_read_b128 v[150:153], v171 offset:1024
	ds_read_b128 v[154:157], v171 offset:2048
	ds_read_b128 v[158:161], v171 offset:3072
	ds_read_b128 v[174:177], v171 offset:4096
	ds_read_b128 v[178:181], v171 offset:5120
	ds_read_b128 v[182:185], v171 offset:6144
	ds_read_b128 v[186:189], v171 offset:7168
	global_load_lds_dwordx4 v138, s[50:51]

	s_add_i32 m0, s53, 0xe000
	s_nop 0
	global_load_lds_dwordx4 v140, s[50:51]
	s_waitcnt vmcnt(8)
	s_waitcnt lgkmcnt(0)
	s_barrier

	v_mfma_f32_16x16x32_bf16 v[92:95], v[96:99], v[146:149], v[92:95]
	v_mfma_f32_16x16x32_bf16 v[88:91], v[104:107], v[146:149], v[88:91]
	v_mfma_f32_16x16x32_bf16 v[84:87], v[96:99], v[154:157], v[84:87]
	v_mfma_f32_16x16x32_bf16 v[80:83], v[104:107], v[154:157], v[80:83]
	v_mfma_f32_16x16x32_bf16 v[68:71], v[96:99], v[174:177], v[68:71]
	v_mfma_f32_16x16x32_bf16 v[64:67], v[104:107], v[174:177], v[64:67]
	v_mfma_f32_16x16x32_bf16 v[52:55], v[96:99], v[182:185], v[52:55]
	v_mfma_f32_16x16x32_bf16 v[48:51], v[104:107], v[182:185], v[48:51]
	v_mfma_f32_16x16x32_bf16 v[92:95], v[100:103], v[150:153], v[92:95]
	v_mfma_f32_16x16x32_bf16 v[88:91], v[108:111], v[150:153], v[88:91]
	v_mfma_f32_16x16x32_bf16 v[84:87], v[100:103], v[158:161], v[84:87]
	v_mfma_f32_16x16x32_bf16 v[80:83], v[108:111], v[158:161], v[80:83]
	v_mfma_f32_16x16x32_bf16 v[68:71], v[100:103], v[178:181], v[68:71]
	v_mfma_f32_16x16x32_bf16 v[64:67], v[108:111], v[178:181], v[64:67]
	v_mfma_f32_16x16x32_bf16 v[52:55], v[100:103], v[186:189], v[52:55]
	v_mfma_f32_16x16x32_bf16 v[48:51], v[108:111], v[186:189], v[48:51]

	v_mfma_f32_16x16x32_bf16 v[76:79], v[112:115], v[146:149], v[76:79]
	v_mfma_f32_16x16x32_bf16 v[72:75], v[120:123], v[146:149], v[72:75]
	v_mfma_f32_16x16x32_bf16 v[60:63], v[112:115], v[154:157], v[60:63]
	v_mfma_f32_16x16x32_bf16 v[56:59], v[120:123], v[154:157], v[56:59]
	v_mfma_f32_16x16x32_bf16 v[44:47], v[112:115], v[174:177], v[44:47]
	v_mfma_f32_16x16x32_bf16 v[40:43], v[120:123], v[174:177], v[40:43]
	v_mfma_f32_16x16x32_bf16 v[36:39], v[112:115], v[182:185], v[36:39]
	v_mfma_f32_16x16x32_bf16 v[32:35], v[120:123], v[182:185], v[32:35]
	v_mfma_f32_16x16x32_bf16 v[76:79], v[116:119], v[150:153], v[76:79]
	v_mfma_f32_16x16x32_bf16 v[72:75], v[124:127], v[150:153], v[72:75]
	v_mfma_f32_16x16x32_bf16 v[60:63], v[116:119], v[158:161], v[60:63]
	v_mfma_f32_16x16x32_bf16 v[56:59], v[124:127], v[158:161], v[56:59]
	v_mfma_f32_16x16x32_bf16 v[44:47], v[116:119], v[178:181], v[44:47]
	v_mfma_f32_16x16x32_bf16 v[40:43], v[124:127], v[178:181], v[40:43]
	v_mfma_f32_16x16x32_bf16 v[36:39], v[116:119], v[186:189], v[36:39]
	v_mfma_f32_16x16x32_bf16 v[32:35], v[124:127], v[186:189], v[32:35]

	s_barrier
	s_add_i32 s59, s73, s25
	v_lshl_add_u64 v[164:165], s[54:55], 0, v[130:131]
	s_mov_b32 m0, s59
	ds_read_b128 v[96:99], v172 offset:16384
	ds_read_b128 v[100:103], v172 offset:17408
	ds_read_b128 v[104:107], v172 offset:18432
	ds_read_b128 v[108:111], v172 offset:19456
	global_load_lds_dwordx4 v[164:165], off
	s_add_i32 m0, s59, 0x2000
	s_add_u32 s90, s54, 0x40000
	v_lshl_add_u64 v[190:191], s[54:55], 0, v[134:135]
	s_addc_u32 s91, s55, 0
	s_add_i32 s59, s76, s25
	global_load_lds_dwordx4 v[190:191], off

	s_mov_b32 m0, s59
	v_lshl_add_u64 v[192:193], s[88:89], 0, v[128:129]
	global_load_lds_dwordx4 v130, s[90:91]

	s_add_i32 m0, s59, 0x2000
	v_lshl_add_u64 v[194:195], s[88:89], 0, v[132:133]
	global_load_lds_dwordx4 v134, s[90:91]
	s_mov_b32 m0, s53
	s_nop 0
	global_load_lds_dwordx4 v[192:193], off
	s_mov_b32 m0, s60
	s_nop 0
	global_load_lds_dwordx4 v[194:195], off
	s_waitcnt vmcnt(8)
	s_waitcnt lgkmcnt(0)
	s_barrier

	v_mfma_f32_16x16x32_bf16 v[28:31], v[96:99], v[146:149], v[28:31]
	v_mfma_f32_16x16x32_bf16 v[24:27], v[104:107], v[146:149], v[24:27]
	v_mfma_f32_16x16x32_bf16 v[20:23], v[96:99], v[154:157], v[20:23]
	v_mfma_f32_16x16x32_bf16 v[16:19], v[104:107], v[154:157], v[16:19]
	v_mfma_f32_16x16x32_bf16 v[12:15], v[96:99], v[174:177], v[12:15]
	v_mfma_f32_16x16x32_bf16 v[8:11], v[104:107], v[174:177], v[8:11]
	v_mfma_f32_16x16x32_bf16 v[4:7], v[96:99], v[182:185], v[4:7]
	v_mfma_f32_16x16x32_bf16 v[0:3], v[104:107], v[182:185], v[0:3]
	v_mfma_f32_16x16x32_bf16 v[28:31], v[100:103], v[150:153], v[28:31]
	v_mfma_f32_16x16x32_bf16 v[24:27], v[108:111], v[150:153], v[24:27]
	v_mfma_f32_16x16x32_bf16 v[20:23], v[100:103], v[158:161], v[20:23]
	v_mfma_f32_16x16x32_bf16 v[16:19], v[108:111], v[158:161], v[16:19]
	v_mfma_f32_16x16x32_bf16 v[12:15], v[100:103], v[178:181], v[12:15]
	v_mfma_f32_16x16x32_bf16 v[8:11], v[108:111], v[178:181], v[8:11]
	v_mfma_f32_16x16x32_bf16 v[4:7], v[100:103], v[186:189], v[4:7]
	v_mfma_f32_16x16x32_bf16 v[0:3], v[108:111], v[186:189], v[0:3]

	s_barrier
	s_add_i32 s59, 0, 0x18000
	s_add_i32 s87, 0, 0x1c000
	v_add_u32_e32 v108, s59, v167
	v_add_u32_e32 v124, s87, v167
	ds_read_b128 v[96:99], v108
	ds_read_b128 v[100:103], v108 offset:1024
	ds_read_b128 v[104:107], v108 offset:2048
	ds_read_b128 v[108:111], v108 offset:3072
	ds_read_b128 v[112:115], v124
	ds_read_b128 v[116:119], v124 offset:1024
	ds_read_b128 v[120:123], v124 offset:2048
	ds_read_b128 v[124:127], v124 offset:3072
	s_add_u32 s88, s54, 0x80000
	s_addc_u32 s89, s55, 0
	s_mov_b32 m0, s61

	ds_read_b128 v[146:149], v171 offset:32768
	ds_read_b128 v[150:153], v171 offset:33792
	ds_read_b128 v[154:157], v171 offset:34816
	ds_read_b128 v[158:161], v171 offset:35840
	ds_read_b128 v[174:177], v171 offset:36864
	ds_read_b128 v[178:181], v171 offset:37888
	ds_read_b128 v[182:185], v171 offset:38912
	ds_read_b128 v[186:189], v171 offset:39936
	global_load_lds_dwordx4 v130, s[88:89]

	s_mov_b32 m0, s62
	s_nop 0
	global_load_lds_dwordx4 v134, s[88:89]
	s_waitcnt vmcnt(8)
	s_waitcnt lgkmcnt(0)
	s_barrier

	v_mfma_f32_16x16x32_bf16 v[92:95], v[96:99], v[146:149], v[92:95]
	v_mfma_f32_16x16x32_bf16 v[88:91], v[104:107], v[146:149], v[88:91]
	v_mfma_f32_16x16x32_bf16 v[84:87], v[96:99], v[154:157], v[84:87]
	v_mfma_f32_16x16x32_bf16 v[80:83], v[104:107], v[154:157], v[80:83]
	v_mfma_f32_16x16x32_bf16 v[68:71], v[96:99], v[174:177], v[68:71]
	v_mfma_f32_16x16x32_bf16 v[64:67], v[104:107], v[174:177], v[64:67]
	v_mfma_f32_16x16x32_bf16 v[52:55], v[96:99], v[182:185], v[52:55]
	v_mfma_f32_16x16x32_bf16 v[48:51], v[104:107], v[182:185], v[48:51]
	v_mfma_f32_16x16x32_bf16 v[92:95], v[100:103], v[150:153], v[92:95]
	v_mfma_f32_16x16x32_bf16 v[88:91], v[108:111], v[150:153], v[88:91]
	v_mfma_f32_16x16x32_bf16 v[84:87], v[100:103], v[158:161], v[84:87]
	v_mfma_f32_16x16x32_bf16 v[80:83], v[108:111], v[158:161], v[80:83]
	v_mfma_f32_16x16x32_bf16 v[68:71], v[100:103], v[178:181], v[68:71]
	v_mfma_f32_16x16x32_bf16 v[64:67], v[108:111], v[178:181], v[64:67]
	v_mfma_f32_16x16x32_bf16 v[52:55], v[100:103], v[186:189], v[52:55]
	v_mfma_f32_16x16x32_bf16 v[48:51], v[108:111], v[186:189], v[48:51]

	v_mfma_f32_16x16x32_bf16 v[76:79], v[112:115], v[146:149], v[76:79]
	v_mfma_f32_16x16x32_bf16 v[72:75], v[120:123], v[146:149], v[72:75]
	v_mfma_f32_16x16x32_bf16 v[60:63], v[112:115], v[154:157], v[60:63]
	v_mfma_f32_16x16x32_bf16 v[56:59], v[120:123], v[154:157], v[56:59]
	v_mfma_f32_16x16x32_bf16 v[44:47], v[112:115], v[174:177], v[44:47]
	v_mfma_f32_16x16x32_bf16 v[40:43], v[120:123], v[174:177], v[40:43]
	v_mfma_f32_16x16x32_bf16 v[36:39], v[112:115], v[182:185], v[36:39]
	v_mfma_f32_16x16x32_bf16 v[32:35], v[120:123], v[182:185], v[32:35]
	v_mfma_f32_16x16x32_bf16 v[76:79], v[116:119], v[150:153], v[76:79]
	v_mfma_f32_16x16x32_bf16 v[72:75], v[124:127], v[150:153], v[72:75]
	v_mfma_f32_16x16x32_bf16 v[60:63], v[116:119], v[158:161], v[60:63]
	v_mfma_f32_16x16x32_bf16 v[56:59], v[124:127], v[158:161], v[56:59]
	v_mfma_f32_16x16x32_bf16 v[44:47], v[116:119], v[178:181], v[44:47]
	v_mfma_f32_16x16x32_bf16 v[40:43], v[124:127], v[178:181], v[40:43]
	v_mfma_f32_16x16x32_bf16 v[36:39], v[116:119], v[186:189], v[36:39]
	v_mfma_f32_16x16x32_bf16 v[32:35], v[124:127], v[186:189], v[32:35]

	s_barrier
	s_add_i32 s59, s59, s25
	v_lshl_add_u64 v[112:113], v[164:165], 0, s[14:15]
	s_mov_b32 m0, s59
	ds_read_b128 v[96:99], v172 offset:49152
	ds_read_b128 v[100:103], v172 offset:50176
	ds_read_b128 v[104:107], v172 offset:51200
	ds_read_b128 v[108:111], v172 offset:52224
	global_load_lds_dwordx4 v[112:113], off
	s_add_i32 m0, s59, 0x2000
	s_add_u32 s54, s54, 0x40080
	v_lshl_add_u64 v[112:113], v[190:191], 0, s[14:15]
	s_addc_u32 s55, s55, 0
	s_add_i32 s59, s87, s25
	global_load_lds_dwordx4 v[112:113], off

	s_mov_b32 m0, s59
	s_nop 0
	global_load_lds_dwordx4 v130, s[54:55]

	s_add_i32 m0, s59, 0x2000
	s_nop 0
	global_load_lds_dwordx4 v134, s[54:55]
	v_lshl_add_u64 v[112:113], v[192:193], 0, s[14:15]
	s_mov_b32 m0, s63
	s_nop 0
	global_load_lds_dwordx4 v[112:113], off
	v_lshl_add_u64 v[112:113], v[194:195], 0, s[14:15]
	s_mov_b32 m0, s64
	s_nop 0
	global_load_lds_dwordx4 v[112:113], off
	s_waitcnt vmcnt(8)
	s_waitcnt lgkmcnt(0)
	s_barrier

	v_mfma_f32_16x16x32_bf16 v[28:31], v[96:99], v[146:149], v[28:31]
	v_mfma_f32_16x16x32_bf16 v[24:27], v[104:107], v[146:149], v[24:27]
	v_mfma_f32_16x16x32_bf16 v[20:23], v[96:99], v[154:157], v[20:23]
	v_mfma_f32_16x16x32_bf16 v[16:19], v[104:107], v[154:157], v[16:19]
	v_mfma_f32_16x16x32_bf16 v[12:15], v[96:99], v[174:177], v[12:15]
	v_mfma_f32_16x16x32_bf16 v[8:11], v[104:107], v[174:177], v[8:11]
	v_mfma_f32_16x16x32_bf16 v[4:7], v[96:99], v[182:185], v[4:7]
	v_mfma_f32_16x16x32_bf16 v[0:3], v[104:107], v[182:185], v[0:3]
	v_mfma_f32_16x16x32_bf16 v[28:31], v[100:103], v[150:153], v[28:31]
	v_mfma_f32_16x16x32_bf16 v[24:27], v[108:111], v[150:153], v[24:27]
	v_mfma_f32_16x16x32_bf16 v[20:23], v[100:103], v[158:161], v[20:23]
	v_mfma_f32_16x16x32_bf16 v[16:19], v[108:111], v[158:161], v[16:19]
	v_mfma_f32_16x16x32_bf16 v[12:15], v[100:103], v[178:181], v[12:15]
	v_mfma_f32_16x16x32_bf16 v[8:11], v[108:111], v[178:181], v[8:11]
	v_mfma_f32_16x16x32_bf16 v[4:7], v[100:103], v[186:189], v[4:7]
	v_mfma_f32_16x16x32_bf16 v[0:3], v[108:111], v[186:189], v[0:3]

	s_barrier
	s_add_i32 s58, s58, 2
	s_add_u32 s56, s56, 0x100
	s_addc_u32 s57, s57, 0
	s_add_u32 s50, s50, 0x100
	s_addc_u32 s51, s51, 0
	s_cmp_gt_u32 s58, 13
	s_cbranch_scc0 .LBB0_1658
	s_mov_b64 s[50:51], 0
	s_branch .LBB0_1661

.LBB0_1663:
	ds_read_b128 v[146:149], v169
	ds_read_b128 v[150:153], v169 offset:1024
	ds_read_b128 v[154:157], v169 offset:2048
	ds_read_b128 v[158:161], v169 offset:3072
	ds_read_b128 v[174:177], v170
	ds_read_b128 v[178:181], v170 offset:1024
	ds_read_b128 v[182:185], v170 offset:2048
	ds_read_b128 v[186:189], v170 offset:3072
	s_add_u32 s58, s48, 0xfffc0080
	s_addc_u32 s59, s49, -1
	s_cmp_eq_u32 s89, 12
	s_cselect_b64 s[56:57], -1, 0
	s_and_b64 s[54:55], s[56:57], exec
	s_cselect_b32 s55, s39, s86
	s_cselect_b32 s54, s43, s85
	s_cselect_b32 s59, s3, s59
	s_cselect_b32 s58, s5, s58

	s_add_i32 m0, s53, 0xc000
	ds_read_b128 v[190:193], v171
	ds_read_b128 v[194:197], v171 offset:1024
	ds_read_b128 v[198:201], v171 offset:2048
	ds_read_b128 v[202:205], v171 offset:3072
	ds_read_b128 v[206:209], v171 offset:4096
	ds_read_b128 v[210:213], v171 offset:5120
	ds_read_b128 v[214:217], v171 offset:6144
	ds_read_b128 v[218:221], v171 offset:7168
	global_load_lds_dwordx4 v142, s[48:49]

	s_add_i32 m0, s53, 0xe000
	s_nop 0
	global_load_lds_dwordx4 v132, s[48:49]
	s_waitcnt vmcnt(8)
	s_waitcnt lgkmcnt(0)
	s_barrier

	v_mfma_f32_16x16x32_bf16 v[92:95], v[146:149], v[190:193], v[92:95]
	v_mfma_f32_16x16x32_bf16 v[88:91], v[154:157], v[190:193], v[88:91]
	v_mfma_f32_16x16x32_bf16 v[84:87], v[146:149], v[198:201], v[84:87]
	v_mfma_f32_16x16x32_bf16 v[80:83], v[154:157], v[198:201], v[80:83]
	v_mfma_f32_16x16x32_bf16 v[68:71], v[146:149], v[206:209], v[68:71]
	v_mfma_f32_16x16x32_bf16 v[64:67], v[154:157], v[206:209], v[64:67]
	v_mfma_f32_16x16x32_bf16 v[52:55], v[146:149], v[214:217], v[52:55]
	v_mfma_f32_16x16x32_bf16 v[48:51], v[154:157], v[214:217], v[48:51]
	v_mfma_f32_16x16x32_bf16 v[92:95], v[150:153], v[194:197], v[92:95]
	v_mfma_f32_16x16x32_bf16 v[88:91], v[158:161], v[194:197], v[88:91]
	v_mfma_f32_16x16x32_bf16 v[84:87], v[150:153], v[202:205], v[84:87]
	v_mfma_f32_16x16x32_bf16 v[80:83], v[158:161], v[202:205], v[80:83]
	v_mfma_f32_16x16x32_bf16 v[68:71], v[150:153], v[210:213], v[68:71]
	v_mfma_f32_16x16x32_bf16 v[64:67], v[158:161], v[210:213], v[64:67]
	v_mfma_f32_16x16x32_bf16 v[52:55], v[150:153], v[218:221], v[52:55]
	v_mfma_f32_16x16x32_bf16 v[48:51], v[158:161], v[218:221], v[48:51]

	v_mfma_f32_16x16x32_bf16 v[76:79], v[174:177], v[190:193], v[76:79]
	v_mfma_f32_16x16x32_bf16 v[72:75], v[182:185], v[190:193], v[72:75]
	v_mfma_f32_16x16x32_bf16 v[60:63], v[174:177], v[198:201], v[60:63]
	v_mfma_f32_16x16x32_bf16 v[56:59], v[182:185], v[198:201], v[56:59]
	v_mfma_f32_16x16x32_bf16 v[44:47], v[174:177], v[206:209], v[44:47]
	v_mfma_f32_16x16x32_bf16 v[40:43], v[182:185], v[206:209], v[40:43]
	v_mfma_f32_16x16x32_bf16 v[36:39], v[174:177], v[214:217], v[36:39]
	v_mfma_f32_16x16x32_bf16 v[32:35], v[182:185], v[214:217], v[32:35]
	v_mfma_f32_16x16x32_bf16 v[76:79], v[178:181], v[194:197], v[76:79]
	v_mfma_f32_16x16x32_bf16 v[72:75], v[186:189], v[194:197], v[72:75]
	v_mfma_f32_16x16x32_bf16 v[60:63], v[178:181], v[202:205], v[60:63]
	v_mfma_f32_16x16x32_bf16 v[56:59], v[186:189], v[202:205], v[56:59]
	v_mfma_f32_16x16x32_bf16 v[44:47], v[178:181], v[210:213], v[44:47]
	v_mfma_f32_16x16x32_bf16 v[40:43], v[186:189], v[210:213], v[40:43]
	v_mfma_f32_16x16x32_bf16 v[36:39], v[178:181], v[218:221], v[36:39]
	v_mfma_f32_16x16x32_bf16 v[32:35], v[186:189], v[218:221], v[32:35]

	s_barrier
	s_add_i32 s90, s73, s25
	v_lshl_add_u64 v[164:165], s[54:55], 0, v[130:131]
	s_mov_b32 m0, s90
	ds_read_b128 v[190:193], v171 offset:16384
	ds_read_b128 v[194:197], v171 offset:17408
	ds_read_b128 v[198:201], v171 offset:18432
	ds_read_b128 v[202:205], v171 offset:19456
	ds_read_b128 v[206:209], v171 offset:20480
	ds_read_b128 v[210:213], v171 offset:21504
	ds_read_b128 v[214:217], v171 offset:22528
	ds_read_b128 v[218:221], v171 offset:23552
	global_load_lds_dwordx4 v[164:165], off
	s_add_i32 m0, s90, 0x2000
	s_add_u32 s90, s54, 0x40000
	v_lshl_add_u64 v[222:223], s[54:55], 0, v[134:135]
	s_addc_u32 s91, s55, 0
	s_add_i32 s92, s76, s25
	global_load_lds_dwordx4 v[222:223], off

	s_mov_b32 m0, s92
	v_lshl_add_u64 v[226:227], s[58:59], 0, v[132:133]
	global_load_lds_dwordx4 v130, s[90:91]

	s_add_i32 m0, s92, 0x2000
	s_nop 0
	global_load_lds_dwordx4 v134, s[90:91]
	v_lshl_add_u64 v[224:225], s[58:59], 0, v[128:129]
	s_mov_b32 m0, s53
	s_nop 0
	global_load_lds_dwordx4 v[224:225], off
	s_mov_b32 m0, s60
	s_nop 0
	global_load_lds_dwordx4 v[226:227], off
	s_waitcnt vmcnt(8)
	s_waitcnt lgkmcnt(0)
	s_barrier

	v_mfma_f32_16x16x32_bf16 v[28:31], v[146:149], v[190:193], v[28:31]
	v_mfma_f32_16x16x32_bf16 v[24:27], v[154:157], v[190:193], v[24:27]
	v_mfma_f32_16x16x32_bf16 v[20:23], v[146:149], v[198:201], v[20:23]
	v_mfma_f32_16x16x32_bf16 v[16:19], v[154:157], v[198:201], v[16:19]
	v_mfma_f32_16x16x32_bf16 v[12:15], v[146:149], v[206:209], v[12:15]
	v_mfma_f32_16x16x32_bf16 v[8:11], v[154:157], v[206:209], v[8:11]
	v_mfma_f32_16x16x32_bf16 v[4:7], v[146:149], v[214:217], v[4:7]
	v_mfma_f32_16x16x32_bf16 v[0:3], v[154:157], v[214:217], v[0:3]
	v_mfma_f32_16x16x32_bf16 v[28:31], v[150:153], v[194:197], v[28:31]
	v_mfma_f32_16x16x32_bf16 v[24:27], v[158:161], v[194:197], v[24:27]
	v_mfma_f32_16x16x32_bf16 v[20:23], v[150:153], v[202:205], v[20:23]
	v_mfma_f32_16x16x32_bf16 v[16:19], v[158:161], v[202:205], v[16:19]
	v_mfma_f32_16x16x32_bf16 v[12:15], v[150:153], v[210:213], v[12:15]
	v_mfma_f32_16x16x32_bf16 v[8:11], v[158:161], v[210:213], v[8:11]
	v_mfma_f32_16x16x32_bf16 v[4:7], v[150:153], v[218:221], v[4:7]
	v_mfma_f32_16x16x32_bf16 v[0:3], v[158:161], v[218:221], v[0:3]

	v_mfma_f32_16x16x32_bf16 v[124:127], v[174:177], v[190:193], v[124:127]
	v_mfma_f32_16x16x32_bf16 v[120:123], v[182:185], v[190:193], v[120:123]
	v_mfma_f32_16x16x32_bf16 v[116:119], v[174:177], v[198:201], v[116:119]
	v_mfma_f32_16x16x32_bf16 v[112:115], v[182:185], v[198:201], v[112:115]
	v_mfma_f32_16x16x32_bf16 v[108:111], v[174:177], v[206:209], v[108:111]
	v_mfma_f32_16x16x32_bf16 v[104:107], v[182:185], v[206:209], v[104:107]
	v_mfma_f32_16x16x32_bf16 v[100:103], v[174:177], v[214:217], v[100:103]
	v_mfma_f32_16x16x32_bf16 v[96:99], v[182:185], v[214:217], v[96:99]
	v_mfma_f32_16x16x32_bf16 v[124:127], v[178:181], v[194:197], v[124:127]
	v_mfma_f32_16x16x32_bf16 v[120:123], v[186:189], v[194:197], v[120:123]
	v_mfma_f32_16x16x32_bf16 v[116:119], v[178:181], v[202:205], v[116:119]
	v_mfma_f32_16x16x32_bf16 v[112:115], v[186:189], v[202:205], v[112:115]
	v_mfma_f32_16x16x32_bf16 v[108:111], v[178:181], v[210:213], v[108:111]
	v_mfma_f32_16x16x32_bf16 v[104:107], v[186:189], v[210:213], v[104:107]
	v_mfma_f32_16x16x32_bf16 v[100:103], v[178:181], v[218:221], v[100:103]
	v_mfma_f32_16x16x32_bf16 v[96:99], v[186:189], v[218:221], v[96:99]

	s_barrier
	s_add_i32 s90, 0, 0x18000
	s_add_i32 s91, 0, 0x1c000
	v_add_u32_e32 v158, s90, v167
	v_add_u32_e32 v162, s91, v167
	ds_read_b128 v[146:149], v158
	ds_read_b128 v[150:153], v158 offset:1024
	ds_read_b128 v[154:157], v158 offset:2048
	ds_read_b128 v[158:161], v158 offset:3072
	ds_read_b128 v[174:177], v162
	ds_read_b128 v[178:181], v162 offset:1024
	ds_read_b128 v[182:185], v162 offset:2048
	ds_read_b128 v[186:189], v162 offset:3072
	s_and_b64 s[56:57], s[40:41], s[56:57]
	s_and_b64 vcc, s[56:57], s[50:51]
	s_add_u32 s58, s58, 0x40000
	s_addc_u32 s59, s59, 0
	s_and_b64 s[56:57], vcc, exec
	s_mov_b32 m0, s61
	v_cndmask_b32_e32 v162, v128, v130, vcc
	s_cselect_b32 s57, s88, s59
	s_cselect_b32 s56, s87, s58
	ds_read_b128 v[190:193], v171 offset:32768
	ds_read_b128 v[194:197], v171 offset:33792
	ds_read_b128 v[198:201], v171 offset:34816
	ds_read_b128 v[202:205], v171 offset:35840
	ds_read_b128 v[206:209], v171 offset:36864
	ds_read_b128 v[210:213], v171 offset:37888
	ds_read_b128 v[214:217], v171 offset:38912
	ds_read_b128 v[218:221], v171 offset:39936
	v_cndmask_b32_e32 v166, v132, v134, vcc
	global_load_lds_dwordx4 v162, s[56:57]
	s_mov_b32 m0, s62
	s_nop 0
	global_load_lds_dwordx4 v166, s[56:57]
	s_waitcnt vmcnt(8)
	s_waitcnt lgkmcnt(0)
	s_barrier

	v_mfma_f32_16x16x32_bf16 v[92:95], v[146:149], v[190:193], v[92:95]
	v_mfma_f32_16x16x32_bf16 v[88:91], v[154:157], v[190:193], v[88:91]
	v_mfma_f32_16x16x32_bf16 v[84:87], v[146:149], v[198:201], v[84:87]
	v_mfma_f32_16x16x32_bf16 v[80:83], v[154:157], v[198:201], v[80:83]
	v_mfma_f32_16x16x32_bf16 v[68:71], v[146:149], v[206:209], v[68:71]
	v_mfma_f32_16x16x32_bf16 v[64:67], v[154:157], v[206:209], v[64:67]
	v_mfma_f32_16x16x32_bf16 v[52:55], v[146:149], v[214:217], v[52:55]
	v_mfma_f32_16x16x32_bf16 v[48:51], v[154:157], v[214:217], v[48:51]
	v_mfma_f32_16x16x32_bf16 v[92:95], v[150:153], v[194:197], v[92:95]
	v_mfma_f32_16x16x32_bf16 v[88:91], v[158:161], v[194:197], v[88:91]
	v_mfma_f32_16x16x32_bf16 v[84:87], v[150:153], v[202:205], v[84:87]
	v_mfma_f32_16x16x32_bf16 v[80:83], v[158:161], v[202:205], v[80:83]
	v_mfma_f32_16x16x32_bf16 v[68:71], v[150:153], v[210:213], v[68:71]
	v_mfma_f32_16x16x32_bf16 v[64:67], v[158:161], v[210:213], v[64:67]
	v_mfma_f32_16x16x32_bf16 v[52:55], v[150:153], v[218:221], v[52:55]
	v_mfma_f32_16x16x32_bf16 v[48:51], v[158:161], v[218:221], v[48:51]

	v_mfma_f32_16x16x32_bf16 v[76:79], v[174:177], v[190:193], v[76:79]
	v_mfma_f32_16x16x32_bf16 v[72:75], v[182:185], v[190:193], v[72:75]
	v_mfma_f32_16x16x32_bf16 v[60:63], v[174:177], v[198:201], v[60:63]
	v_mfma_f32_16x16x32_bf16 v[56:59], v[182:185], v[198:201], v[56:59]
	v_mfma_f32_16x16x32_bf16 v[44:47], v[174:177], v[206:209], v[44:47]
	v_mfma_f32_16x16x32_bf16 v[40:43], v[182:185], v[206:209], v[40:43]
	v_mfma_f32_16x16x32_bf16 v[36:39], v[174:177], v[214:217], v[36:39]
	v_mfma_f32_16x16x32_bf16 v[32:35], v[182:185], v[214:217], v[32:35]
	v_mfma_f32_16x16x32_bf16 v[76:79], v[178:181], v[194:197], v[76:79]
	v_mfma_f32_16x16x32_bf16 v[72:75], v[186:189], v[194:197], v[72:75]
	v_mfma_f32_16x16x32_bf16 v[60:63], v[178:181], v[202:205], v[60:63]
	v_mfma_f32_16x16x32_bf16 v[56:59], v[186:189], v[202:205], v[56:59]
	v_mfma_f32_16x16x32_bf16 v[44:47], v[178:181], v[210:213], v[44:47]
	v_mfma_f32_16x16x32_bf16 v[40:43], v[186:189], v[210:213], v[40:43]
	v_mfma_f32_16x16x32_bf16 v[36:39], v[178:181], v[218:221], v[36:39]
	v_mfma_f32_16x16x32_bf16 v[32:35], v[186:189], v[218:221], v[32:35]

	s_barrier
	s_add_i32 s56, s90, s25
	v_lshl_add_u64 v[164:165], v[164:165], 0, s[14:15]
	s_mov_b32 m0, s56
	ds_read_b128 v[190:193], v171 offset:49152
	ds_read_b128 v[194:197], v171 offset:50176
	ds_read_b128 v[198:201], v171 offset:51200
	ds_read_b128 v[202:205], v171 offset:52224
	ds_read_b128 v[206:209], v171 offset:53248
	ds_read_b128 v[210:213], v171 offset:54272
	ds_read_b128 v[214:217], v171 offset:55296
	ds_read_b128 v[218:221], v171 offset:56320
	global_load_lds_dwordx4 v[164:165], off
	s_add_i32 m0, s56, 0x2000
	s_add_u32 s54, s54, 0x40080
	v_lshl_add_u64 v[164:165], v[222:223], 0, s[14:15]
	s_addc_u32 s55, s55, 0
	s_add_i32 s56, s91, s25
	global_load_lds_dwordx4 v[164:165], off

	s_mov_b32 m0, s56
	s_nop 0
	global_load_lds_dwordx4 v130, s[54:55]

	s_add_i32 m0, s56, 0x2000
	s_nop 0
	global_load_lds_dwordx4 v134, s[54:55]
	v_lshl_add_u64 v[164:165], v[224:225], 0, s[14:15]
	s_mov_b32 m0, s63
	s_nop 0
	global_load_lds_dwordx4 v[164:165], off
	v_lshl_add_u64 v[164:165], v[226:227], 0, s[14:15]
	s_mov_b32 m0, s64
	s_nop 0
	global_load_lds_dwordx4 v[164:165], off
	s_waitcnt vmcnt(8)
	s_waitcnt lgkmcnt(0)
	s_barrier

	v_mfma_f32_16x16x32_bf16 v[28:31], v[146:149], v[190:193], v[28:31]
	v_mfma_f32_16x16x32_bf16 v[24:27], v[154:157], v[190:193], v[24:27]
	v_mfma_f32_16x16x32_bf16 v[20:23], v[146:149], v[198:201], v[20:23]
	v_mfma_f32_16x16x32_bf16 v[16:19], v[154:157], v[198:201], v[16:19]
	v_mfma_f32_16x16x32_bf16 v[12:15], v[146:149], v[206:209], v[12:15]
	v_mfma_f32_16x16x32_bf16 v[8:11], v[154:157], v[206:209], v[8:11]
	v_mfma_f32_16x16x32_bf16 v[4:7], v[146:149], v[214:217], v[4:7]
	v_mfma_f32_16x16x32_bf16 v[0:3], v[154:157], v[214:217], v[0:3]
	v_mfma_f32_16x16x32_bf16 v[28:31], v[150:153], v[194:197], v[28:31]
	v_mfma_f32_16x16x32_bf16 v[24:27], v[158:161], v[194:197], v[24:27]
	v_mfma_f32_16x16x32_bf16 v[20:23], v[150:153], v[202:205], v[20:23]
	v_mfma_f32_16x16x32_bf16 v[16:19], v[158:161], v[202:205], v[16:19]
	v_mfma_f32_16x16x32_bf16 v[12:15], v[150:153], v[210:213], v[12:15]
	v_mfma_f32_16x16x32_bf16 v[8:11], v[158:161], v[210:213], v[8:11]
	v_mfma_f32_16x16x32_bf16 v[4:7], v[150:153], v[218:221], v[4:7]
	v_mfma_f32_16x16x32_bf16 v[0:3], v[158:161], v[218:221], v[0:3]

	v_mfma_f32_16x16x32_bf16 v[124:127], v[174:177], v[190:193], v[124:127]
	v_mfma_f32_16x16x32_bf16 v[120:123], v[182:185], v[190:193], v[120:123]
	v_mfma_f32_16x16x32_bf16 v[116:119], v[174:177], v[198:201], v[116:119]
	v_mfma_f32_16x16x32_bf16 v[112:115], v[182:185], v[198:201], v[112:115]
	v_mfma_f32_16x16x32_bf16 v[108:111], v[174:177], v[206:209], v[108:111]
	v_mfma_f32_16x16x32_bf16 v[104:107], v[182:185], v[206:209], v[104:107]
	v_mfma_f32_16x16x32_bf16 v[100:103], v[174:177], v[214:217], v[100:103]
	v_mfma_f32_16x16x32_bf16 v[96:99], v[182:185], v[214:217], v[96:99]
	v_mfma_f32_16x16x32_bf16 v[124:127], v[178:181], v[194:197], v[124:127]
	v_mfma_f32_16x16x32_bf16 v[120:123], v[186:189], v[194:197], v[120:123]
	v_mfma_f32_16x16x32_bf16 v[116:119], v[178:181], v[202:205], v[116:119]
	v_mfma_f32_16x16x32_bf16 v[112:115], v[186:189], v[202:205], v[112:115]
	v_mfma_f32_16x16x32_bf16 v[108:111], v[178:181], v[210:213], v[108:111]
	v_mfma_f32_16x16x32_bf16 v[104:107], v[186:189], v[210:213], v[104:107]
	v_mfma_f32_16x16x32_bf16 v[100:103], v[178:181], v[218:221], v[100:103]
	v_mfma_f32_16x16x32_bf16 v[96:99], v[186:189], v[218:221], v[96:99]

	s_barrier
	s_add_i32 s89, s89, 2
	s_add_u32 s48, s48, 0x100
	s_addc_u32 s49, s49, 0
	s_add_u32 s85, s85, 0x100
	s_addc_u32 s86, s86, 0
	s_cmp_gt_u32 s89, 13
	s_cbranch_scc0 .LBB0_1663

.LBB0_1747:
	s_ashr_i32 s49, s48, 31
	s_lshl_b64 s[6:7], s[48:49], 11
	s_add_u32 s56, s34, s6
	s_addc_u32 s57, s35, s7
	s_and_b64 s[6:7], s[50:51], exec
	s_cselect_b32 s3, s57, s9
	s_cselect_b32 s5, s56, s8
	s_ashr_i32 s55, s54, 31
	s_lshl_b64 s[6:7], s[54:55], 11
	s_add_u32 s58, s45, s6
	s_addc_u32 s59, s47, s7
	s_and_b64 s[6:7], s[50:51], exec
	s_cselect_b32 s49, s59, s61
	s_cselect_b32 s52, s58, s60
	s_cmp_lg_u32 s62, 0
	s_cselect_b64 s[6:7], -1, 0
	s_add_u32 s53, s60, 0x100
	s_addc_u32 s55, s61, 0
	s_cmp_eq_u32 s62, 0
	s_cbranch_scc1 .LBB0_1800
	s_add_u32 s64, s8, 0x100
	s_addc_u32 s65, s9, 0
	s_add_u32 s60, s60, 0x80080
	v_mov_b32_e32 v14, 0
	s_addc_u32 s61, s61, 0
	s_mov_b32 s66, -2
	v_mov_b32_e32 v15, v14
	v_mov_b32_e32 v16, v14
	v_mov_b32_e32 v17, v14
	v_mov_b32_e32 v22, v14
	v_mov_b32_e32 v23, v14
	v_mov_b32_e32 v24, v14
	v_mov_b32_e32 v25, v14
	v_mov_b32_e32 v34, v14
	v_mov_b32_e32 v35, v14
	s_waitcnt vmcnt(0)
	v_mov_b64_e32 v[36:37], 0
	v_mov_b64_e32 v[42:43], 0
	v_mov_b64_e32 v[44:45], 0
	v_mov_b64_e32 v[50:51], 0
	v_mov_b64_e32 v[52:53], 0
	v_mov_b64_e32 v[54:55], 0
	v_mov_b64_e32 v[56:57], 0
	v_mov_b64_e32 v[58:59], 0
	v_mov_b64_e32 v[60:61], 0
	v_mov_b64_e32 v[62:63], 0
	v_mov_b64_e32 v[64:65], 0
	v_mov_b64_e32 v[66:67], 0
	v_mov_b64_e32 v[68:69], 0
	v_mov_b64_e32 v[70:71], 0
	v_mov_b64_e32 v[72:73], 0
	v_mov_b64_e32 v[74:75], 0
	v_mov_b64_e32 v[76:77], 0
	v_mov_b64_e32 v[78:79], 0
	v_mov_b64_e32 v[80:81], 0
	v_mov_b64_e32 v[82:83], 0
	v_mov_b64_e32 v[84:85], 0
	v_mov_b64_e32 v[86:87], 0
	v_mov_b64_e32 v[88:89], 0
	v_mov_b64_e32 v[90:91], 0
	v_mov_b64_e32 v[92:93], 0
	v_mov_b64_e32 v[94:95], 0
	v_mov_b64_e32 v[96:97], 0
	v_mov_b64_e32 v[98:99], 0
	v_mov_b64_e32 v[100:101], 0
	v_mov_b64_e32 v[102:103], 0
	v_mov_b64_e32 v[104:105], 0
	v_mov_b64_e32 v[106:107], 0
	v_mov_b64_e32 v[108:109], 0
	v_mov_b64_e32 v[110:111], 0
	v_mov_b64_e32 v[112:113], 0
	v_mov_b64_e32 v[114:115], 0
	v_mov_b64_e32 v[116:117], 0
	v_mov_b64_e32 v[118:119], 0
	v_mov_b64_e32 v[120:121], 0
	v_mov_b64_e32 v[122:123], 0
	v_mov_b64_e32 v[124:125], 0
	v_mov_b64_e32 v[126:127], 0
	v_mov_b64_e32 v[128:129], 0
	s_nop 0
	s_nop 0
	s_nop 0
	s_nop 0
	s_nop 0
	s_nop 0
	s_nop 0
	s_nop 0
	s_nop 0
	s_nop 0
	s_nop 0
	s_nop 0
.LBB0_1749:
	ds_read_b128 v[2:5], v243
	ds_read_b128 v[6:9], v243 offset:1024
	ds_read_b128 v[10:13], v243 offset:2048
	ds_read_b128 v[18:21], v243 offset:3072
	ds_read_b128 v[26:29], v244
	ds_read_b128 v[30:33], v244 offset:1024
	ds_read_b128 v[38:41], v244 offset:2048
	ds_read_b128 v[46:49], v244 offset:3072
	s_add_u32 s62, s60, 0xfff80080
	s_addc_u32 s63, s61, -1
	s_cmp_eq_u32 s66, 12
	s_cselect_b32 s69, s3, s65
	s_cselect_b32 s68, s5, s64
	s_cselect_b32 s63, s49, s63
	s_cselect_b32 s62, s52, s62

	s_add_i32 m0, s71, 0xc000
	ds_read_b128 v[130:133], v245
	ds_read_b128 v[134:137], v245 offset:1024
	ds_read_b128 v[138:141], v245 offset:2048
	ds_read_b128 v[142:145], v245 offset:3072
	ds_read_b128 v[146:149], v245 offset:4096
	ds_read_b128 v[150:153], v245 offset:5120
	ds_read_b128 v[154:157], v245 offset:6144
	ds_read_b128 v[158:161], v245 offset:7168
	global_load_lds_dwordx4 v192, s[60:61]

	s_add_i32 m0, s71, 0xe000
	s_nop 0
	global_load_lds_dwordx4 v194, s[60:61]
	s_waitcnt vmcnt(8)
	s_waitcnt lgkmcnt(0)
	s_barrier

	v_mfma_f32_16x16x32_bf16 v[126:129], v[2:5], v[130:133], v[126:129]
	v_mfma_f32_16x16x32_bf16 v[122:125], v[10:13], v[130:133], v[122:125]
	v_mfma_f32_16x16x32_bf16 v[118:121], v[2:5], v[138:141], v[118:121]
	v_mfma_f32_16x16x32_bf16 v[114:117], v[10:13], v[138:141], v[114:117]
	v_mfma_f32_16x16x32_bf16 v[110:113], v[2:5], v[146:149], v[110:113]
	v_mfma_f32_16x16x32_bf16 v[106:109], v[10:13], v[146:149], v[106:109]
	v_mfma_f32_16x16x32_bf16 v[2:5], v[2:5], v[154:157], v[102:105]
	v_mfma_f32_16x16x32_bf16 v[126:129], v[6:9], v[134:137], v[126:129]
	v_mfma_f32_16x16x32_bf16 v[122:125], v[18:21], v[134:137], v[122:125]
	v_mfma_f32_16x16x32_bf16 v[118:121], v[6:9], v[142:145], v[118:121]
	v_mfma_f32_16x16x32_bf16 v[114:117], v[18:21], v[142:145], v[114:117]
	v_mfma_f32_16x16x32_bf16 v[110:113], v[6:9], v[150:153], v[110:113]
	v_mfma_f32_16x16x32_bf16 v[106:109], v[18:21], v[150:153], v[106:109]
	v_mfma_f32_16x16x32_bf16 v[2:5], v[6:9], v[158:161], v[2:5]
	v_mfma_f32_16x16x32_bf16 v[6:9], v[10:13], v[154:157], v[98:101]
	v_mfma_f32_16x16x32_bf16 v[6:9], v[18:21], v[158:161], v[6:9]

	v_mfma_f32_16x16x32_bf16 v[10:13], v[26:29], v[130:133], v[94:97]
	v_mfma_f32_16x16x32_bf16 v[86:89], v[26:29], v[138:141], v[86:89]
	v_mfma_f32_16x16x32_bf16 v[82:85], v[38:41], v[138:141], v[82:85]
	v_mfma_f32_16x16x32_bf16 v[78:81], v[26:29], v[146:149], v[78:81]
	v_mfma_f32_16x16x32_bf16 v[74:77], v[38:41], v[146:149], v[74:77]
	v_mfma_f32_16x16x32_bf16 v[26:29], v[26:29], v[154:157], v[70:73]
	v_mfma_f32_16x16x32_bf16 v[10:13], v[30:33], v[134:137], v[10:13]
	v_mfma_f32_16x16x32_bf16 v[18:21], v[38:41], v[130:133], v[90:93]
	v_mfma_f32_16x16x32_bf16 v[86:89], v[30:33], v[142:145], v[86:89]
	v_mfma_f32_16x16x32_bf16 v[82:85], v[46:49], v[142:145], v[82:85]
	v_mfma_f32_16x16x32_bf16 v[78:81], v[30:33], v[150:153], v[78:81]
	v_mfma_f32_16x16x32_bf16 v[74:77], v[46:49], v[150:153], v[74:77]
	v_mfma_f32_16x16x32_bf16 v[26:29], v[30:33], v[158:161], v[26:29]
	v_mfma_f32_16x16x32_bf16 v[30:33], v[38:41], v[154:157], v[66:69]
	v_mfma_f32_16x16x32_bf16 v[18:21], v[46:49], v[134:137], v[18:21]
	v_mfma_f32_16x16x32_bf16 v[30:33], v[46:49], v[158:161], v[30:33]

	s_barrier
	s_add_i32 s67, s74, s70
	v_lshl_add_u64 v[178:179], s[62:63], 0, v[184:185]
	s_mov_b32 m0, s67
	ds_read_b128 v[38:41], v246 offset:16384
	ds_read_b128 v[46:49], v246 offset:17408
	ds_read_b128 v[66:69], v246 offset:18432
	ds_read_b128 v[70:73], v246 offset:19456
	global_load_lds_dwordx4 v[178:179], off
	s_add_i32 m0, s67, 0x2000
	s_add_u32 s72, s62, 0x40000
	v_lshl_add_u64 v[180:181], s[62:63], 0, v[188:189]
	s_addc_u32 s73, s63, 0
	s_add_i32 s67, s75, s70
	global_load_lds_dwordx4 v[180:181], off

	s_mov_b32 m0, s67
	v_lshl_add_u64 v[198:199], s[68:69], 0, v[182:183]
	global_load_lds_dwordx4 v184, s[72:73]

	s_add_i32 m0, s67, 0x2000
	v_lshl_add_u64 v[200:201], s[68:69], 0, v[186:187]
	global_load_lds_dwordx4 v188, s[72:73]
	s_mov_b32 m0, s71
	s_nop 0
	global_load_lds_dwordx4 v[198:199], off
	s_mov_b32 m0, s76
	s_nop 0
	global_load_lds_dwordx4 v[200:201], off
	s_waitcnt vmcnt(8)
	s_waitcnt lgkmcnt(0)
	s_barrier

	v_mfma_f32_16x16x32_bf16 v[62:65], v[38:41], v[130:133], v[62:65]
	v_mfma_f32_16x16x32_bf16 v[58:61], v[66:69], v[130:133], v[58:61]
	v_mfma_f32_16x16x32_bf16 v[54:57], v[38:41], v[138:141], v[54:57]
	v_mfma_f32_16x16x32_bf16 v[50:53], v[66:69], v[138:141], v[50:53]
	v_mfma_f32_16x16x32_bf16 v[42:45], v[38:41], v[146:149], v[42:45]
	v_mfma_f32_16x16x32_bf16 v[34:37], v[66:69], v[146:149], v[34:37]
	v_mfma_f32_16x16x32_bf16 v[22:25], v[38:41], v[154:157], v[22:25]
	v_mfma_f32_16x16x32_bf16 v[14:17], v[66:69], v[154:157], v[14:17]
	v_mfma_f32_16x16x32_bf16 v[62:65], v[46:49], v[134:137], v[62:65]
	v_mfma_f32_16x16x32_bf16 v[58:61], v[70:73], v[134:137], v[58:61]
	v_mfma_f32_16x16x32_bf16 v[54:57], v[46:49], v[142:145], v[54:57]
	v_mfma_f32_16x16x32_bf16 v[50:53], v[70:73], v[142:145], v[50:53]
	v_mfma_f32_16x16x32_bf16 v[42:45], v[46:49], v[150:153], v[42:45]
	v_mfma_f32_16x16x32_bf16 v[34:37], v[70:73], v[150:153], v[34:37]
	v_mfma_f32_16x16x32_bf16 v[22:25], v[46:49], v[158:161], v[22:25]
	v_mfma_f32_16x16x32_bf16 v[14:17], v[70:73], v[158:161], v[14:17]

	s_barrier
	s_add_i32 s67, 0, 0x18000
	v_add_u32_e32 v1, s67, v241
	s_add_i32 s72, 0, 0x1c000
	ds_read_b128 v[38:41], v1
	ds_read_b128 v[46:49], v1 offset:1024
	ds_read_b128 v[66:69], v1 offset:2048
	ds_read_b128 v[70:73], v1 offset:3072
	v_add_u32_e32 v1, s72, v241
	ds_read_b128 v[130:133], v1
	ds_read_b128 v[134:137], v1 offset:1024
	ds_read_b128 v[138:141], v1 offset:2048
	ds_read_b128 v[142:145], v1 offset:3072
	s_add_u32 s68, s62, 0x80000
	s_addc_u32 s69, s63, 0
	s_mov_b32 m0, s77

	ds_read_b128 v[146:149], v245 offset:32768
	ds_read_b128 v[150:153], v245 offset:33792
	ds_read_b128 v[154:157], v245 offset:34816
	ds_read_b128 v[158:161], v245 offset:35840
	ds_read_b128 v[162:165], v245 offset:36864
	ds_read_b128 v[166:169], v245 offset:37888
	ds_read_b128 v[170:173], v245 offset:38912
	ds_read_b128 v[174:177], v245 offset:39936
	global_load_lds_dwordx4 v184, s[68:69]

	s_mov_b32 m0, s78
	s_nop 0
	global_load_lds_dwordx4 v188, s[68:69]
	s_waitcnt vmcnt(8)
	s_waitcnt lgkmcnt(0)
	s_barrier

	v_mfma_f32_16x16x32_bf16 v[90:93], v[38:41], v[146:149], v[126:129]
	v_mfma_f32_16x16x32_bf16 v[126:129], v[46:49], v[150:153], v[90:93]
	v_mfma_f32_16x16x32_bf16 v[90:93], v[66:69], v[146:149], v[122:125]
	v_mfma_f32_16x16x32_bf16 v[122:125], v[70:73], v[150:153], v[90:93]
	v_mfma_f32_16x16x32_bf16 v[90:93], v[38:41], v[154:157], v[118:121]
	v_mfma_f32_16x16x32_bf16 v[118:121], v[46:49], v[158:161], v[90:93]
	v_mfma_f32_16x16x32_bf16 v[90:93], v[66:69], v[154:157], v[114:117]
	v_mfma_f32_16x16x32_bf16 v[114:117], v[70:73], v[158:161], v[90:93]
	v_mfma_f32_16x16x32_bf16 v[90:93], v[38:41], v[162:165], v[110:113]
	v_mfma_f32_16x16x32_bf16 v[2:5], v[38:41], v[170:173], v[2:5]
	v_mfma_f32_16x16x32_bf16 v[110:113], v[46:49], v[166:169], v[90:93]
	v_mfma_f32_16x16x32_bf16 v[90:93], v[66:69], v[162:165], v[106:109]
	v_mfma_f32_16x16x32_bf16 v[102:105], v[46:49], v[174:177], v[2:5]
	v_mfma_f32_16x16x32_bf16 v[2:5], v[66:69], v[170:173], v[6:9]
	v_mfma_f32_16x16x32_bf16 v[106:109], v[70:73], v[166:169], v[90:93]
	v_mfma_f32_16x16x32_bf16 v[98:101], v[70:73], v[174:177], v[2:5]

	v_mfma_f32_16x16x32_bf16 v[2:5], v[130:133], v[146:149], v[10:13]
	v_mfma_f32_16x16x32_bf16 v[94:97], v[134:137], v[150:153], v[2:5]
	v_mfma_f32_16x16x32_bf16 v[2:5], v[138:141], v[146:149], v[18:21]
	v_mfma_f32_16x16x32_bf16 v[90:93], v[142:145], v[150:153], v[2:5]
	v_mfma_f32_16x16x32_bf16 v[2:5], v[130:133], v[154:157], v[86:89]
	v_mfma_f32_16x16x32_bf16 v[86:89], v[134:137], v[158:161], v[2:5]
	v_mfma_f32_16x16x32_bf16 v[2:5], v[138:141], v[154:157], v[82:85]
	v_mfma_f32_16x16x32_bf16 v[82:85], v[142:145], v[158:161], v[2:5]
	v_mfma_f32_16x16x32_bf16 v[2:5], v[130:133], v[162:165], v[78:81]
	v_mfma_f32_16x16x32_bf16 v[78:81], v[134:137], v[166:169], v[2:5]
	v_mfma_f32_16x16x32_bf16 v[2:5], v[138:141], v[162:165], v[74:77]
	v_mfma_f32_16x16x32_bf16 v[74:77], v[142:145], v[166:169], v[2:5]
	v_mfma_f32_16x16x32_bf16 v[2:5], v[130:133], v[170:173], v[26:29]
	v_mfma_f32_16x16x32_bf16 v[70:73], v[134:137], v[174:177], v[2:5]
	v_mfma_f32_16x16x32_bf16 v[2:5], v[138:141], v[170:173], v[30:33]
	v_mfma_f32_16x16x32_bf16 v[66:69], v[142:145], v[174:177], v[2:5]

	s_barrier
	s_add_i32 s67, s67, s70
	v_lshl_add_u64 v[26:27], v[178:179], 0, s[38:39]
	s_mov_b32 m0, s67
	s_nop 1
	ds_read_b128 v[2:5], v246 offset:49152
	ds_read_b128 v[6:9], v246 offset:50176
	ds_read_b128 v[10:13], v246 offset:51200
	ds_read_b128 v[18:21], v246 offset:52224
	global_load_lds_dwordx4 v[26:27], off
	s_add_i32 m0, s67, 0x2000
	s_add_u32 s62, s62, 0x40080
	v_lshl_add_u64 v[26:27], v[180:181], 0, s[38:39]
	s_addc_u32 s63, s63, 0
	s_add_i32 s67, s72, s70
	global_load_lds_dwordx4 v[26:27], off

	s_mov_b32 m0, s67
	s_nop 0
	global_load_lds_dwordx4 v184, s[62:63]

	s_add_i32 m0, s67, 0x2000
	s_nop 0
	global_load_lds_dwordx4 v188, s[62:63]
	v_lshl_add_u64 v[26:27], v[198:199], 0, s[38:39]
	s_mov_b32 m0, s79
	s_nop 0
	global_load_lds_dwordx4 v[26:27], off
	v_lshl_add_u64 v[26:27], v[200:201], 0, s[38:39]
	s_mov_b32 m0, s80
	s_nop 0
	global_load_lds_dwordx4 v[26:27], off
	s_waitcnt vmcnt(8)
	s_waitcnt lgkmcnt(0)
	s_barrier

	v_mfma_f32_16x16x32_bf16 v[26:29], v[2:5], v[146:149], v[62:65]
	v_mfma_f32_16x16x32_bf16 v[62:65], v[6:9], v[150:153], v[26:29]
	v_mfma_f32_16x16x32_bf16 v[26:29], v[10:13], v[146:149], v[58:61]
	v_mfma_f32_16x16x32_bf16 v[58:61], v[18:21], v[150:153], v[26:29]
	v_mfma_f32_16x16x32_bf16 v[26:29], v[2:5], v[154:157], v[54:57]
	v_mfma_f32_16x16x32_bf16 v[54:57], v[6:9], v[158:161], v[26:29]
	v_mfma_f32_16x16x32_bf16 v[26:29], v[10:13], v[154:157], v[50:53]
	v_mfma_f32_16x16x32_bf16 v[50:53], v[18:21], v[158:161], v[26:29]
	v_mfma_f32_16x16x32_bf16 v[26:29], v[2:5], v[162:165], v[42:45]
	v_mfma_f32_16x16x32_bf16 v[2:5], v[2:5], v[170:173], v[22:25]
	v_mfma_f32_16x16x32_bf16 v[42:45], v[6:9], v[166:169], v[26:29]
	v_mfma_f32_16x16x32_bf16 v[26:29], v[10:13], v[162:165], v[34:37]
	v_mfma_f32_16x16x32_bf16 v[22:25], v[6:9], v[174:177], v[2:5]
	v_mfma_f32_16x16x32_bf16 v[2:5], v[10:13], v[170:173], v[14:17]
	v_mfma_f32_16x16x32_bf16 v[34:37], v[18:21], v[166:169], v[26:29]
	v_mfma_f32_16x16x32_bf16 v[14:17], v[18:21], v[174:177], v[2:5]

	s_barrier
	s_add_i32 s66, s66, 2
	s_add_u32 s64, s64, 0x100
	s_addc_u32 s65, s65, 0
	s_add_u32 s60, s60, 0x100
	s_addc_u32 s61, s61, 0
	s_cmp_gt_u32 s66, 13
	s_cbranch_scc0 .LBB0_1749
	s_branch .LBB0_1801

.LBB0_1752:
	ds_read_b128 v[130:133], v243
	ds_read_b128 v[134:137], v243 offset:1024
	ds_read_b128 v[138:141], v243 offset:2048
	ds_read_b128 v[142:145], v243 offset:3072
	ds_read_b128 v[146:149], v244
	ds_read_b128 v[150:153], v244 offset:1024
	ds_read_b128 v[154:157], v244 offset:2048
	ds_read_b128 v[158:161], v244 offset:3072
	s_add_u32 s66, s8, 0xfffc0080
	s_addc_u32 s67, s9, -1
	s_cmp_eq_u32 s72, 12
	s_cselect_b64 s[64:65], -1, 0
	s_and_b64 s[62:63], s[64:65], exec
	s_cselect_b32 s63, s49, s55
	s_cselect_b32 s62, s52, s53
	s_cselect_b32 s67, s3, s67
	s_cselect_b32 s66, s5, s66

	s_add_i32 m0, s71, 0xc000
	ds_read_b128 v[162:165], v245
	ds_read_b128 v[166:169], v245 offset:1024
	ds_read_b128 v[170:173], v245 offset:2048
	ds_read_b128 v[174:177], v245 offset:3072
	ds_read_b128 v[178:181], v245 offset:4096
	ds_read_b128 v[198:201], v245 offset:5120
	ds_read_b128 v[202:205], v245 offset:6144
	ds_read_b128 v[206:209], v245 offset:7168
	global_load_lds_dwordx4 v196, s[8:9]

	s_add_i32 m0, s71, 0xe000
	s_nop 0
	global_load_lds_dwordx4 v186, s[8:9]
	s_waitcnt vmcnt(8)
	s_waitcnt lgkmcnt(0)
	s_barrier

	v_mfma_f32_16x16x32_bf16 v[126:129], v[130:133], v[162:165], v[126:129]
	v_mfma_f32_16x16x32_bf16 v[122:125], v[138:141], v[162:165], v[122:125]
	v_mfma_f32_16x16x32_bf16 v[118:121], v[130:133], v[170:173], v[118:121]
	v_mfma_f32_16x16x32_bf16 v[114:117], v[138:141], v[170:173], v[114:117]
	v_mfma_f32_16x16x32_bf16 v[110:113], v[130:133], v[178:181], v[110:113]
	v_mfma_f32_16x16x32_bf16 v[106:109], v[138:141], v[178:181], v[106:109]
	v_mfma_f32_16x16x32_bf16 v[102:105], v[130:133], v[202:205], v[102:105]
	v_mfma_f32_16x16x32_bf16 v[98:101], v[138:141], v[202:205], v[98:101]
	v_mfma_f32_16x16x32_bf16 v[126:129], v[134:137], v[166:169], v[126:129]
	v_mfma_f32_16x16x32_bf16 v[122:125], v[142:145], v[166:169], v[122:125]
	v_mfma_f32_16x16x32_bf16 v[118:121], v[134:137], v[174:177], v[118:121]
	v_mfma_f32_16x16x32_bf16 v[114:117], v[142:145], v[174:177], v[114:117]
	v_mfma_f32_16x16x32_bf16 v[110:113], v[134:137], v[198:201], v[110:113]
	v_mfma_f32_16x16x32_bf16 v[106:109], v[142:145], v[198:201], v[106:109]
	v_mfma_f32_16x16x32_bf16 v[102:105], v[134:137], v[206:209], v[102:105]
	v_mfma_f32_16x16x32_bf16 v[98:101], v[142:145], v[206:209], v[98:101]

	v_mfma_f32_16x16x32_bf16 v[94:97], v[146:149], v[162:165], v[94:97]
	v_mfma_f32_16x16x32_bf16 v[90:93], v[154:157], v[162:165], v[90:93]
	v_mfma_f32_16x16x32_bf16 v[86:89], v[146:149], v[170:173], v[86:89]
	v_mfma_f32_16x16x32_bf16 v[82:85], v[154:157], v[170:173], v[82:85]
	v_mfma_f32_16x16x32_bf16 v[78:81], v[146:149], v[178:181], v[78:81]
	v_mfma_f32_16x16x32_bf16 v[74:77], v[154:157], v[178:181], v[74:77]
	v_mfma_f32_16x16x32_bf16 v[70:73], v[146:149], v[202:205], v[70:73]
	v_mfma_f32_16x16x32_bf16 v[66:69], v[154:157], v[202:205], v[66:69]
	v_mfma_f32_16x16x32_bf16 v[94:97], v[150:153], v[166:169], v[94:97]
	v_mfma_f32_16x16x32_bf16 v[90:93], v[158:161], v[166:169], v[90:93]
	v_mfma_f32_16x16x32_bf16 v[86:89], v[150:153], v[174:177], v[86:89]
	v_mfma_f32_16x16x32_bf16 v[82:85], v[158:161], v[174:177], v[82:85]
	v_mfma_f32_16x16x32_bf16 v[78:81], v[150:153], v[198:201], v[78:81]
	v_mfma_f32_16x16x32_bf16 v[74:77], v[158:161], v[198:201], v[74:77]
	v_mfma_f32_16x16x32_bf16 v[70:73], v[150:153], v[206:209], v[70:73]
	v_mfma_f32_16x16x32_bf16 v[66:69], v[158:161], v[206:209], v[66:69]

	s_barrier
	s_add_i32 s73, s74, s70
	v_lshl_add_u64 v[210:211], s[62:63], 0, v[184:185]
	s_mov_b32 m0, s73
	ds_read_b128 v[162:165], v245 offset:16384
	ds_read_b128 v[166:169], v245 offset:17408
	ds_read_b128 v[170:173], v245 offset:18432
	ds_read_b128 v[174:177], v245 offset:19456
	ds_read_b128 v[178:181], v245 offset:20480
	ds_read_b128 v[198:201], v245 offset:21504
	ds_read_b128 v[202:205], v245 offset:22528
	ds_read_b128 v[206:209], v245 offset:23552
	global_load_lds_dwordx4 v[210:211], off
	s_add_i32 m0, s73, 0x2000
	s_add_u32 vcc_lo, s62, 0x40000
	v_lshl_add_u64 v[212:213], s[62:63], 0, v[188:189]
	s_addc_u32 vcc_hi, s63, 0
	s_add_i32 s73, s75, s70
	global_load_lds_dwordx4 v[212:213], off
	v_lshl_add_u64 v[214:215], vcc, 0, v[184:185]
	s_mov_b32 m0, s73
	v_lshl_add_u64 v[216:217], s[66:67], 0, v[186:187]
	global_load_lds_dwordx4 v[214:215], off
	v_lshl_add_u64 v[214:215], vcc, 0, v[188:189]
	s_add_i32 m0, s73, 0x2000
	s_nop 0
	global_load_lds_dwordx4 v[214:215], off
	v_lshl_add_u64 v[214:215], s[66:67], 0, v[182:183]
	s_mov_b32 m0, s71
	s_nop 0
	global_load_lds_dwordx4 v[214:215], off
	s_mov_b32 m0, s76
	s_nop 0
	global_load_lds_dwordx4 v[216:217], off
	s_waitcnt vmcnt(8)
	s_waitcnt lgkmcnt(0)
	s_barrier

	v_mfma_f32_16x16x32_bf16 v[62:65], v[130:133], v[162:165], v[62:65]
	v_mfma_f32_16x16x32_bf16 v[58:61], v[138:141], v[162:165], v[58:61]
	v_mfma_f32_16x16x32_bf16 v[54:57], v[130:133], v[170:173], v[54:57]
	v_mfma_f32_16x16x32_bf16 v[50:53], v[138:141], v[170:173], v[50:53]
	v_mfma_f32_16x16x32_bf16 v[42:45], v[130:133], v[178:181], v[42:45]
	v_mfma_f32_16x16x32_bf16 v[34:37], v[138:141], v[178:181], v[34:37]
	v_mfma_f32_16x16x32_bf16 v[22:25], v[130:133], v[202:205], v[22:25]
	v_mfma_f32_16x16x32_bf16 v[14:17], v[138:141], v[202:205], v[14:17]
	v_mfma_f32_16x16x32_bf16 v[62:65], v[134:137], v[166:169], v[62:65]
	v_mfma_f32_16x16x32_bf16 v[58:61], v[142:145], v[166:169], v[58:61]
	v_mfma_f32_16x16x32_bf16 v[54:57], v[134:137], v[174:177], v[54:57]
	v_mfma_f32_16x16x32_bf16 v[50:53], v[142:145], v[174:177], v[50:53]
	v_mfma_f32_16x16x32_bf16 v[42:45], v[134:137], v[198:201], v[42:45]
	v_mfma_f32_16x16x32_bf16 v[34:37], v[142:145], v[198:201], v[34:37]
	v_mfma_f32_16x16x32_bf16 v[22:25], v[134:137], v[206:209], v[22:25]
	v_mfma_f32_16x16x32_bf16 v[14:17], v[142:145], v[206:209], v[14:17]

	v_mfma_f32_16x16x32_bf16 v[46:49], v[146:149], v[162:165], v[46:49]
	v_mfma_f32_16x16x32_bf16 v[38:41], v[154:157], v[162:165], v[38:41]
	v_mfma_f32_16x16x32_bf16 v[30:33], v[146:149], v[170:173], v[30:33]
	v_mfma_f32_16x16x32_bf16 v[26:29], v[154:157], v[170:173], v[26:29]
	v_mfma_f32_16x16x32_bf16 v[18:21], v[146:149], v[178:181], v[18:21]
	v_mfma_f32_16x16x32_bf16 v[10:13], v[154:157], v[178:181], v[10:13]
	v_mfma_f32_16x16x32_bf16 v[6:9], v[146:149], v[202:205], v[6:9]
	v_mfma_f32_16x16x32_bf16 v[2:5], v[154:157], v[202:205], v[2:5]
	v_mfma_f32_16x16x32_bf16 v[46:49], v[150:153], v[166:169], v[46:49]
	v_mfma_f32_16x16x32_bf16 v[38:41], v[158:161], v[166:169], v[38:41]
	v_mfma_f32_16x16x32_bf16 v[30:33], v[150:153], v[174:177], v[30:33]
	v_mfma_f32_16x16x32_bf16 v[26:29], v[158:161], v[174:177], v[26:29]
	v_mfma_f32_16x16x32_bf16 v[18:21], v[150:153], v[198:201], v[18:21]
	v_mfma_f32_16x16x32_bf16 v[10:13], v[158:161], v[198:201], v[10:13]
	v_mfma_f32_16x16x32_bf16 v[6:9], v[150:153], v[206:209], v[6:9]
	v_mfma_f32_16x16x32_bf16 v[2:5], v[158:161], v[206:209], v[2:5]

	s_barrier
	s_add_i32 s73, 0, 0x18000
	v_add_u32_e32 v1, s73, v241
	s_add_i32 s96, 0, 0x1c000
	ds_read_b128 v[130:133], v1
	ds_read_b128 v[134:137], v1 offset:1024
	ds_read_b128 v[138:141], v1 offset:2048
	ds_read_b128 v[142:145], v1 offset:3072
	v_add_u32_e32 v1, s96, v241
	ds_read_b128 v[146:149], v1
	ds_read_b128 v[150:153], v1 offset:1024
	ds_read_b128 v[154:157], v1 offset:2048
	ds_read_b128 v[158:161], v1 offset:3072
	s_and_b64 s[64:65], s[50:51], s[64:65]
	s_and_b64 vcc, s[64:65], s[60:61]
	s_add_u32 s66, s66, 0x40000
	s_addc_u32 s67, s67, 0
	s_and_b64 s[64:65], vcc, exec
	s_mov_b32 m0, s77
	v_cndmask_b32_e32 v1, v182, v184, vcc
	s_cselect_b32 s65, s69, s67
	s_cselect_b32 s64, s68, s66
	ds_read_b128 v[162:165], v245 offset:32768
	ds_read_b128 v[166:169], v245 offset:33792
	ds_read_b128 v[170:173], v245 offset:34816
	ds_read_b128 v[174:177], v245 offset:35840
	ds_read_b128 v[178:181], v245 offset:36864
	ds_read_b128 v[198:201], v245 offset:37888
	ds_read_b128 v[202:205], v245 offset:38912
	ds_read_b128 v[206:209], v245 offset:39936
	v_cndmask_b32_e32 v218, v186, v188, vcc
	global_load_lds_dwordx4 v1, s[64:65]
	s_mov_b32 m0, s78
	s_nop 0
	global_load_lds_dwordx4 v218, s[64:65]
	s_waitcnt vmcnt(8)
	s_waitcnt lgkmcnt(0)
	s_barrier

	v_mfma_f32_16x16x32_bf16 v[126:129], v[130:133], v[162:165], v[126:129]
	v_mfma_f32_16x16x32_bf16 v[122:125], v[138:141], v[162:165], v[122:125]
	v_mfma_f32_16x16x32_bf16 v[118:121], v[130:133], v[170:173], v[118:121]
	v_mfma_f32_16x16x32_bf16 v[114:117], v[138:141], v[170:173], v[114:117]
	v_mfma_f32_16x16x32_bf16 v[110:113], v[130:133], v[178:181], v[110:113]
	v_mfma_f32_16x16x32_bf16 v[106:109], v[138:141], v[178:181], v[106:109]
	v_mfma_f32_16x16x32_bf16 v[102:105], v[130:133], v[202:205], v[102:105]
	v_mfma_f32_16x16x32_bf16 v[98:101], v[138:141], v[202:205], v[98:101]
	v_mfma_f32_16x16x32_bf16 v[126:129], v[134:137], v[166:169], v[126:129]
	v_mfma_f32_16x16x32_bf16 v[122:125], v[142:145], v[166:169], v[122:125]
	v_mfma_f32_16x16x32_bf16 v[118:121], v[134:137], v[174:177], v[118:121]
	v_mfma_f32_16x16x32_bf16 v[114:117], v[142:145], v[174:177], v[114:117]
	v_mfma_f32_16x16x32_bf16 v[110:113], v[134:137], v[198:201], v[110:113]
	v_mfma_f32_16x16x32_bf16 v[106:109], v[142:145], v[198:201], v[106:109]
	v_mfma_f32_16x16x32_bf16 v[102:105], v[134:137], v[206:209], v[102:105]
	v_mfma_f32_16x16x32_bf16 v[98:101], v[142:145], v[206:209], v[98:101]

	v_mfma_f32_16x16x32_bf16 v[94:97], v[146:149], v[162:165], v[94:97]
	v_mfma_f32_16x16x32_bf16 v[90:93], v[154:157], v[162:165], v[90:93]
	v_mfma_f32_16x16x32_bf16 v[86:89], v[146:149], v[170:173], v[86:89]
	v_mfma_f32_16x16x32_bf16 v[82:85], v[154:157], v[170:173], v[82:85]
	v_mfma_f32_16x16x32_bf16 v[78:81], v[146:149], v[178:181], v[78:81]
	v_mfma_f32_16x16x32_bf16 v[74:77], v[154:157], v[178:181], v[74:77]
	v_mfma_f32_16x16x32_bf16 v[70:73], v[146:149], v[202:205], v[70:73]
	v_mfma_f32_16x16x32_bf16 v[66:69], v[154:157], v[202:205], v[66:69]
	v_mfma_f32_16x16x32_bf16 v[94:97], v[150:153], v[166:169], v[94:97]
	v_mfma_f32_16x16x32_bf16 v[90:93], v[158:161], v[166:169], v[90:93]
	v_mfma_f32_16x16x32_bf16 v[86:89], v[150:153], v[174:177], v[86:89]
	v_mfma_f32_16x16x32_bf16 v[82:85], v[158:161], v[174:177], v[82:85]
	v_mfma_f32_16x16x32_bf16 v[78:81], v[150:153], v[198:201], v[78:81]
	v_mfma_f32_16x16x32_bf16 v[74:77], v[158:161], v[198:201], v[74:77]
	v_mfma_f32_16x16x32_bf16 v[70:73], v[150:153], v[206:209], v[70:73]
	v_mfma_f32_16x16x32_bf16 v[66:69], v[158:161], v[206:209], v[66:69]

	s_barrier
	s_add_i32 s64, s73, s70
	v_lshl_add_u64 v[210:211], v[210:211], 0, s[38:39]
	s_mov_b32 m0, s64
	ds_read_b128 v[162:165], v245 offset:49152
	ds_read_b128 v[166:169], v245 offset:50176
	ds_read_b128 v[170:173], v245 offset:51200
	ds_read_b128 v[174:177], v245 offset:52224
	ds_read_b128 v[178:181], v245 offset:53248
	ds_read_b128 v[198:201], v245 offset:54272
	ds_read_b128 v[202:205], v245 offset:55296
	ds_read_b128 v[206:209], v245 offset:56320
	global_load_lds_dwordx4 v[210:211], off
	s_add_i32 m0, s64, 0x2000
	s_add_u32 s62, s62, 0x40080
	v_lshl_add_u64 v[210:211], v[212:213], 0, s[38:39]
	s_addc_u32 s63, s63, 0
	s_add_i32 s64, s96, s70
	global_load_lds_dwordx4 v[210:211], off

	s_mov_b32 m0, s64
	s_nop 0
	global_load_lds_dwordx4 v184, s[62:63]

	s_add_i32 m0, s64, 0x2000
	s_nop 0
	global_load_lds_dwordx4 v188, s[62:63]
	v_lshl_add_u64 v[210:211], v[214:215], 0, s[38:39]
	s_mov_b32 m0, s79
	s_nop 0
	global_load_lds_dwordx4 v[210:211], off
	v_lshl_add_u64 v[210:211], v[216:217], 0, s[38:39]
	s_mov_b32 m0, s80
	s_nop 0
	global_load_lds_dwordx4 v[210:211], off
	s_waitcnt vmcnt(8)
	s_waitcnt lgkmcnt(0)
	s_barrier

	v_mfma_f32_16x16x32_bf16 v[62:65], v[130:133], v[162:165], v[62:65]
	v_mfma_f32_16x16x32_bf16 v[58:61], v[138:141], v[162:165], v[58:61]
	v_mfma_f32_16x16x32_bf16 v[54:57], v[130:133], v[170:173], v[54:57]
	v_mfma_f32_16x16x32_bf16 v[50:53], v[138:141], v[170:173], v[50:53]
	v_mfma_f32_16x16x32_bf16 v[42:45], v[130:133], v[178:181], v[42:45]
	v_mfma_f32_16x16x32_bf16 v[34:37], v[138:141], v[178:181], v[34:37]
	v_mfma_f32_16x16x32_bf16 v[22:25], v[130:133], v[202:205], v[22:25]
	v_mfma_f32_16x16x32_bf16 v[14:17], v[138:141], v[202:205], v[14:17]
	v_mfma_f32_16x16x32_bf16 v[62:65], v[134:137], v[166:169], v[62:65]
	v_mfma_f32_16x16x32_bf16 v[58:61], v[142:145], v[166:169], v[58:61]
	v_mfma_f32_16x16x32_bf16 v[54:57], v[134:137], v[174:177], v[54:57]
	v_mfma_f32_16x16x32_bf16 v[50:53], v[142:145], v[174:177], v[50:53]
	v_mfma_f32_16x16x32_bf16 v[42:45], v[134:137], v[198:201], v[42:45]
	v_mfma_f32_16x16x32_bf16 v[34:37], v[142:145], v[198:201], v[34:37]
	v_mfma_f32_16x16x32_bf16 v[22:25], v[134:137], v[206:209], v[22:25]
	v_mfma_f32_16x16x32_bf16 v[14:17], v[142:145], v[206:209], v[14:17]

	v_mfma_f32_16x16x32_bf16 v[46:49], v[146:149], v[162:165], v[46:49]
	v_mfma_f32_16x16x32_bf16 v[38:41], v[154:157], v[162:165], v[38:41]
	v_mfma_f32_16x16x32_bf16 v[30:33], v[146:149], v[170:173], v[30:33]
	v_mfma_f32_16x16x32_bf16 v[26:29], v[154:157], v[170:173], v[26:29]
	v_mfma_f32_16x16x32_bf16 v[18:21], v[146:149], v[178:181], v[18:21]
	v_mfma_f32_16x16x32_bf16 v[10:13], v[154:157], v[178:181], v[10:13]
	v_mfma_f32_16x16x32_bf16 v[6:9], v[146:149], v[202:205], v[6:9]
	v_mfma_f32_16x16x32_bf16 v[2:5], v[154:157], v[202:205], v[2:5]
	v_mfma_f32_16x16x32_bf16 v[46:49], v[150:153], v[166:169], v[46:49]
	v_mfma_f32_16x16x32_bf16 v[38:41], v[158:161], v[166:169], v[38:41]
	v_mfma_f32_16x16x32_bf16 v[30:33], v[150:153], v[174:177], v[30:33]
	v_mfma_f32_16x16x32_bf16 v[26:29], v[158:161], v[174:177], v[26:29]
	v_mfma_f32_16x16x32_bf16 v[18:21], v[150:153], v[198:201], v[18:21]
	v_mfma_f32_16x16x32_bf16 v[10:13], v[158:161], v[198:201], v[10:13]
	v_mfma_f32_16x16x32_bf16 v[6:9], v[150:153], v[206:209], v[6:9]
	v_mfma_f32_16x16x32_bf16 v[2:5], v[158:161], v[206:209], v[2:5]

	s_barrier
	s_add_i32 s72, s72, 2
	s_add_u32 s8, s8, 0x100
	s_addc_u32 s9, s9, 0
	s_add_u32 s53, s53, 0x100
	s_addc_u32 s55, s55, 0
	s_cmp_gt_u32 s72, 13
	s_cbranch_scc0 .LBB0_1752
	s_andn2_b64 vcc, exec, s[40:41]
	s_cbranch_vccnz .LBB0_1755

.LBB0_1882:
	ds_read_b128 v[128:131], v203
	ds_read_b128 v[132:135], v203 offset:1024
	ds_read_b128 v[136:139], v203 offset:2048
	ds_read_b128 v[140:143], v203 offset:3072
	ds_read_b128 v[144:147], v204
	ds_read_b128 v[148:151], v204 offset:1024
	ds_read_b128 v[152:155], v204 offset:2048
	ds_read_b128 v[172:175], v204 offset:3072
	s_add_u32 s2, s22, 0x100
	s_addc_u32 s3, s23, 0
	s_cmp_eq_u32 s58, 40
	s_cselect_b32 s29, s21, s3
	s_cselect_b32 s28, s20, s2
	s_cselect_b32 s25, s5, s57
	s_cselect_b32 s24, s4, s56
	v_lshl_add_u64 v[214:215], s[22:23], 0, v[164:165]
	s_add_i32 m0, s39, 0xc000
	ds_read_b128 v[176:179], v205
	ds_read_b128 v[180:183], v205 offset:1024
	ds_read_b128 v[184:187], v205 offset:2048
	ds_read_b128 v[188:191], v205 offset:3072
	ds_read_b128 v[192:195], v205 offset:4096
	ds_read_b128 v[196:199], v205 offset:5120
	ds_read_b128 v[206:209], v205 offset:6144
	ds_read_b128 v[210:213], v205 offset:7168
	global_load_lds_dwordx4 v[214:215], off
	v_lshl_add_u64 v[214:215], s[22:23], 0, v[166:167]
	s_add_i32 m0, s39, 0xe000
	s_nop 0
	global_load_lds_dwordx4 v[214:215], off
	s_waitcnt vmcnt(8)
	s_waitcnt lgkmcnt(0)
	s_barrier

	v_mfma_f32_16x16x32_bf16 v[124:127], v[128:131], v[176:179], v[124:127]
	v_mfma_f32_16x16x32_bf16 v[120:123], v[136:139], v[176:179], v[120:123]
	v_mfma_f32_16x16x32_bf16 v[108:111], v[128:131], v[184:187], v[108:111]
	v_mfma_f32_16x16x32_bf16 v[104:107], v[136:139], v[184:187], v[104:107]
	v_mfma_f32_16x16x32_bf16 v[92:95], v[128:131], v[192:195], v[92:95]
	v_mfma_f32_16x16x32_bf16 v[88:91], v[136:139], v[192:195], v[88:91]
	v_mfma_f32_16x16x32_bf16 v[76:79], v[128:131], v[206:209], v[76:79]
	v_mfma_f32_16x16x32_bf16 v[72:75], v[136:139], v[206:209], v[72:75]
	v_mfma_f32_16x16x32_bf16 v[124:127], v[132:135], v[180:183], v[124:127]
	v_mfma_f32_16x16x32_bf16 v[120:123], v[140:143], v[180:183], v[120:123]
	v_mfma_f32_16x16x32_bf16 v[108:111], v[132:135], v[188:191], v[108:111]
	v_mfma_f32_16x16x32_bf16 v[104:107], v[140:143], v[188:191], v[104:107]
	v_mfma_f32_16x16x32_bf16 v[92:95], v[132:135], v[196:199], v[92:95]
	v_mfma_f32_16x16x32_bf16 v[88:91], v[140:143], v[196:199], v[88:91]
	v_mfma_f32_16x16x32_bf16 v[76:79], v[132:135], v[210:213], v[76:79]
	v_mfma_f32_16x16x32_bf16 v[72:75], v[140:143], v[210:213], v[72:75]

	v_mfma_f32_16x16x32_bf16 v[116:119], v[144:147], v[176:179], v[116:119]
	v_mfma_f32_16x16x32_bf16 v[112:115], v[152:155], v[176:179], v[112:115]
	v_mfma_f32_16x16x32_bf16 v[100:103], v[144:147], v[184:187], v[100:103]
	v_mfma_f32_16x16x32_bf16 v[96:99], v[152:155], v[184:187], v[96:99]
	v_mfma_f32_16x16x32_bf16 v[84:87], v[144:147], v[192:195], v[84:87]
	v_mfma_f32_16x16x32_bf16 v[80:83], v[152:155], v[192:195], v[80:83]
	v_mfma_f32_16x16x32_bf16 v[68:71], v[144:147], v[206:209], v[68:71]
	v_mfma_f32_16x16x32_bf16 v[64:67], v[152:155], v[206:209], v[64:67]
	v_mfma_f32_16x16x32_bf16 v[116:119], v[148:151], v[180:183], v[116:119]
	v_mfma_f32_16x16x32_bf16 v[112:115], v[172:175], v[180:183], v[112:115]
	v_mfma_f32_16x16x32_bf16 v[100:103], v[148:151], v[188:191], v[100:103]
	v_mfma_f32_16x16x32_bf16 v[96:99], v[172:175], v[188:191], v[96:99]
	v_mfma_f32_16x16x32_bf16 v[84:87], v[148:151], v[196:199], v[84:87]
	v_mfma_f32_16x16x32_bf16 v[80:83], v[172:175], v[196:199], v[80:83]
	v_mfma_f32_16x16x32_bf16 v[68:71], v[148:151], v[210:213], v[68:71]
	v_mfma_f32_16x16x32_bf16 v[64:67], v[172:175], v[210:213], v[64:67]

	s_barrier
	s_add_i32 s22, s48, s38
	v_lshl_add_u64 v[214:215], s[24:25], 0, v[158:159]
	s_mov_b32 m0, s22
	ds_read_b128 v[176:179], v205 offset:16384
	ds_read_b128 v[180:183], v205 offset:17408
	ds_read_b128 v[184:187], v205 offset:18432
	ds_read_b128 v[188:191], v205 offset:19456
	ds_read_b128 v[192:195], v205 offset:20480
	ds_read_b128 v[196:199], v205 offset:21504
	ds_read_b128 v[206:209], v205 offset:22528
	ds_read_b128 v[210:213], v205 offset:23552
	global_load_lds_dwordx4 v[214:215], off
	s_add_i32 m0, s22, 0x2000
	s_add_u32 s22, s24, 0xb0000
	v_lshl_add_u64 v[216:217], s[24:25], 0, v[162:163]
	s_addc_u32 s23, s25, 0
	s_add_i32 s59, s49, s38
	global_load_lds_dwordx4 v[216:217], off

	s_mov_b32 m0, s59
	v_lshl_add_u64 v[220:221], s[28:29], 0, v[160:161]
	global_load_lds_dwordx4 v158, s[22:23]

	s_add_i32 m0, s59, 0x2000
	s_nop 0
	global_load_lds_dwordx4 v162, s[22:23]
	v_lshl_add_u64 v[218:219], s[28:29], 0, v[156:157]
	s_mov_b32 m0, s39
	s_nop 0
	global_load_lds_dwordx4 v[218:219], off
	s_mov_b32 m0, s40
	s_nop 0
	global_load_lds_dwordx4 v[220:221], off
	s_waitcnt vmcnt(8)
	s_waitcnt lgkmcnt(0)
	s_barrier

	v_mfma_f32_16x16x32_bf16 v[60:63], v[128:131], v[176:179], v[60:63]
	v_mfma_f32_16x16x32_bf16 v[56:59], v[136:139], v[176:179], v[56:59]
	v_mfma_f32_16x16x32_bf16 v[44:47], v[128:131], v[184:187], v[44:47]
	v_mfma_f32_16x16x32_bf16 v[40:43], v[136:139], v[184:187], v[40:43]
	v_mfma_f32_16x16x32_bf16 v[28:31], v[128:131], v[192:195], v[28:31]
	v_mfma_f32_16x16x32_bf16 v[24:27], v[136:139], v[192:195], v[24:27]
	v_mfma_f32_16x16x32_bf16 v[12:15], v[128:131], v[206:209], v[12:15]
	v_mfma_f32_16x16x32_bf16 v[8:11], v[136:139], v[206:209], v[8:11]
	v_mfma_f32_16x16x32_bf16 v[60:63], v[132:135], v[180:183], v[60:63]
	v_mfma_f32_16x16x32_bf16 v[56:59], v[140:143], v[180:183], v[56:59]
	v_mfma_f32_16x16x32_bf16 v[44:47], v[132:135], v[188:191], v[44:47]
	v_mfma_f32_16x16x32_bf16 v[40:43], v[140:143], v[188:191], v[40:43]
	v_mfma_f32_16x16x32_bf16 v[28:31], v[132:135], v[196:199], v[28:31]
	v_mfma_f32_16x16x32_bf16 v[24:27], v[140:143], v[196:199], v[24:27]
	v_mfma_f32_16x16x32_bf16 v[12:15], v[132:135], v[210:213], v[12:15]
	v_mfma_f32_16x16x32_bf16 v[8:11], v[140:143], v[210:213], v[8:11]

	v_mfma_f32_16x16x32_bf16 v[52:55], v[144:147], v[176:179], v[52:55]
	v_mfma_f32_16x16x32_bf16 v[48:51], v[152:155], v[176:179], v[48:51]
	v_mfma_f32_16x16x32_bf16 v[36:39], v[144:147], v[184:187], v[36:39]
	v_mfma_f32_16x16x32_bf16 v[32:35], v[152:155], v[184:187], v[32:35]
	v_mfma_f32_16x16x32_bf16 v[20:23], v[144:147], v[192:195], v[20:23]
	v_mfma_f32_16x16x32_bf16 v[16:19], v[152:155], v[192:195], v[16:19]
	v_mfma_f32_16x16x32_bf16 v[4:7], v[144:147], v[206:209], v[4:7]
	v_mfma_f32_16x16x32_bf16 v[0:3], v[152:155], v[206:209], v[0:3]
	v_mfma_f32_16x16x32_bf16 v[52:55], v[148:151], v[180:183], v[52:55]
	v_mfma_f32_16x16x32_bf16 v[48:51], v[172:175], v[180:183], v[48:51]
	v_mfma_f32_16x16x32_bf16 v[36:39], v[148:151], v[188:191], v[36:39]
	v_mfma_f32_16x16x32_bf16 v[32:35], v[172:175], v[188:191], v[32:35]
	v_mfma_f32_16x16x32_bf16 v[20:23], v[148:151], v[196:199], v[20:23]
	v_mfma_f32_16x16x32_bf16 v[16:19], v[172:175], v[196:199], v[16:19]
	v_mfma_f32_16x16x32_bf16 v[4:7], v[148:151], v[210:213], v[4:7]
	v_mfma_f32_16x16x32_bf16 v[0:3], v[172:175], v[210:213], v[0:3]

	s_barrier
	s_add_i32 s59, 0, 0x18000
	s_add_i32 s60, 0, 0x1c000
	v_add_u32_e32 v140, s59, v201
	v_add_u32_e32 v172, s60, v201
	ds_read_b128 v[128:131], v140
	ds_read_b128 v[132:135], v140 offset:1024
	ds_read_b128 v[136:139], v140 offset:2048
	ds_read_b128 v[140:143], v140 offset:3072
	ds_read_b128 v[144:147], v172
	ds_read_b128 v[148:151], v172 offset:1024
	ds_read_b128 v[152:155], v172 offset:2048
	ds_read_b128 v[172:175], v172 offset:3072
	s_add_u32 s22, s28, 0xb0000
	s_addc_u32 s23, s29, 0
	s_mov_b32 m0, s41

	ds_read_b128 v[176:179], v205 offset:32768
	ds_read_b128 v[180:183], v205 offset:33792
	ds_read_b128 v[184:187], v205 offset:34816
	ds_read_b128 v[188:191], v205 offset:35840
	ds_read_b128 v[192:195], v205 offset:36864
	ds_read_b128 v[196:199], v205 offset:37888
	ds_read_b128 v[206:209], v205 offset:38912
	ds_read_b128 v[210:213], v205 offset:39936
	global_load_lds_dwordx4 v156, s[22:23]

	s_mov_b32 m0, s42
	s_nop 0
	global_load_lds_dwordx4 v160, s[22:23]
	s_waitcnt vmcnt(8)
	s_waitcnt lgkmcnt(0)
	s_barrier

	v_mfma_f32_16x16x32_bf16 v[124:127], v[128:131], v[176:179], v[124:127]
	v_mfma_f32_16x16x32_bf16 v[120:123], v[136:139], v[176:179], v[120:123]
	v_mfma_f32_16x16x32_bf16 v[108:111], v[128:131], v[184:187], v[108:111]
	v_mfma_f32_16x16x32_bf16 v[104:107], v[136:139], v[184:187], v[104:107]
	v_mfma_f32_16x16x32_bf16 v[92:95], v[128:131], v[192:195], v[92:95]
	v_mfma_f32_16x16x32_bf16 v[88:91], v[136:139], v[192:195], v[88:91]
	v_mfma_f32_16x16x32_bf16 v[76:79], v[128:131], v[206:209], v[76:79]
	v_mfma_f32_16x16x32_bf16 v[72:75], v[136:139], v[206:209], v[72:75]
	v_mfma_f32_16x16x32_bf16 v[124:127], v[132:135], v[180:183], v[124:127]
	v_mfma_f32_16x16x32_bf16 v[120:123], v[140:143], v[180:183], v[120:123]
	v_mfma_f32_16x16x32_bf16 v[108:111], v[132:135], v[188:191], v[108:111]
	v_mfma_f32_16x16x32_bf16 v[104:107], v[140:143], v[188:191], v[104:107]
	v_mfma_f32_16x16x32_bf16 v[92:95], v[132:135], v[196:199], v[92:95]
	v_mfma_f32_16x16x32_bf16 v[88:91], v[140:143], v[196:199], v[88:91]
	v_mfma_f32_16x16x32_bf16 v[76:79], v[132:135], v[210:213], v[76:79]
	v_mfma_f32_16x16x32_bf16 v[72:75], v[140:143], v[210:213], v[72:75]

	v_mfma_f32_16x16x32_bf16 v[116:119], v[144:147], v[176:179], v[116:119]
	v_mfma_f32_16x16x32_bf16 v[112:115], v[152:155], v[176:179], v[112:115]
	v_mfma_f32_16x16x32_bf16 v[100:103], v[144:147], v[184:187], v[100:103]
	v_mfma_f32_16x16x32_bf16 v[96:99], v[152:155], v[184:187], v[96:99]
	v_mfma_f32_16x16x32_bf16 v[84:87], v[144:147], v[192:195], v[84:87]
	v_mfma_f32_16x16x32_bf16 v[80:83], v[152:155], v[192:195], v[80:83]
	v_mfma_f32_16x16x32_bf16 v[68:71], v[144:147], v[206:209], v[68:71]
	v_mfma_f32_16x16x32_bf16 v[64:67], v[152:155], v[206:209], v[64:67]
	v_mfma_f32_16x16x32_bf16 v[116:119], v[148:151], v[180:183], v[116:119]
	v_mfma_f32_16x16x32_bf16 v[112:115], v[172:175], v[180:183], v[112:115]
	v_mfma_f32_16x16x32_bf16 v[100:103], v[148:151], v[188:191], v[100:103]
	v_mfma_f32_16x16x32_bf16 v[96:99], v[172:175], v[188:191], v[96:99]
	v_mfma_f32_16x16x32_bf16 v[84:87], v[148:151], v[196:199], v[84:87]
	v_mfma_f32_16x16x32_bf16 v[80:83], v[172:175], v[196:199], v[80:83]
	v_mfma_f32_16x16x32_bf16 v[68:71], v[148:151], v[210:213], v[68:71]
	v_mfma_f32_16x16x32_bf16 v[64:67], v[172:175], v[210:213], v[64:67]

	s_barrier
	s_add_i32 s22, s59, s38
	v_lshl_add_u64 v[214:215], v[214:215], 0, s[6:7]
	s_mov_b32 m0, s22
	ds_read_b128 v[176:179], v205 offset:49152
	ds_read_b128 v[180:183], v205 offset:50176
	ds_read_b128 v[184:187], v205 offset:51200
	ds_read_b128 v[188:191], v205 offset:52224
	ds_read_b128 v[192:195], v205 offset:53248
	ds_read_b128 v[196:199], v205 offset:54272
	ds_read_b128 v[206:209], v205 offset:55296
	ds_read_b128 v[210:213], v205 offset:56320
	global_load_lds_dwordx4 v[214:215], off
	s_add_i32 m0, s22, 0x2000
	s_add_u32 s22, s24, 0xb0080
	v_lshl_add_u64 v[214:215], v[216:217], 0, s[6:7]
	s_addc_u32 s23, s25, 0
	s_add_i32 s24, s60, s38
	global_load_lds_dwordx4 v[214:215], off

	s_mov_b32 m0, s24
	s_nop 0
	global_load_lds_dwordx4 v158, s[22:23]

	s_add_i32 m0, s24, 0x2000
	s_nop 0
	global_load_lds_dwordx4 v162, s[22:23]
	v_lshl_add_u64 v[214:215], v[218:219], 0, s[6:7]
	s_mov_b32 m0, s44
	s_nop 0
	global_load_lds_dwordx4 v[214:215], off
	v_lshl_add_u64 v[214:215], v[220:221], 0, s[6:7]
	s_mov_b32 m0, s45
	s_nop 0
	global_load_lds_dwordx4 v[214:215], off
	s_waitcnt vmcnt(8)
	s_waitcnt lgkmcnt(0)
	s_barrier

	v_mfma_f32_16x16x32_bf16 v[60:63], v[128:131], v[176:179], v[60:63]
	v_mfma_f32_16x16x32_bf16 v[56:59], v[136:139], v[176:179], v[56:59]
	v_mfma_f32_16x16x32_bf16 v[44:47], v[128:131], v[184:187], v[44:47]
	v_mfma_f32_16x16x32_bf16 v[40:43], v[136:139], v[184:187], v[40:43]
	v_mfma_f32_16x16x32_bf16 v[28:31], v[128:131], v[192:195], v[28:31]
	v_mfma_f32_16x16x32_bf16 v[24:27], v[136:139], v[192:195], v[24:27]
	v_mfma_f32_16x16x32_bf16 v[12:15], v[128:131], v[206:209], v[12:15]
	v_mfma_f32_16x16x32_bf16 v[8:11], v[136:139], v[206:209], v[8:11]
	v_mfma_f32_16x16x32_bf16 v[60:63], v[132:135], v[180:183], v[60:63]
	v_mfma_f32_16x16x32_bf16 v[56:59], v[140:143], v[180:183], v[56:59]
	v_mfma_f32_16x16x32_bf16 v[44:47], v[132:135], v[188:191], v[44:47]
	v_mfma_f32_16x16x32_bf16 v[40:43], v[140:143], v[188:191], v[40:43]
	v_mfma_f32_16x16x32_bf16 v[28:31], v[132:135], v[196:199], v[28:31]
	v_mfma_f32_16x16x32_bf16 v[24:27], v[140:143], v[196:199], v[24:27]
	v_mfma_f32_16x16x32_bf16 v[12:15], v[132:135], v[210:213], v[12:15]
	v_mfma_f32_16x16x32_bf16 v[8:11], v[140:143], v[210:213], v[8:11]

	v_mfma_f32_16x16x32_bf16 v[52:55], v[144:147], v[176:179], v[52:55]
	v_mfma_f32_16x16x32_bf16 v[48:51], v[152:155], v[176:179], v[48:51]
	v_mfma_f32_16x16x32_bf16 v[36:39], v[144:147], v[184:187], v[36:39]
	v_mfma_f32_16x16x32_bf16 v[32:35], v[152:155], v[184:187], v[32:35]
	v_mfma_f32_16x16x32_bf16 v[20:23], v[144:147], v[192:195], v[20:23]
	v_mfma_f32_16x16x32_bf16 v[16:19], v[152:155], v[192:195], v[16:19]
	v_mfma_f32_16x16x32_bf16 v[4:7], v[144:147], v[206:209], v[4:7]
	v_mfma_f32_16x16x32_bf16 v[0:3], v[152:155], v[206:209], v[0:3]
	v_mfma_f32_16x16x32_bf16 v[52:55], v[148:151], v[180:183], v[52:55]
	v_mfma_f32_16x16x32_bf16 v[48:51], v[172:175], v[180:183], v[48:51]
	v_mfma_f32_16x16x32_bf16 v[36:39], v[148:151], v[188:191], v[36:39]
	v_mfma_f32_16x16x32_bf16 v[32:35], v[172:175], v[188:191], v[32:35]
	v_mfma_f32_16x16x32_bf16 v[20:23], v[148:151], v[196:199], v[20:23]
	v_mfma_f32_16x16x32_bf16 v[16:19], v[172:175], v[196:199], v[16:19]
	v_mfma_f32_16x16x32_bf16 v[4:7], v[148:151], v[210:213], v[4:7]
	v_mfma_f32_16x16x32_bf16 v[0:3], v[172:175], v[210:213], v[0:3]

	s_barrier
	s_add_i32 s58, s58, 2
	s_add_u32 s56, s56, 0x100
	s_addc_u32 s57, s57, 0
	s_cmp_gt_u32 s58, 41
	s_mov_b64 s[22:23], s[2:3]
	s_cbranch_scc0 .LBB0_1882
	v_lshl_add_u32 v174, s55, 8, v200
	v_lshl_or_b32 v172, s54, 8, v202
	v_ashrrev_i32_e32 v175, 31, v174
	v_ashrrev_i32_e32 v173, 31, v172
	v_lshlrev_b64 v[128:129], 10, v[174:175]
	v_lshl_add_u64 v[198:199], v[128:129], 0, v[172:173]
	v_lshlrev_b64 v[128:129], 1, v[198:199]
	v_lshl_add_u64 v[196:197], s[34:35], 0, v[128:129]
	v_or_b32_e32 v128, 0x100, v128
	v_lshl_add_u64 v[194:195], s[34:35], 0, v[128:129]
	v_or_b32_e32 v128, 16, v174
	v_ashrrev_i32_e32 v129, 31, v128
	v_lshlrev_b64 v[128:129], 10, v[128:129]
	v_lshl_add_u64 v[192:193], v[128:129], 0, v[172:173]
	v_lshlrev_b64 v[128:129], 1, v[192:193]
	v_lshl_add_u64 v[190:191], s[34:35], 0, v[128:129]
	v_or_b32_e32 v128, 0x100, v128
	v_lshl_add_u64 v[188:189], s[34:35], 0, v[128:129]
	v_or_b32_e32 v128, 32, v174
	v_ashrrev_i32_e32 v129, 31, v128
	v_lshlrev_b64 v[128:129], 10, v[128:129]
	v_lshl_add_u64 v[186:187], v[128:129], 0, v[172:173]
	v_lshlrev_b64 v[128:129], 1, v[186:187]
	v_lshl_add_u64 v[184:185], s[34:35], 0, v[128:129]
	v_or_b32_e32 v128, 0x100, v128
	v_lshl_add_u64 v[182:183], s[34:35], 0, v[128:129]
	v_or_b32_e32 v128, 48, v174
	v_ashrrev_i32_e32 v129, 31, v128
	v_lshlrev_b64 v[128:129], 10, v[128:129]
	v_lshl_add_u64 v[180:181], v[128:129], 0, v[172:173]
	v_lshlrev_b64 v[128:129], 1, v[180:181]
	global_load_dwordx4 v[206:209], v[196:197], off
	global_load_dwordx4 v[152:155], v[194:195], off
	v_lshl_add_u64 v[178:179], s[34:35], 0, v[128:129]
	v_or_b32_e32 v128, 0x100, v128
	global_load_dwordx4 v[148:151], v[190:191], off
	global_load_dwordx4 v[144:147], v[188:189], off
	global_load_dwordx4 v[140:143], v[184:185], off
	global_load_dwordx4 v[136:139], v[182:183], off
	v_lshl_add_u64 v[176:177], s[34:35], 0, v[128:129]
	global_load_dwordx4 v[132:135], v[178:179], off
	global_load_dwordx4 v[128:131], v[176:177], off
	v_cndmask_b32_e64 v210, 0, 1, s[8:9]
	v_cmp_ne_u32_e64 s[2:3], 1, v210
	s_andn2_b64 vcc, exec, s[8:9]
	v_lshl_add_u64 v[198:199], v[198:199], 2, s[26:27]
	s_waitcnt vmcnt(0)
	v_lshlrev_b32_e32 v210, 16, v206
	v_and_b32_e32 v211, 0xffff0000, v206
	v_lshlrev_b32_e32 v206, 16, v207
	v_and_b32_e32 v207, 0xffff0000, v207
	v_lshlrev_b32_e32 v212, 16, v208
	v_and_b32_e32 v213, 0xffff0000, v208
	v_lshlrev_b32_e32 v208, 16, v209
	v_and_b32_e32 v209, 0xffff0000, v209
	v_pk_add_f32 v[126:127], v[126:127], v[206:207]
	v_pk_add_f32 v[124:125], v[124:125], v[210:211]
	v_pk_add_f32 v[122:123], v[122:123], v[208:209]
	v_pk_add_f32 v[120:121], v[120:121], v[212:213]
	s_cbranch_vccnz .LBB0_1930
	global_store_dwordx4 v[198:199], v[124:127], off nt
	global_store_dwordx4 v[198:199], v[120:123], off offset:16 nt
	s_cbranch_execnz .LBB0_1886
